# v7 + SGPR-base form for LDS-DMA loads whose address add is not reused (drops 54 VALU 64-bit adds from the loader segments)
# speedup vs baseline: 1.0020x; 1.0001x over previous
.LBB0_285:
	s_add_u32 s8, s28, 0x11500000
	s_addc_u32 s9, s29, 0
	s_lshl_b32 s1, s10, 5
	s_mov_b64 s[10:11], 0x80
	s_and_b32 s18, s1, 0x60
	s_add_i32 m0, s76, 0x18000
	v_lshl_add_u64 v[6:7], v[6:7], 0, s[10:11]
	s_ashr_i32 s81, s34, 31
	s_lshl_b32 s15, s14, 13
	s_lshl_b32 s19, s18, 7
	s_waitcnt vmcnt(2)
	s_barrier
	global_load_lds_dwordx4 v[6:7], off
	v_lshl_add_u64 v[4:5], v[4:5], 0, s[10:11]
	s_add_i32 m0, s76, 0x1a000
	s_add_i32 s82, s76, 0x8000
	s_add_i32 s83, s76, 0xa000
	global_load_lds_dwordx4 v[4:5], off
	v_lshl_add_u64 v[0:1], v[0:1], 0, s[10:11]
	s_mov_b32 m0, s82
	s_add_u32 s16, s70, 0x40080
	global_load_lds_dwordx4 v[0:1], off
	v_lshl_add_u64 v[0:1], v[2:3], 0, s[10:11]
	s_mov_b32 m0, s83
	s_addc_u32 s17, s71, 0
	global_load_lds_dwordx4 v[0:1], off
	s_add_i32 m0, s76, 0x1c000
	s_nop 0
	global_load_lds_dwordx4 v132, s[16:17]
	v_lshl_add_u64 v[0:1], s[16:17], 0, v[136:137]
	s_add_i32 m0, s76, 0x1e000
	s_sext_i32_i8 s1, s2
	global_load_lds_dwordx4 v[0:1], off
	v_and_b32_e32 v0, 15, v128
	v_lshlrev_b32_e32 v1, 1, v11
	v_lshlrev_b32_e32 v2, 6, v128
	s_movk_i32 s2, 0x3c0
	v_lshlrev_b32_e32 v3, 2, v128
	v_and_or_b32 v2, v2, s2, v1
	v_and_b32_e32 v3, 32, v3
	v_lshl_or_b32 v152, s14, 6, v0
	v_lshl_or_b32 v0, v0, 6, v1
	v_lshlrev_b32_e32 v1, 8, v128
	v_bitop3_b32 v153, s19, v2, v3 bitop3:0xf6
	v_and_b32_e32 v1, 0x38000, v1
	v_lshlrev_b32_e32 v2, 11, v10
	v_or3_b32 v1, v8, v1, v2
	v_add_u32_e32 v138, v1, v9
	v_lshlrev_b32_e32 v1, 4, v12
	s_waitcnt vmcnt(6)
	s_cmpk_lt_u32 s3, 0x100
	v_and_b32_e32 v1, 0x78000, v1
	v_bitop3_b32 v0, v0, s15, v3 bitop3:0xde
	s_cselect_b64 s[14:15], -1, 0
	v_or3_b32 v1, v8, v1, v2
	s_add_i32 s85, 0, 0x10000
	s_add_i32 s86, 0, 0x14000
	s_mov_b32 s84, s34
	v_or_b32_e32 v154, s18, v11
	v_mov_b32_e32 v139, v133
	v_add_u32_e32 v140, v1, v9
	v_mov_b32_e32 v141, v133
	v_mov_b64_e32 v[142:143], 0x400
	v_mov_b64_e32 v[144:145], 0x3ff
	v_add_u32_e32 v155, s85, v153
	v_add_u32_e32 v156, s86, v153
	v_add_u32_e32 v157, 0, v0
	v_mov_b32_e32 v158, 0x358637bd
	s_mov_b32 s87, 0x800000
	s_mov_b32 s88, 0x140000
	s_mov_b64 s[16:17], 0x160000
	s_mov_b32 s89, 0x160000
	s_barrier
	s_branch .LBB0_288

.LBB0_295:
	ds_read_b128 v[146:149], v155
	ds_read_b128 v[160:163], v155 offset:1024
	ds_read_b128 v[164:167], v155 offset:2048
	ds_read_b128 v[168:171], v155 offset:3072
	ds_read_b128 v[172:175], v156
	ds_read_b128 v[176:179], v156 offset:1024
	ds_read_b128 v[180:183], v156 offset:2048
	ds_read_b128 v[184:187], v156 offset:3072
	s_add_u32 s23, s64, 0xfffc0080
	s_addc_u32 s33, s65, -1
	s_cmp_eq_u32 s92, 12
	s_cselect_b32 s73, s20, s33
	s_cselect_b32 s72, s21, s23
	s_cselect_b32 s71, s19, s91
	s_cselect_b32 s70, s55, s90
	s_add_i32 m0, s76, 0xc000
	ds_read_b128 v[188:191], v157
	ds_read_b128 v[192:195], v157 offset:1024
	ds_read_b128 v[196:199], v157 offset:2048
	ds_read_b128 v[200:203], v157 offset:3072
	ds_read_b128 v[204:207], v157 offset:4096
	ds_read_b128 v[208:211], v157 offset:5120
	ds_read_b128 v[212:215], v157 offset:6144
	ds_read_b128 v[216:219], v157 offset:7168
	global_load_lds_dwordx4 v138, s[64:65]
	s_add_i32 m0, s76, 0xe000
	s_nop 0
	global_load_lds_dwordx4 v140, s[64:65]
	s_waitcnt vmcnt(8)
	s_waitcnt lgkmcnt(0)
	s_barrier
	s_setprio 1
	v_mfma_f32_16x16x32_bf16 v[124:127], v[146:149], v[188:191], v[124:127]
	v_mfma_f32_16x16x32_bf16 v[120:123], v[164:167], v[188:191], v[120:123]
	v_mfma_f32_16x16x32_bf16 v[108:111], v[146:149], v[196:199], v[108:111]
	v_mfma_f32_16x16x32_bf16 v[104:107], v[164:167], v[196:199], v[104:107]
	v_mfma_f32_16x16x32_bf16 v[92:95], v[146:149], v[204:207], v[92:95]
	v_mfma_f32_16x16x32_bf16 v[88:91], v[164:167], v[204:207], v[88:91]
	v_mfma_f32_16x16x32_bf16 v[76:79], v[146:149], v[212:215], v[76:79]
	v_mfma_f32_16x16x32_bf16 v[72:75], v[164:167], v[212:215], v[72:75]
	v_mfma_f32_16x16x32_bf16 v[124:127], v[160:163], v[192:195], v[124:127]
	v_mfma_f32_16x16x32_bf16 v[120:123], v[168:171], v[192:195], v[120:123]
	v_mfma_f32_16x16x32_bf16 v[108:111], v[160:163], v[200:203], v[108:111]
	v_mfma_f32_16x16x32_bf16 v[104:107], v[168:171], v[200:203], v[104:107]
	v_mfma_f32_16x16x32_bf16 v[92:95], v[160:163], v[208:211], v[92:95]
	v_mfma_f32_16x16x32_bf16 v[88:91], v[168:171], v[208:211], v[88:91]
	v_mfma_f32_16x16x32_bf16 v[76:79], v[160:163], v[216:219], v[76:79]
	v_mfma_f32_16x16x32_bf16 v[72:75], v[168:171], v[216:219], v[72:75]
	v_mfma_f32_16x16x32_bf16 v[116:119], v[172:175], v[188:191], v[116:119]
	v_mfma_f32_16x16x32_bf16 v[112:115], v[180:183], v[188:191], v[112:115]
	v_mfma_f32_16x16x32_bf16 v[100:103], v[172:175], v[196:199], v[100:103]
	v_mfma_f32_16x16x32_bf16 v[96:99], v[180:183], v[196:199], v[96:99]
	v_mfma_f32_16x16x32_bf16 v[84:87], v[172:175], v[204:207], v[84:87]
	v_mfma_f32_16x16x32_bf16 v[80:83], v[180:183], v[204:207], v[80:83]
	v_mfma_f32_16x16x32_bf16 v[68:71], v[172:175], v[212:215], v[68:71]
	v_mfma_f32_16x16x32_bf16 v[64:67], v[180:183], v[212:215], v[64:67]
	v_mfma_f32_16x16x32_bf16 v[116:119], v[176:179], v[192:195], v[116:119]
	v_mfma_f32_16x16x32_bf16 v[112:115], v[184:187], v[192:195], v[112:115]
	v_mfma_f32_16x16x32_bf16 v[100:103], v[176:179], v[200:203], v[100:103]
	v_mfma_f32_16x16x32_bf16 v[96:99], v[184:187], v[200:203], v[96:99]
	v_mfma_f32_16x16x32_bf16 v[84:87], v[176:179], v[208:211], v[84:87]
	v_mfma_f32_16x16x32_bf16 v[80:83], v[184:187], v[208:211], v[80:83]
	v_mfma_f32_16x16x32_bf16 v[68:71], v[176:179], v[216:219], v[68:71]
	v_mfma_f32_16x16x32_bf16 v[64:67], v[184:187], v[216:219], v[64:67]
	s_setprio 0
	s_barrier
	s_add_i32 s23, s85, s74
	v_lshl_add_u64 v[150:151], s[70:71], 0, v[132:133]
	s_mov_b32 m0, s23
	ds_read_b128 v[188:191], v157 offset:16384
	ds_read_b128 v[192:195], v157 offset:17408
	ds_read_b128 v[196:199], v157 offset:18432
	ds_read_b128 v[200:203], v157 offset:19456
	ds_read_b128 v[204:207], v157 offset:20480
	ds_read_b128 v[208:211], v157 offset:21504
	ds_read_b128 v[212:215], v157 offset:22528
	ds_read_b128 v[216:219], v157 offset:23552
	global_load_lds_dwordx4 v[150:151], off
	s_add_i32 m0, s23, 0x2000
	s_add_u32 s94, s70, 0x40000
	v_lshl_add_u64 v[220:221], s[70:71], 0, v[136:137]
	s_addc_u32 s95, s71, 0
	s_add_i32 s23, s86, s74
	global_load_lds_dwordx4 v[220:221], off
	s_mov_b32 m0, s23
	v_lshl_add_u64 v[224:225], s[72:73], 0, v[134:135]
	global_load_lds_dwordx4 v132, s[94:95]
	s_add_i32 m0, s23, 0x2000
	s_nop 0
	global_load_lds_dwordx4 v136, s[94:95]
	v_lshl_add_u64 v[222:223], s[72:73], 0, v[130:131]
	s_mov_b32 m0, s76
	s_nop 0
	global_load_lds_dwordx4 v[222:223], off
	s_mov_b32 m0, s77
	s_nop 0
	global_load_lds_dwordx4 v[224:225], off
	s_waitcnt vmcnt(8)
	s_waitcnt lgkmcnt(0)
	s_barrier
	s_setprio 1
	v_mfma_f32_16x16x32_bf16 v[60:63], v[146:149], v[188:191], v[60:63]
	v_mfma_f32_16x16x32_bf16 v[56:59], v[164:167], v[188:191], v[56:59]
	v_mfma_f32_16x16x32_bf16 v[44:47], v[146:149], v[196:199], v[44:47]
	v_mfma_f32_16x16x32_bf16 v[40:43], v[164:167], v[196:199], v[40:43]
	v_mfma_f32_16x16x32_bf16 v[28:31], v[146:149], v[204:207], v[28:31]
	v_mfma_f32_16x16x32_bf16 v[24:27], v[164:167], v[204:207], v[24:27]
	v_mfma_f32_16x16x32_bf16 v[12:15], v[146:149], v[212:215], v[12:15]
	v_mfma_f32_16x16x32_bf16 v[8:11], v[164:167], v[212:215], v[8:11]
	v_mfma_f32_16x16x32_bf16 v[60:63], v[160:163], v[192:195], v[60:63]
	v_mfma_f32_16x16x32_bf16 v[56:59], v[168:171], v[192:195], v[56:59]
	v_mfma_f32_16x16x32_bf16 v[44:47], v[160:163], v[200:203], v[44:47]
	v_mfma_f32_16x16x32_bf16 v[40:43], v[168:171], v[200:203], v[40:43]
	v_mfma_f32_16x16x32_bf16 v[28:31], v[160:163], v[208:211], v[28:31]
	v_mfma_f32_16x16x32_bf16 v[24:27], v[168:171], v[208:211], v[24:27]
	v_mfma_f32_16x16x32_bf16 v[12:15], v[160:163], v[216:219], v[12:15]
	v_mfma_f32_16x16x32_bf16 v[8:11], v[168:171], v[216:219], v[8:11]
	v_mfma_f32_16x16x32_bf16 v[52:55], v[172:175], v[188:191], v[52:55]
	v_mfma_f32_16x16x32_bf16 v[48:51], v[180:183], v[188:191], v[48:51]
	v_mfma_f32_16x16x32_bf16 v[36:39], v[172:175], v[196:199], v[36:39]
	v_mfma_f32_16x16x32_bf16 v[32:35], v[180:183], v[196:199], v[32:35]
	v_mfma_f32_16x16x32_bf16 v[20:23], v[172:175], v[204:207], v[20:23]
	v_mfma_f32_16x16x32_bf16 v[16:19], v[180:183], v[204:207], v[16:19]
	v_mfma_f32_16x16x32_bf16 v[4:7], v[172:175], v[212:215], v[4:7]
	v_mfma_f32_16x16x32_bf16 v[0:3], v[180:183], v[212:215], v[0:3]
	v_mfma_f32_16x16x32_bf16 v[52:55], v[176:179], v[192:195], v[52:55]
	v_mfma_f32_16x16x32_bf16 v[48:51], v[184:187], v[192:195], v[48:51]
	v_mfma_f32_16x16x32_bf16 v[36:39], v[176:179], v[200:203], v[36:39]
	v_mfma_f32_16x16x32_bf16 v[32:35], v[184:187], v[200:203], v[32:35]
	v_mfma_f32_16x16x32_bf16 v[20:23], v[176:179], v[208:211], v[20:23]
	v_mfma_f32_16x16x32_bf16 v[16:19], v[184:187], v[208:211], v[16:19]
	v_mfma_f32_16x16x32_bf16 v[4:7], v[176:179], v[216:219], v[4:7]
	v_mfma_f32_16x16x32_bf16 v[0:3], v[184:187], v[216:219], v[0:3]
	s_setprio 0
	s_barrier
	s_add_i32 s23, 0, 0x18000
	v_add_u32_e32 v159, s23, v153
	s_add_i32 s33, 0, 0x1c000
	ds_read_b128 v[146:149], v159
	ds_read_b128 v[160:163], v159 offset:1024
	ds_read_b128 v[164:167], v159 offset:2048
	ds_read_b128 v[168:171], v159 offset:3072
	v_add_u32_e32 v159, s33, v153
	ds_read_b128 v[172:175], v159
	ds_read_b128 v[176:179], v159 offset:1024
	ds_read_b128 v[180:183], v159 offset:2048
	ds_read_b128 v[184:187], v159 offset:3072
	s_add_u32 s72, s72, 0x40000
	s_addc_u32 s73, s73, 0
	s_mov_b32 m0, s78
	ds_read_b128 v[188:191], v157 offset:32768
	ds_read_b128 v[192:195], v157 offset:33792
	ds_read_b128 v[196:199], v157 offset:34816
	ds_read_b128 v[200:203], v157 offset:35840
	ds_read_b128 v[204:207], v157 offset:36864
	ds_read_b128 v[208:211], v157 offset:37888
	ds_read_b128 v[212:215], v157 offset:38912
	ds_read_b128 v[216:219], v157 offset:39936
	global_load_lds_dwordx4 v130, s[72:73]
	v_lshl_add_u64 v[226:227], s[72:73], 0, v[134:135]
	s_mov_b32 m0, s79
	s_nop 0
	global_load_lds_dwordx4 v[226:227], off
	s_waitcnt vmcnt(8)
	s_waitcnt lgkmcnt(0)
	s_barrier
	s_setprio 1
	v_mfma_f32_16x16x32_bf16 v[124:127], v[146:149], v[188:191], v[124:127]
	v_mfma_f32_16x16x32_bf16 v[120:123], v[164:167], v[188:191], v[120:123]
	v_mfma_f32_16x16x32_bf16 v[108:111], v[146:149], v[196:199], v[108:111]
	v_mfma_f32_16x16x32_bf16 v[104:107], v[164:167], v[196:199], v[104:107]
	v_mfma_f32_16x16x32_bf16 v[92:95], v[146:149], v[204:207], v[92:95]
	v_mfma_f32_16x16x32_bf16 v[88:91], v[164:167], v[204:207], v[88:91]
	v_mfma_f32_16x16x32_bf16 v[76:79], v[146:149], v[212:215], v[76:79]
	v_mfma_f32_16x16x32_bf16 v[72:75], v[164:167], v[212:215], v[72:75]
	v_mfma_f32_16x16x32_bf16 v[124:127], v[160:163], v[192:195], v[124:127]
	v_mfma_f32_16x16x32_bf16 v[120:123], v[168:171], v[192:195], v[120:123]
	v_mfma_f32_16x16x32_bf16 v[108:111], v[160:163], v[200:203], v[108:111]
	v_mfma_f32_16x16x32_bf16 v[104:107], v[168:171], v[200:203], v[104:107]
	v_mfma_f32_16x16x32_bf16 v[92:95], v[160:163], v[208:211], v[92:95]
	v_mfma_f32_16x16x32_bf16 v[88:91], v[168:171], v[208:211], v[88:91]
	v_mfma_f32_16x16x32_bf16 v[76:79], v[160:163], v[216:219], v[76:79]
	v_mfma_f32_16x16x32_bf16 v[72:75], v[168:171], v[216:219], v[72:75]
	v_mfma_f32_16x16x32_bf16 v[116:119], v[172:175], v[188:191], v[116:119]
	v_mfma_f32_16x16x32_bf16 v[112:115], v[180:183], v[188:191], v[112:115]
	v_mfma_f32_16x16x32_bf16 v[100:103], v[172:175], v[196:199], v[100:103]
	v_mfma_f32_16x16x32_bf16 v[96:99], v[180:183], v[196:199], v[96:99]
	v_mfma_f32_16x16x32_bf16 v[84:87], v[172:175], v[204:207], v[84:87]
	v_mfma_f32_16x16x32_bf16 v[80:83], v[180:183], v[204:207], v[80:83]
	v_mfma_f32_16x16x32_bf16 v[68:71], v[172:175], v[212:215], v[68:71]
	v_mfma_f32_16x16x32_bf16 v[64:67], v[180:183], v[212:215], v[64:67]
	v_mfma_f32_16x16x32_bf16 v[116:119], v[176:179], v[192:195], v[116:119]
	v_mfma_f32_16x16x32_bf16 v[112:115], v[184:187], v[192:195], v[112:115]
	v_mfma_f32_16x16x32_bf16 v[100:103], v[176:179], v[200:203], v[100:103]
	v_mfma_f32_16x16x32_bf16 v[96:99], v[184:187], v[200:203], v[96:99]
	v_mfma_f32_16x16x32_bf16 v[84:87], v[176:179], v[208:211], v[84:87]
	v_mfma_f32_16x16x32_bf16 v[80:83], v[184:187], v[208:211], v[80:83]
	v_mfma_f32_16x16x32_bf16 v[68:71], v[176:179], v[216:219], v[68:71]
	v_mfma_f32_16x16x32_bf16 v[64:67], v[184:187], v[216:219], v[64:67]
	s_setprio 0
	s_barrier
	s_add_i32 s23, s23, s74
	v_lshl_add_u64 v[150:151], v[150:151], 0, s[10:11]
	s_mov_b32 m0, s23
	ds_read_b128 v[188:191], v157 offset:49152
	ds_read_b128 v[192:195], v157 offset:50176
	ds_read_b128 v[196:199], v157 offset:51200
	ds_read_b128 v[200:203], v157 offset:52224
	ds_read_b128 v[204:207], v157 offset:53248
	ds_read_b128 v[208:211], v157 offset:54272
	ds_read_b128 v[212:215], v157 offset:55296
	ds_read_b128 v[216:219], v157 offset:56320
	global_load_lds_dwordx4 v[150:151], off
	s_add_i32 m0, s23, 0x2000
	s_add_u32 s70, s70, 0x40080
	v_lshl_add_u64 v[150:151], v[220:221], 0, s[10:11]
	s_addc_u32 s71, s71, 0
	s_add_i32 s23, s33, s74
	global_load_lds_dwordx4 v[150:151], off
	s_mov_b32 m0, s23
	s_nop 0
	global_load_lds_dwordx4 v132, s[70:71]
	s_add_i32 m0, s23, 0x2000
	s_nop 0
	global_load_lds_dwordx4 v136, s[70:71]
	v_lshl_add_u64 v[150:151], v[222:223], 0, s[10:11]
	s_mov_b32 m0, s82
	s_nop 0
	global_load_lds_dwordx4 v[150:151], off
	v_lshl_add_u64 v[150:151], v[224:225], 0, s[10:11]
	s_mov_b32 m0, s83
	s_nop 0
	global_load_lds_dwordx4 v[150:151], off
	s_waitcnt vmcnt(8)
	s_waitcnt lgkmcnt(0)
	s_barrier
	s_setprio 1
	v_mfma_f32_16x16x32_bf16 v[60:63], v[146:149], v[188:191], v[60:63]
	v_mfma_f32_16x16x32_bf16 v[56:59], v[164:167], v[188:191], v[56:59]
	v_mfma_f32_16x16x32_bf16 v[44:47], v[146:149], v[196:199], v[44:47]
	v_mfma_f32_16x16x32_bf16 v[40:43], v[164:167], v[196:199], v[40:43]
	v_mfma_f32_16x16x32_bf16 v[28:31], v[146:149], v[204:207], v[28:31]
	v_mfma_f32_16x16x32_bf16 v[24:27], v[164:167], v[204:207], v[24:27]
	v_mfma_f32_16x16x32_bf16 v[12:15], v[146:149], v[212:215], v[12:15]
	v_mfma_f32_16x16x32_bf16 v[8:11], v[164:167], v[212:215], v[8:11]
	v_mfma_f32_16x16x32_bf16 v[60:63], v[160:163], v[192:195], v[60:63]
	v_mfma_f32_16x16x32_bf16 v[56:59], v[168:171], v[192:195], v[56:59]
	v_mfma_f32_16x16x32_bf16 v[44:47], v[160:163], v[200:203], v[44:47]
	v_mfma_f32_16x16x32_bf16 v[40:43], v[168:171], v[200:203], v[40:43]
	v_mfma_f32_16x16x32_bf16 v[28:31], v[160:163], v[208:211], v[28:31]
	v_mfma_f32_16x16x32_bf16 v[24:27], v[168:171], v[208:211], v[24:27]
	v_mfma_f32_16x16x32_bf16 v[12:15], v[160:163], v[216:219], v[12:15]
	v_mfma_f32_16x16x32_bf16 v[8:11], v[168:171], v[216:219], v[8:11]
	v_mfma_f32_16x16x32_bf16 v[52:55], v[172:175], v[188:191], v[52:55]
	v_mfma_f32_16x16x32_bf16 v[48:51], v[180:183], v[188:191], v[48:51]
	v_mfma_f32_16x16x32_bf16 v[36:39], v[172:175], v[196:199], v[36:39]
	v_mfma_f32_16x16x32_bf16 v[32:35], v[180:183], v[196:199], v[32:35]
	v_mfma_f32_16x16x32_bf16 v[20:23], v[172:175], v[204:207], v[20:23]
	v_mfma_f32_16x16x32_bf16 v[16:19], v[180:183], v[204:207], v[16:19]
	v_mfma_f32_16x16x32_bf16 v[4:7], v[172:175], v[212:215], v[4:7]
	v_mfma_f32_16x16x32_bf16 v[0:3], v[180:183], v[212:215], v[0:3]
	v_mfma_f32_16x16x32_bf16 v[52:55], v[176:179], v[192:195], v[52:55]
	v_mfma_f32_16x16x32_bf16 v[48:51], v[184:187], v[192:195], v[48:51]
	v_mfma_f32_16x16x32_bf16 v[36:39], v[176:179], v[200:203], v[36:39]
	v_mfma_f32_16x16x32_bf16 v[32:35], v[184:187], v[200:203], v[32:35]
	v_mfma_f32_16x16x32_bf16 v[20:23], v[176:179], v[208:211], v[20:23]
	v_mfma_f32_16x16x32_bf16 v[16:19], v[184:187], v[208:211], v[16:19]
	v_mfma_f32_16x16x32_bf16 v[4:7], v[176:179], v[216:219], v[4:7]
	v_mfma_f32_16x16x32_bf16 v[0:3], v[184:187], v[216:219], v[0:3]
	s_setprio 0
	s_barrier
	s_add_i32 s92, s92, 2
	s_add_u32 s64, s64, 0x100
	s_addc_u32 s65, s65, 0
	s_add_u32 s90, s90, 0x100
	s_addc_u32 s91, s91, 0
	s_cmp_gt_u32 s92, 13
	s_cbranch_scc0 .LBB0_295
	s_and_b64 vcc, exec, s[14:15]
	s_cbranch_vccz .LBB0_298
	s_barrier

.LBB0_436:
	v_bfe_u32 v138, v128, 4, 2
	s_lshl_b32 s4, s4, 5
	v_and_b32_e32 v140, 15, v128
	v_lshlrev_b32_e32 v12, 4, v138
	v_lshlrev_b32_e32 v14, 2, v128
	s_and_b32 s59, s4, 0x60
	v_lshlrev_b32_e32 v15, 6, v128
	s_movk_i32 s4, 0x3c0
	s_lshl_b32 s64, s5, 6
	v_lshl_or_b32 v13, v140, 6, v12
	s_lshl_b32 s5, s5, 13
	v_and_b32_e32 v14, 32, v14
	v_and_or_b32 v12, v15, s4, v12
	s_lshl_b32 s4, s59, 7
	v_bitop3_b32 v13, v13, s5, v14 bitop3:0xde
	v_bitop3_b32 v12, s4, v12, v14 bitop3:0xf6
	s_mov_b64 s[4:5], 0x80
	s_add_i32 m0, s17, 0x18000
	v_lshl_add_u64 v[6:7], v[6:7], 0, s[4:5]
	s_waitcnt vmcnt(2)
	s_barrier
	global_load_lds_dwordx4 v[6:7], off
	v_lshl_add_u64 v[4:5], v[4:5], 0, s[4:5]
	s_add_i32 m0, s17, 0x1a000
	s_add_i32 s65, s17, 0x8000
	s_add_i32 s68, s17, 0xa000
	global_load_lds_dwordx4 v[4:5], off
	v_lshl_add_u64 v[2:3], v[2:3], 0, s[4:5]
	s_mov_b32 m0, s65
	s_add_u32 s12, s0, 0x40080
	global_load_lds_dwordx4 v[2:3], off
	v_lshl_add_u64 v[0:1], v[0:1], 0, s[4:5]
	s_mov_b32 m0, s68
	s_addc_u32 s13, s1, 0
	global_load_lds_dwordx4 v[0:1], off
	s_add_i32 m0, s17, 0x1c000
	s_nop 0
	global_load_lds_dwordx4 v132, s[12:13]
	v_lshl_add_u64 v[0:1], s[12:13], 0, v[130:131]
	s_add_i32 m0, s17, 0x1e000
	v_lshlrev_b32_e32 v2, 11, v11
	global_load_lds_dwordx4 v[0:1], off
	v_lshlrev_b32_e32 v0, 8, v128
	v_and_b32_e32 v0, 0x38000, v0
	s_add_u32 s6, s28, s6
	v_or3_b32 v0, v10, v0, v2
	s_addc_u32 s7, s29, 0
	v_add_u32_e32 v0, v0, v9
	v_mov_b32_e32 v1, v133
	v_lshl_add_u64 v[0:1], s[6:7], 0, v[0:1]
	s_mov_b64 s[12:13], 0x2340080
	v_lshl_add_u64 v[134:135], v[0:1], 0, s[12:13]
	v_lshlrev_b32_e32 v0, 4, v8
	s_add_u32 s8, s28, s8
	v_and_b32_e32 v0, 0x78000, v0
	s_addc_u32 s9, s29, 0
	v_or3_b32 v0, v10, v0, v2
	s_add_u32 s69, s8, 0xa00100
	s_waitcnt vmcnt(6)
	v_add_u32_e32 v0, v0, v9
	v_mov_b32_e32 v1, v133
	s_addc_u32 s70, s9, 0
	s_add_i32 s74, 0, 0x10000
	s_add_i32 s76, 0, 0x14000
	s_add_i32 s78, 0, 0x18000
	s_add_i32 s80, 0, 0x1c000
	v_lshl_add_u64 v[0:1], s[6:7], 0, v[0:1]
	v_add_u32_e32 v139, s74, v12
	v_add_u32_e32 v141, s76, v12
	s_add_i32 s74, s74, s10
	s_add_i32 s76, s76, s10
	v_add_u32_e32 v143, s78, v12
	v_add_u32_e32 v144, s80, v12
	s_add_i32 s78, s78, s10
	s_add_i32 s80, s80, s10
	v_lshl_add_u64 v[136:137], v[0:1], 0, s[12:13]
	s_mov_b32 s71, -2
	s_mov_b64 s[8:9], 0
	v_add_u32_e32 v142, 0, v13
	s_add_i32 s72, s17, 0xc000
	s_add_i32 s73, s17, 0xe000
	s_add_i32 s75, s74, 0x2000
	s_add_i32 s77, s76, 0x2000
	s_add_i32 s79, s78, 0x2000
	s_add_i32 s81, s80, 0x2000
	v_mov_b32_e32 v0, v133
	v_mov_b32_e32 v1, v133
	v_mov_b32_e32 v2, v133
	v_mov_b32_e32 v3, v133
	v_mov_b32_e32 v4, v133
	v_mov_b32_e32 v5, v133
	v_mov_b32_e32 v6, v133
	v_mov_b32_e32 v7, v133
	v_mov_b32_e32 v16, v133
	v_mov_b32_e32 v17, v133
	v_mov_b32_e32 v18, v133
	v_mov_b32_e32 v19, v133
	v_mov_b32_e32 v20, v133
	v_mov_b32_e32 v21, v133
	s_waitcnt vmcnt(0)
	v_mov_b32_e32 v22, v133
	v_mov_b32_e32 v23, v133
	v_mov_b32_e32 v32, v133
	v_mov_b32_e32 v33, v133
	v_mov_b32_e32 v34, v133
	v_mov_b32_e32 v35, v133
	v_mov_b32_e32 v36, v133
	v_mov_b32_e32 v37, v133
	v_mov_b32_e32 v38, v133
	v_mov_b32_e32 v39, v133
	v_mov_b32_e32 v48, v133
	v_mov_b32_e32 v49, v133
	v_mov_b32_e32 v50, v133
	v_mov_b32_e32 v51, v133
	v_mov_b32_e32 v52, v133
	v_mov_b32_e32 v53, v133
	v_mov_b32_e32 v54, v133
	v_mov_b32_e32 v55, v133
	v_mov_b32_e32 v8, v133
	v_mov_b32_e32 v9, v133
	v_mov_b32_e32 v10, v133
	v_mov_b32_e32 v11, v133
	v_mov_b32_e32 v12, v133
	v_mov_b32_e32 v13, v133
	v_mov_b32_e32 v14, v133
	v_mov_b32_e32 v15, v133
	v_mov_b32_e32 v24, v133
	v_mov_b32_e32 v25, v133
	v_mov_b32_e32 v26, v133
	v_mov_b32_e32 v27, v133
	v_mov_b32_e32 v28, v133
	v_mov_b32_e32 v29, v133
	v_mov_b32_e32 v30, v133
	v_mov_b32_e32 v31, v133
	v_mov_b32_e32 v40, v133
	v_mov_b32_e32 v41, v133
	v_mov_b32_e32 v42, v133
	v_mov_b32_e32 v43, v133
	v_mov_b32_e32 v44, v133
	v_mov_b32_e32 v45, v133
	v_mov_b32_e32 v46, v133
	v_mov_b32_e32 v47, v133
	v_mov_b32_e32 v56, v133
	v_mov_b32_e32 v57, v133
	v_mov_b32_e32 v58, v133
	v_mov_b32_e32 v59, v133
	v_mov_b32_e32 v60, v133
	v_mov_b32_e32 v61, v133
	v_mov_b32_e32 v62, v133
	v_mov_b32_e32 v63, v133
	v_mov_b32_e32 v64, v133
	v_mov_b32_e32 v65, v133
	v_mov_b32_e32 v66, v133
	v_mov_b32_e32 v67, v133
	v_mov_b32_e32 v68, v133
	v_mov_b32_e32 v69, v133
	v_mov_b32_e32 v70, v133
	v_mov_b32_e32 v71, v133
	v_mov_b32_e32 v80, v133
	v_mov_b32_e32 v81, v133
	v_mov_b32_e32 v82, v133
	v_mov_b32_e32 v83, v133
	v_mov_b32_e32 v84, v133
	v_mov_b32_e32 v85, v133
	v_mov_b32_e32 v86, v133
	v_mov_b32_e32 v87, v133
	v_mov_b32_e32 v96, v133
	v_mov_b32_e32 v97, v133
	v_mov_b32_e32 v98, v133
	v_mov_b32_e32 v99, v133
	v_mov_b32_e32 v100, v133
	v_mov_b32_e32 v101, v133
	v_mov_b32_e32 v102, v133
	v_mov_b32_e32 v103, v133
	v_mov_b32_e32 v112, v133
	v_mov_b32_e32 v113, v133
	v_mov_b32_e32 v114, v133
	v_mov_b32_e32 v115, v133
	v_mov_b32_e32 v116, v133
	v_mov_b32_e32 v117, v133
	v_mov_b32_e32 v118, v133
	v_mov_b32_e32 v119, v133
	v_mov_b32_e32 v72, v133
	v_mov_b32_e32 v73, v133
	v_mov_b32_e32 v74, v133
	v_mov_b32_e32 v75, v133
	v_mov_b32_e32 v76, v133
	v_mov_b32_e32 v77, v133
	v_mov_b32_e32 v78, v133
	v_mov_b32_e32 v79, v133
	v_mov_b32_e32 v88, v133
	v_mov_b32_e32 v89, v133
	v_mov_b32_e32 v90, v133
	v_mov_b32_e32 v91, v133
	v_mov_b32_e32 v92, v133
	v_mov_b32_e32 v93, v133
	v_mov_b32_e32 v94, v133
	v_mov_b32_e32 v95, v133
	v_mov_b32_e32 v104, v133
	v_mov_b32_e32 v105, v133
	v_mov_b32_e32 v106, v133
	v_mov_b32_e32 v107, v133
	v_mov_b32_e32 v108, v133
	v_mov_b32_e32 v109, v133
	v_mov_b32_e32 v110, v133
	v_mov_b32_e32 v111, v133
	v_mov_b32_e32 v120, v133
	v_mov_b32_e32 v121, v133
	v_mov_b32_e32 v122, v133
	v_mov_b32_e32 v123, v133
	v_mov_b32_e32 v124, v133
	v_mov_b32_e32 v125, v133
	v_mov_b32_e32 v126, v133
	v_mov_b32_e32 v127, v133
	s_barrier
.LBB0_437:
	ds_read_b128 v[146:149], v139
	ds_read_b128 v[150:153], v139 offset:1024
	ds_read_b128 v[154:157], v139 offset:2048
	ds_read_b128 v[158:161], v139 offset:3072
	ds_read_b128 v[162:165], v141
	ds_read_b128 v[166:169], v141 offset:1024
	ds_read_b128 v[170:173], v141 offset:2048
	ds_read_b128 v[174:177], v141 offset:3072
	s_add_u32 s10, s6, s8
	s_addc_u32 s11, s7, s9
	s_add_u32 s10, s10, 0x2300100
	s_addc_u32 s11, s11, 0
	s_add_u32 s23, s69, s8
	s_addc_u32 s33, s70, s9
	s_cmpk_eq_i32 s8, 0x700
	s_cselect_b32 s13, s3, s11
	s_cselect_b32 s12, s2, s10
	s_cselect_b32 s11, s1, s33
	s_cselect_b32 s10, s0, s23
	s_mov_b32 m0, s72
	v_lshl_add_u64 v[210:211], v[134:135], 0, s[8:9]
	ds_read_b128 v[178:181], v142
	ds_read_b128 v[182:185], v142 offset:1024
	ds_read_b128 v[186:189], v142 offset:2048
	ds_read_b128 v[190:193], v142 offset:3072
	ds_read_b128 v[194:197], v142 offset:4096
	ds_read_b128 v[198:201], v142 offset:5120
	ds_read_b128 v[202:205], v142 offset:6144
	ds_read_b128 v[206:209], v142 offset:7168
	global_load_lds_dwordx4 v[210:211], off
	v_lshl_add_u64 v[210:211], v[136:137], 0, s[8:9]
	s_mov_b32 m0, s73
	s_nop 0
	global_load_lds_dwordx4 v[210:211], off
	s_waitcnt vmcnt(8)
	s_waitcnt lgkmcnt(0)
	s_barrier
	s_setprio 1
	v_mfma_f32_16x16x32_bf16 v[124:127], v[146:149], v[178:181], v[124:127]
	v_mfma_f32_16x16x32_bf16 v[120:123], v[154:157], v[178:181], v[120:123]
	v_mfma_f32_16x16x32_bf16 v[108:111], v[146:149], v[186:189], v[108:111]
	v_mfma_f32_16x16x32_bf16 v[104:107], v[154:157], v[186:189], v[104:107]
	v_mfma_f32_16x16x32_bf16 v[92:95], v[146:149], v[194:197], v[92:95]
	v_mfma_f32_16x16x32_bf16 v[88:91], v[154:157], v[194:197], v[88:91]
	v_mfma_f32_16x16x32_bf16 v[76:79], v[146:149], v[202:205], v[76:79]
	v_mfma_f32_16x16x32_bf16 v[72:75], v[154:157], v[202:205], v[72:75]
	v_mfma_f32_16x16x32_bf16 v[124:127], v[150:153], v[182:185], v[124:127]
	v_mfma_f32_16x16x32_bf16 v[120:123], v[158:161], v[182:185], v[120:123]
	v_mfma_f32_16x16x32_bf16 v[108:111], v[150:153], v[190:193], v[108:111]
	v_mfma_f32_16x16x32_bf16 v[104:107], v[158:161], v[190:193], v[104:107]
	v_mfma_f32_16x16x32_bf16 v[92:95], v[150:153], v[198:201], v[92:95]
	v_mfma_f32_16x16x32_bf16 v[88:91], v[158:161], v[198:201], v[88:91]
	v_mfma_f32_16x16x32_bf16 v[76:79], v[150:153], v[206:209], v[76:79]
	v_mfma_f32_16x16x32_bf16 v[72:75], v[158:161], v[206:209], v[72:75]
	v_mfma_f32_16x16x32_bf16 v[116:119], v[162:165], v[178:181], v[116:119]
	v_mfma_f32_16x16x32_bf16 v[112:115], v[170:173], v[178:181], v[112:115]
	v_mfma_f32_16x16x32_bf16 v[100:103], v[162:165], v[186:189], v[100:103]
	v_mfma_f32_16x16x32_bf16 v[96:99], v[170:173], v[186:189], v[96:99]
	v_mfma_f32_16x16x32_bf16 v[84:87], v[162:165], v[194:197], v[84:87]
	v_mfma_f32_16x16x32_bf16 v[80:83], v[170:173], v[194:197], v[80:83]
	v_mfma_f32_16x16x32_bf16 v[68:71], v[162:165], v[202:205], v[68:71]
	v_mfma_f32_16x16x32_bf16 v[64:67], v[170:173], v[202:205], v[64:67]
	v_mfma_f32_16x16x32_bf16 v[116:119], v[166:169], v[182:185], v[116:119]
	v_mfma_f32_16x16x32_bf16 v[112:115], v[174:177], v[182:185], v[112:115]
	v_mfma_f32_16x16x32_bf16 v[100:103], v[166:169], v[190:193], v[100:103]
	v_mfma_f32_16x16x32_bf16 v[96:99], v[174:177], v[190:193], v[96:99]
	v_mfma_f32_16x16x32_bf16 v[84:87], v[166:169], v[198:201], v[84:87]
	v_mfma_f32_16x16x32_bf16 v[80:83], v[174:177], v[198:201], v[80:83]
	v_mfma_f32_16x16x32_bf16 v[68:71], v[166:169], v[206:209], v[68:71]
	v_mfma_f32_16x16x32_bf16 v[64:67], v[174:177], v[206:209], v[64:67]
	s_setprio 0
	s_barrier
	s_mov_b32 m0, s74
	v_lshl_add_u64 v[210:211], s[10:11], 0, v[132:133]
	s_add_u32 s82, s10, 0x40000
	ds_read_b128 v[178:181], v142 offset:16384
	ds_read_b128 v[182:185], v142 offset:17408
	ds_read_b128 v[186:189], v142 offset:18432
	ds_read_b128 v[190:193], v142 offset:19456
	ds_read_b128 v[194:197], v142 offset:20480
	ds_read_b128 v[198:201], v142 offset:21504
	ds_read_b128 v[202:205], v142 offset:22528
	ds_read_b128 v[206:209], v142 offset:23552
	global_load_lds_dwordx4 v[210:211], off
	v_lshl_add_u64 v[212:213], s[10:11], 0, v[130:131]
	s_mov_b32 m0, s75
	s_addc_u32 s83, s11, 0
	global_load_lds_dwordx4 v[212:213], off
	s_mov_b32 m0, s76
	v_lshl_add_u64 v[216:217], s[12:13], 0, v[130:131]
	global_load_lds_dwordx4 v132, s[82:83]
	s_mov_b32 m0, s77
	s_nop 0
	global_load_lds_dwordx4 v130, s[82:83]
	v_lshl_add_u64 v[214:215], s[12:13], 0, v[132:133]
	s_mov_b32 m0, s17
	s_nop 0
	global_load_lds_dwordx4 v[214:215], off
	s_mov_b32 m0, s20
	s_nop 0
	global_load_lds_dwordx4 v[216:217], off
	s_waitcnt vmcnt(8)
	s_waitcnt lgkmcnt(0)
	s_barrier
	s_setprio 1
	v_mfma_f32_16x16x32_bf16 v[60:63], v[146:149], v[178:181], v[60:63]
	v_mfma_f32_16x16x32_bf16 v[56:59], v[154:157], v[178:181], v[56:59]
	v_mfma_f32_16x16x32_bf16 v[44:47], v[146:149], v[186:189], v[44:47]
	v_mfma_f32_16x16x32_bf16 v[40:43], v[154:157], v[186:189], v[40:43]
	v_mfma_f32_16x16x32_bf16 v[28:31], v[146:149], v[194:197], v[28:31]
	v_mfma_f32_16x16x32_bf16 v[24:27], v[154:157], v[194:197], v[24:27]
	v_mfma_f32_16x16x32_bf16 v[12:15], v[146:149], v[202:205], v[12:15]
	v_mfma_f32_16x16x32_bf16 v[8:11], v[154:157], v[202:205], v[8:11]
	v_mfma_f32_16x16x32_bf16 v[60:63], v[150:153], v[182:185], v[60:63]
	v_mfma_f32_16x16x32_bf16 v[56:59], v[158:161], v[182:185], v[56:59]
	v_mfma_f32_16x16x32_bf16 v[44:47], v[150:153], v[190:193], v[44:47]
	v_mfma_f32_16x16x32_bf16 v[40:43], v[158:161], v[190:193], v[40:43]
	v_mfma_f32_16x16x32_bf16 v[28:31], v[150:153], v[198:201], v[28:31]
	v_mfma_f32_16x16x32_bf16 v[24:27], v[158:161], v[198:201], v[24:27]
	v_mfma_f32_16x16x32_bf16 v[12:15], v[150:153], v[206:209], v[12:15]
	v_mfma_f32_16x16x32_bf16 v[8:11], v[158:161], v[206:209], v[8:11]
	v_mfma_f32_16x16x32_bf16 v[52:55], v[162:165], v[178:181], v[52:55]
	v_mfma_f32_16x16x32_bf16 v[48:51], v[170:173], v[178:181], v[48:51]
	v_mfma_f32_16x16x32_bf16 v[36:39], v[162:165], v[186:189], v[36:39]
	v_mfma_f32_16x16x32_bf16 v[32:35], v[170:173], v[186:189], v[32:35]
	v_mfma_f32_16x16x32_bf16 v[20:23], v[162:165], v[194:197], v[20:23]
	v_mfma_f32_16x16x32_bf16 v[16:19], v[170:173], v[194:197], v[16:19]
	v_mfma_f32_16x16x32_bf16 v[4:7], v[162:165], v[202:205], v[4:7]
	v_mfma_f32_16x16x32_bf16 v[0:3], v[170:173], v[202:205], v[0:3]
	v_mfma_f32_16x16x32_bf16 v[52:55], v[166:169], v[182:185], v[52:55]
	v_mfma_f32_16x16x32_bf16 v[48:51], v[174:177], v[182:185], v[48:51]
	v_mfma_f32_16x16x32_bf16 v[36:39], v[166:169], v[190:193], v[36:39]
	v_mfma_f32_16x16x32_bf16 v[32:35], v[174:177], v[190:193], v[32:35]
	v_mfma_f32_16x16x32_bf16 v[20:23], v[166:169], v[198:201], v[20:23]
	v_mfma_f32_16x16x32_bf16 v[16:19], v[174:177], v[198:201], v[16:19]
	v_mfma_f32_16x16x32_bf16 v[4:7], v[166:169], v[206:209], v[4:7]
	v_mfma_f32_16x16x32_bf16 v[0:3], v[174:177], v[206:209], v[0:3]
	s_setprio 0
	s_barrier
	ds_read_b128 v[146:149], v143
	ds_read_b128 v[150:153], v143 offset:1024
	ds_read_b128 v[154:157], v143 offset:2048
	ds_read_b128 v[158:161], v143 offset:3072
	ds_read_b128 v[162:165], v144
	ds_read_b128 v[166:169], v144 offset:1024
	ds_read_b128 v[170:173], v144 offset:2048
	ds_read_b128 v[174:177], v144 offset:3072
	s_add_u32 s12, s12, 0x40000
	s_addc_u32 s13, s13, 0
	s_mov_b32 m0, s21
	ds_read_b128 v[178:181], v142 offset:32768
	ds_read_b128 v[182:185], v142 offset:33792
	ds_read_b128 v[186:189], v142 offset:34816
	ds_read_b128 v[190:193], v142 offset:35840
	ds_read_b128 v[194:197], v142 offset:36864
	ds_read_b128 v[198:201], v142 offset:37888
	ds_read_b128 v[202:205], v142 offset:38912
	ds_read_b128 v[206:209], v142 offset:39936
	global_load_lds_dwordx4 v132, s[12:13]
	v_lshl_add_u64 v[218:219], s[12:13], 0, v[130:131]
	s_mov_b32 m0, s58
	s_nop 0
	global_load_lds_dwordx4 v[218:219], off
	s_waitcnt vmcnt(8)
	s_waitcnt lgkmcnt(0)
	s_barrier
	s_setprio 1
	v_mfma_f32_16x16x32_bf16 v[124:127], v[146:149], v[178:181], v[124:127]
	v_mfma_f32_16x16x32_bf16 v[120:123], v[154:157], v[178:181], v[120:123]
	v_mfma_f32_16x16x32_bf16 v[108:111], v[146:149], v[186:189], v[108:111]
	v_mfma_f32_16x16x32_bf16 v[104:107], v[154:157], v[186:189], v[104:107]
	v_mfma_f32_16x16x32_bf16 v[92:95], v[146:149], v[194:197], v[92:95]
	v_mfma_f32_16x16x32_bf16 v[88:91], v[154:157], v[194:197], v[88:91]
	v_mfma_f32_16x16x32_bf16 v[76:79], v[146:149], v[202:205], v[76:79]
	v_mfma_f32_16x16x32_bf16 v[72:75], v[154:157], v[202:205], v[72:75]
	v_mfma_f32_16x16x32_bf16 v[124:127], v[150:153], v[182:185], v[124:127]
	v_mfma_f32_16x16x32_bf16 v[120:123], v[158:161], v[182:185], v[120:123]
	v_mfma_f32_16x16x32_bf16 v[108:111], v[150:153], v[190:193], v[108:111]
	v_mfma_f32_16x16x32_bf16 v[104:107], v[158:161], v[190:193], v[104:107]
	v_mfma_f32_16x16x32_bf16 v[92:95], v[150:153], v[198:201], v[92:95]
	v_mfma_f32_16x16x32_bf16 v[88:91], v[158:161], v[198:201], v[88:91]
	v_mfma_f32_16x16x32_bf16 v[76:79], v[150:153], v[206:209], v[76:79]
	v_mfma_f32_16x16x32_bf16 v[72:75], v[158:161], v[206:209], v[72:75]
	v_mfma_f32_16x16x32_bf16 v[116:119], v[162:165], v[178:181], v[116:119]
	v_mfma_f32_16x16x32_bf16 v[112:115], v[170:173], v[178:181], v[112:115]
	v_mfma_f32_16x16x32_bf16 v[100:103], v[162:165], v[186:189], v[100:103]
	v_mfma_f32_16x16x32_bf16 v[96:99], v[170:173], v[186:189], v[96:99]
	v_mfma_f32_16x16x32_bf16 v[84:87], v[162:165], v[194:197], v[84:87]
	v_mfma_f32_16x16x32_bf16 v[80:83], v[170:173], v[194:197], v[80:83]
	v_mfma_f32_16x16x32_bf16 v[68:71], v[162:165], v[202:205], v[68:71]
	v_mfma_f32_16x16x32_bf16 v[64:67], v[170:173], v[202:205], v[64:67]
	v_mfma_f32_16x16x32_bf16 v[116:119], v[166:169], v[182:185], v[116:119]
	v_mfma_f32_16x16x32_bf16 v[112:115], v[174:177], v[182:185], v[112:115]
	v_mfma_f32_16x16x32_bf16 v[100:103], v[166:169], v[190:193], v[100:103]
	v_mfma_f32_16x16x32_bf16 v[96:99], v[174:177], v[190:193], v[96:99]
	v_mfma_f32_16x16x32_bf16 v[84:87], v[166:169], v[198:201], v[84:87]
	v_mfma_f32_16x16x32_bf16 v[80:83], v[174:177], v[198:201], v[80:83]
	v_mfma_f32_16x16x32_bf16 v[68:71], v[166:169], v[206:209], v[68:71]
	v_mfma_f32_16x16x32_bf16 v[64:67], v[174:177], v[206:209], v[64:67]
	s_setprio 0
	s_barrier
	s_mov_b32 m0, s78
	v_lshl_add_u64 v[210:211], v[210:211], 0, s[4:5]
	s_add_u32 s10, s10, 0x40080
	ds_read_b128 v[178:181], v142 offset:49152
	ds_read_b128 v[182:185], v142 offset:50176
	ds_read_b128 v[186:189], v142 offset:51200
	ds_read_b128 v[190:193], v142 offset:52224
	ds_read_b128 v[194:197], v142 offset:53248
	ds_read_b128 v[198:201], v142 offset:54272
	ds_read_b128 v[202:205], v142 offset:55296
	ds_read_b128 v[206:209], v142 offset:56320
	global_load_lds_dwordx4 v[210:211], off
	v_lshl_add_u64 v[210:211], v[212:213], 0, s[4:5]
	s_mov_b32 m0, s79
	s_addc_u32 s11, s11, 0
	global_load_lds_dwordx4 v[210:211], off
	s_mov_b32 m0, s80
	s_nop 0
	global_load_lds_dwordx4 v132, s[10:11]
	s_mov_b32 m0, s81
	s_nop 0
	global_load_lds_dwordx4 v130, s[10:11]
	v_lshl_add_u64 v[210:211], v[214:215], 0, s[4:5]
	s_mov_b32 m0, s65
	s_nop 0
	global_load_lds_dwordx4 v[210:211], off
	v_lshl_add_u64 v[210:211], v[216:217], 0, s[4:5]
	s_mov_b32 m0, s68
	s_nop 0
	global_load_lds_dwordx4 v[210:211], off
	s_waitcnt vmcnt(8)
	s_waitcnt lgkmcnt(0)
	s_barrier
	s_setprio 1
	v_mfma_f32_16x16x32_bf16 v[60:63], v[146:149], v[178:181], v[60:63]
	v_mfma_f32_16x16x32_bf16 v[56:59], v[154:157], v[178:181], v[56:59]
	v_mfma_f32_16x16x32_bf16 v[44:47], v[146:149], v[186:189], v[44:47]
	v_mfma_f32_16x16x32_bf16 v[40:43], v[154:157], v[186:189], v[40:43]
	v_mfma_f32_16x16x32_bf16 v[28:31], v[146:149], v[194:197], v[28:31]
	v_mfma_f32_16x16x32_bf16 v[24:27], v[154:157], v[194:197], v[24:27]
	v_mfma_f32_16x16x32_bf16 v[12:15], v[146:149], v[202:205], v[12:15]
	v_mfma_f32_16x16x32_bf16 v[8:11], v[154:157], v[202:205], v[8:11]
	v_mfma_f32_16x16x32_bf16 v[60:63], v[150:153], v[182:185], v[60:63]
	v_mfma_f32_16x16x32_bf16 v[56:59], v[158:161], v[182:185], v[56:59]
	v_mfma_f32_16x16x32_bf16 v[44:47], v[150:153], v[190:193], v[44:47]
	v_mfma_f32_16x16x32_bf16 v[40:43], v[158:161], v[190:193], v[40:43]
	v_mfma_f32_16x16x32_bf16 v[28:31], v[150:153], v[198:201], v[28:31]
	v_mfma_f32_16x16x32_bf16 v[24:27], v[158:161], v[198:201], v[24:27]
	v_mfma_f32_16x16x32_bf16 v[12:15], v[150:153], v[206:209], v[12:15]
	v_mfma_f32_16x16x32_bf16 v[8:11], v[158:161], v[206:209], v[8:11]
	v_mfma_f32_16x16x32_bf16 v[52:55], v[162:165], v[178:181], v[52:55]
	v_mfma_f32_16x16x32_bf16 v[48:51], v[170:173], v[178:181], v[48:51]
	v_mfma_f32_16x16x32_bf16 v[36:39], v[162:165], v[186:189], v[36:39]
	v_mfma_f32_16x16x32_bf16 v[32:35], v[170:173], v[186:189], v[32:35]
	v_mfma_f32_16x16x32_bf16 v[20:23], v[162:165], v[194:197], v[20:23]
	v_mfma_f32_16x16x32_bf16 v[16:19], v[170:173], v[194:197], v[16:19]
	v_mfma_f32_16x16x32_bf16 v[4:7], v[162:165], v[202:205], v[4:7]
	v_mfma_f32_16x16x32_bf16 v[0:3], v[170:173], v[202:205], v[0:3]
	v_mfma_f32_16x16x32_bf16 v[52:55], v[166:169], v[182:185], v[52:55]
	v_mfma_f32_16x16x32_bf16 v[48:51], v[174:177], v[182:185], v[48:51]
	v_mfma_f32_16x16x32_bf16 v[36:39], v[166:169], v[190:193], v[36:39]
	v_mfma_f32_16x16x32_bf16 v[32:35], v[174:177], v[190:193], v[32:35]
	v_mfma_f32_16x16x32_bf16 v[20:23], v[166:169], v[198:201], v[20:23]
	v_mfma_f32_16x16x32_bf16 v[16:19], v[174:177], v[198:201], v[16:19]
	v_mfma_f32_16x16x32_bf16 v[4:7], v[166:169], v[206:209], v[4:7]
	v_mfma_f32_16x16x32_bf16 v[0:3], v[174:177], v[206:209], v[0:3]
	s_setprio 0
	s_barrier
	s_add_i32 s71, s71, 2
	s_add_u32 s8, s8, 0x100
	s_addc_u32 s9, s9, 0
	s_cmp_gt_u32 s71, 13
	s_cbranch_scc0 .LBB0_437
	s_add_u32 s4, s28, 0x2f41000
	s_addc_u32 s5, s29, 0
	s_lshl_b32 s0, s16, 8
	s_add_i32 s64, s64, s0
	v_or_b32_e32 v130, s64, v140
	v_mov_b32_e32 v131, 0
	v_lshl_add_u64 v[132:133], v[130:131], 2, s[4:5]
	global_load_dword v149, v[132:133], off
	v_lshl_or_b32 v134, v138, 2, s59
	v_mov_b32_e32 v148, 0x358637bd
	s_lshl_b32 s13, s15, 8
	s_mov_b32 s6, 0x800000
	s_movk_i32 s0, 0x36c
	v_or_b32_e32 v146, s13, v134
	s_and_b32 s9, s13, 0x300
	v_mov_b32_e32 v150, s13
	s_lshl_b32 s13, s64, 2
	v_mov_b32_e32 v142, 0x80
	s_movk_i32 s10, 0xec
	v_lshlrev_b32_e32 v138, 1, v134
	v_bitop3_b32 v134, v134, s0, v150 bitop3:0xc8
	s_and_b32 s0, s13, 0xfffffc00
	v_bitop3_b32 v154, v146, s10, v142 bitop3:0xc8
	s_or_b32 s10, s0, s9
	s_mov_b32 s1, 0x4880000
	s_cmp_gt_u32 s15, 3
	v_mov_b32_e32 v136, 0xcf
	s_mov_b32 s2, 0x2b00000
	s_cselect_b32 s0, s1, 0x4080000
	s_movk_i32 s3, 0x37c
	s_movk_i32 s8, 0x3ec
	v_bitop3_b32 v152, s64, v136, v140 bitop3:0xc8
	s_cselect_b32 s1, s2, 0x2700000
	s_add_u32 s2, s26, s0
	v_bitop3_b32 v136, v146, s3, 16 bitop3:0xc8
	v_bitop3_b32 v153, v146, s8, v142 bitop3:0xc8
	v_or_b32_e32 v152, s10, v152
	s_addc_u32 s3, s27, 0
	s_movk_i32 s7, 0x7c
	s_movk_i32 s11, 0x3fc
	v_mov_b32_e32 v144, 0x90
	s_movk_i32 s12, 0xfc
	v_lshlrev_b64 v[150:151], 12, v[130:131]
	v_lshlrev_b32_e32 v142, 2, v153
	v_ashrrev_i32_e32 v153, 31, v152
	s_add_u32 s0, s28, s1
	v_mov_b32_e32 v147, v131
	v_bitop3_b32 v140, v146, s7, 16 bitop3:0xc8
	v_bitop3_b32 v155, v146, s11, v144 bitop3:0xc8
	v_bitop3_b32 v167, v146, s12, v144 bitop3:0xc8
	v_lshlrev_b32_e32 v146, 2, v134
	v_lshlrev_b64 v[152:153], 9, v[152:153]
	v_lshl_add_u64 v[150:151], s[2:3], 0, v[150:151]
	s_addc_u32 s1, s29, 0
	v_mov_b32_e32 v139, v131
	v_lshlrev_b32_e32 v144, 2, v136
	v_lshlrev_b32_e32 v134, 1, v140
	v_lshlrev_b32_e32 v136, 1, v154
	v_lshlrev_b32_e32 v140, 2, v155
	v_lshl_add_u64 v[154:155], v[150:151], 0, v[146:147]
	v_lshl_add_u64 v[152:153], s[0:1], 0, v[152:153]
	v_mov_b32_e32 v145, v131
	v_mov_b32_e32 v135, v131
	v_mov_b32_e32 v143, v131
	v_mov_b32_e32 v137, v131
	v_lshl_add_u64 v[156:157], v[150:151], 0, v[144:145]
	v_lshl_add_u64 v[162:163], v[152:153], 0, v[134:135]
	v_mov_b32_e32 v141, v131
	v_lshl_add_u64 v[158:159], v[150:151], 0, v[142:143]
	v_lshl_add_u64 v[164:165], v[152:153], 0, v[136:137]
	v_lshl_add_u64 v[150:151], v[150:151], 0, v[140:141]
	s_movk_i32 s7, 0xdf
	s_movk_i32 s8, 0xef
	s_cmpk_lt_u32 s14, 0x100
	s_waitcnt vmcnt(0)
	v_fmamk_f32 v149, v149, 0x3a800000, v148
	v_mul_f32_e32 v160, 0x4b800000, v149
	v_cmp_gt_f32_e32 vcc, s6, v149
	s_nop 1
	v_cndmask_b32_e32 v149, v149, v160, vcc
	v_rsq_f32_e32 v149, v149
	v_lshl_add_u64 v[160:161], v[152:153], 0, v[138:139]
	v_mul_f32_e32 v166, 0x45800000, v149
	v_cndmask_b32_e32 v166, v149, v166, vcc
	v_pk_mul_f32 v[126:127], v[126:127], v[166:167] op_sel_hi:[1,0]
	v_pk_mul_f32 v[124:125], v[124:125], v[166:167] op_sel_hi:[1,0]
	v_pk_mul_f32 v[120:121], v[120:121], v[166:167] op_sel_hi:[1,0]
	global_store_dwordx4 v[154:155], v[124:127], off
	v_pk_mul_f32 v[122:123], v[122:123], v[166:167] op_sel_hi:[1,0]
	v_pk_mul_f32 v[116:117], v[116:117], v[166:167] op_sel_hi:[1,0]
	v_cvt_pk_bf16_f32 v124, v124, v125
	v_cvt_pk_bf16_f32 v125, v126, v127
	global_store_dwordx2 v[160:161], v[124:125], off
	global_store_dwordx4 v[156:157], v[120:123], off
	v_pk_mul_f32 v[118:119], v[118:119], v[166:167] op_sel_hi:[1,0]
	v_pk_mul_f32 v[112:113], v[112:113], v[166:167] op_sel_hi:[1,0]
	v_cvt_pk_bf16_f32 v120, v120, v121
	v_cvt_pk_bf16_f32 v121, v122, v123
	global_store_dwordx2 v[162:163], v[120:121], off
	global_store_dwordx4 v[158:159], v[116:119], off
	v_pk_mul_f32 v[114:115], v[114:115], v[166:167] op_sel_hi:[1,0]
	v_bitop3_b32 v120, v130, s7, 16 bitop3:0xc8
	v_cvt_pk_bf16_f32 v116, v116, v117
	v_cvt_pk_bf16_f32 v117, v118, v119
	global_store_dwordx2 v[164:165], v[116:117], off
	global_store_dwordx4 v[150:151], v[112:115], off
	v_cvt_pk_bf16_f32 v116, v112, v113
	v_cvt_pk_bf16_f32 v117, v114, v115
	v_or_b32_e32 v120, s10, v120
	v_ashrrev_i32_e32 v121, 31, v120
	v_lshlrev_b32_e32 v112, 1, v167
	v_mov_b32_e32 v113, v131
	v_lshl_add_u64 v[114:115], v[152:153], 0, v[112:113]
	global_store_dwordx2 v[114:115], v[116:117], off
	v_or_b32_e32 v114, 16, v130
	v_mov_b32_e32 v115, v131
	v_lshl_add_u64 v[116:117], v[114:115], 2, s[4:5]
	global_load_dword v149, v[116:117], off
	v_lshlrev_b64 v[114:115], 12, v[114:115]
	v_lshlrev_b64 v[120:121], 9, v[120:121]
	v_lshl_add_u64 v[114:115], s[2:3], 0, v[114:115]
	v_lshl_add_u64 v[122:123], v[114:115], 0, v[146:147]
	v_lshl_add_u64 v[120:121], s[0:1], 0, v[120:121]
	v_lshl_add_u64 v[150:151], v[120:121], 0, v[138:139]
	v_lshl_add_u64 v[124:125], v[114:115], 0, v[144:145]
	v_mov_b32_e32 v117, v131
	v_or_b32_e32 v116, 32, v130
	v_lshl_add_u64 v[126:127], v[114:115], 0, v[142:143]
	v_lshl_add_u64 v[154:155], v[120:121], 0, v[136:137]
	v_lshl_add_u64 v[118:119], v[116:117], 2, s[4:5]
	v_lshl_add_u64 v[114:115], v[114:115], 0, v[140:141]
	s_waitcnt vmcnt(0)
	v_fmamk_f32 v149, v149, 0x3a800000, v148
	v_mul_f32_e32 v152, 0x4b800000, v149
	v_cmp_gt_f32_e32 vcc, s6, v149
	s_nop 1
	v_cndmask_b32_e32 v149, v149, v152, vcc
	v_rsq_f32_e32 v149, v149
	v_lshl_add_u64 v[152:153], v[120:121], 0, v[134:135]
	v_lshl_add_u64 v[120:121], v[120:121], 0, v[112:113]
	v_mul_f32_e32 v156, 0x45800000, v149
	v_cndmask_b32_e32 v156, v149, v156, vcc
	v_pk_mul_f32 v[110:111], v[110:111], v[156:157] op_sel_hi:[1,0]
	v_pk_mul_f32 v[108:109], v[108:109], v[156:157] op_sel_hi:[1,0]
	v_pk_mul_f32 v[104:105], v[104:105], v[156:157] op_sel_hi:[1,0]
	global_store_dwordx4 v[122:123], v[108:111], off
	v_pk_mul_f32 v[106:107], v[106:107], v[156:157] op_sel_hi:[1,0]
	v_pk_mul_f32 v[100:101], v[100:101], v[156:157] op_sel_hi:[1,0]
	v_cvt_pk_bf16_f32 v108, v108, v109
	v_cvt_pk_bf16_f32 v109, v110, v111
	global_store_dwordx2 v[150:151], v[108:109], off
	global_store_dwordx4 v[124:125], v[104:107], off
	v_pk_mul_f32 v[102:103], v[102:103], v[156:157] op_sel_hi:[1,0]
	v_pk_mul_f32 v[96:97], v[96:97], v[156:157] op_sel_hi:[1,0]
	v_cvt_pk_bf16_f32 v104, v104, v105
	v_cvt_pk_bf16_f32 v105, v106, v107
	global_store_dwordx2 v[152:153], v[104:105], off
	global_store_dwordx4 v[126:127], v[100:103], off
	v_pk_mul_f32 v[98:99], v[98:99], v[156:157] op_sel_hi:[1,0]
	s_nop 0
	v_cvt_pk_bf16_f32 v100, v100, v101
	v_cvt_pk_bf16_f32 v101, v102, v103
	global_store_dwordx2 v[154:155], v[100:101], off
	global_store_dwordx4 v[114:115], v[96:99], off
	v_bitop3_b32 v102, v130, s8, 32 bitop3:0xc8
	v_or_b32_e32 v102, s10, v102
	v_cvt_pk_bf16_f32 v96, v96, v97
	v_cvt_pk_bf16_f32 v97, v98, v99
	global_store_dwordx2 v[120:121], v[96:97], off
	global_load_dword v114, v[118:119], off
	v_lshlrev_b64 v[98:99], 12, v[116:117]
	v_ashrrev_i32_e32 v103, 31, v102
	v_lshlrev_b64 v[102:103], 9, v[102:103]
	v_lshl_add_u64 v[98:99], s[2:3], 0, v[98:99]
	v_lshl_add_u64 v[104:105], v[98:99], 0, v[146:147]
	v_lshl_add_u64 v[102:103], s[0:1], 0, v[102:103]
	v_lshl_add_u64 v[110:111], v[102:103], 0, v[138:139]
	v_lshl_add_u64 v[106:107], v[98:99], 0, v[144:145]
	v_mov_b32_e32 v97, v131
	v_or_b32_e32 v96, 48, v130
	v_lshl_add_u64 v[108:109], v[98:99], 0, v[142:143]
	v_lshl_add_u64 v[116:117], v[102:103], 0, v[136:137]
	v_lshl_add_u64 v[100:101], v[96:97], 2, s[4:5]
	v_lshl_add_u64 v[98:99], v[98:99], 0, v[140:141]
	s_movk_i32 s4, 0xff
	s_movk_i32 s5, 0xcf
	s_waitcnt vmcnt(0)
	v_fmamk_f32 v114, v114, 0x3a800000, v148
	v_mul_f32_e32 v115, 0x4b800000, v114
	v_cmp_gt_f32_e32 vcc, s6, v114
	s_nop 1
	v_cndmask_b32_e32 v114, v114, v115, vcc
	v_rsq_f32_e32 v118, v114
	v_lshl_add_u64 v[114:115], v[102:103], 0, v[134:135]
	v_lshl_add_u64 v[102:103], v[102:103], 0, v[112:113]
	v_mul_f32_e32 v119, 0x45800000, v118
	v_cndmask_b32_e32 v118, v118, v119, vcc
	v_pk_mul_f32 v[94:95], v[94:95], v[118:119] op_sel_hi:[1,0]
	v_pk_mul_f32 v[92:93], v[92:93], v[118:119] op_sel_hi:[1,0]
	v_pk_mul_f32 v[88:89], v[88:89], v[118:119] op_sel_hi:[1,0]
	global_store_dwordx4 v[104:105], v[92:95], off
	v_pk_mul_f32 v[90:91], v[90:91], v[118:119] op_sel_hi:[1,0]
	v_pk_mul_f32 v[84:85], v[84:85], v[118:119] op_sel_hi:[1,0]
	v_cvt_pk_bf16_f32 v92, v92, v93
	v_cvt_pk_bf16_f32 v93, v94, v95
	global_store_dwordx2 v[110:111], v[92:93], off
	global_store_dwordx4 v[106:107], v[88:91], off
	v_pk_mul_f32 v[86:87], v[86:87], v[118:119] op_sel_hi:[1,0]
	v_pk_mul_f32 v[80:81], v[80:81], v[118:119] op_sel_hi:[1,0]
	v_cvt_pk_bf16_f32 v88, v88, v89
	v_cvt_pk_bf16_f32 v89, v90, v91
	global_store_dwordx2 v[114:115], v[88:89], off
	global_store_dwordx4 v[108:109], v[84:87], off
	v_pk_mul_f32 v[82:83], v[82:83], v[118:119] op_sel_hi:[1,0]
	s_nop 0
	v_cvt_pk_bf16_f32 v84, v84, v85
	v_cvt_pk_bf16_f32 v85, v86, v87
	global_store_dwordx2 v[116:117], v[84:85], off
	global_store_dwordx4 v[98:99], v[80:83], off
	s_nop 1
	v_cvt_pk_bf16_f32 v80, v80, v81
	v_cvt_pk_bf16_f32 v81, v82, v83
	global_store_dwordx2 v[102:103], v[80:81], off
	global_load_dword v92, v[100:101], off
	v_lshlrev_b64 v[80:81], 12, v[96:97]
	v_bitop3_b32 v82, v130, s4, 48 bitop3:0xc8
	v_or_b32_e32 v82, s10, v82
	v_ashrrev_i32_e32 v83, 31, v82
	v_lshlrev_b64 v[82:83], 9, v[82:83]
	v_lshl_add_u64 v[80:81], s[2:3], 0, v[80:81]
	v_lshl_add_u64 v[84:85], v[80:81], 0, v[146:147]
	v_lshl_add_u64 v[82:83], s[0:1], 0, v[82:83]
	v_lshl_add_u64 v[90:91], v[82:83], 0, v[138:139]
	v_lshl_add_u64 v[86:87], v[80:81], 0, v[144:145]
	v_lshl_add_u64 v[88:89], v[80:81], 0, v[142:143]
	v_lshl_add_u64 v[94:95], v[82:83], 0, v[136:137]
	v_lshl_add_u64 v[80:81], v[80:81], 0, v[140:141]
	s_waitcnt vmcnt(0)
	v_fmamk_f32 v92, v92, 0x3a800000, v148
	v_mul_f32_e32 v93, 0x4b800000, v92
	v_cmp_gt_f32_e32 vcc, s6, v92
	s_nop 1
	v_cndmask_b32_e32 v92, v92, v93, vcc
	v_rsq_f32_e32 v96, v92
	v_lshl_add_u64 v[92:93], v[82:83], 0, v[134:135]
	v_lshl_add_u64 v[82:83], v[82:83], 0, v[112:113]
	v_mul_f32_e32 v97, 0x45800000, v96
	v_cndmask_b32_e32 v96, v96, v97, vcc
	v_pk_mul_f32 v[78:79], v[78:79], v[96:97] op_sel_hi:[1,0]
	v_pk_mul_f32 v[76:77], v[76:77], v[96:97] op_sel_hi:[1,0]
	v_pk_mul_f32 v[72:73], v[72:73], v[96:97] op_sel_hi:[1,0]
	global_store_dwordx4 v[84:85], v[76:79], off
	v_pk_mul_f32 v[74:75], v[74:75], v[96:97] op_sel_hi:[1,0]
	v_pk_mul_f32 v[68:69], v[68:69], v[96:97] op_sel_hi:[1,0]
	v_cvt_pk_bf16_f32 v76, v76, v77
	v_cvt_pk_bf16_f32 v77, v78, v79
	global_store_dwordx2 v[90:91], v[76:77], off
	global_store_dwordx4 v[86:87], v[72:75], off
	v_pk_mul_f32 v[70:71], v[70:71], v[96:97] op_sel_hi:[1,0]
	v_pk_mul_f32 v[64:65], v[64:65], v[96:97] op_sel_hi:[1,0]
	v_cvt_pk_bf16_f32 v72, v72, v73
	v_cvt_pk_bf16_f32 v73, v74, v75
	global_store_dwordx2 v[92:93], v[72:73], off
	global_store_dwordx4 v[88:89], v[68:71], off
	v_pk_mul_f32 v[66:67], v[66:67], v[96:97] op_sel_hi:[1,0]
	s_nop 0
	v_cvt_pk_bf16_f32 v68, v68, v69
	v_cvt_pk_bf16_f32 v69, v70, v71
	global_store_dwordx2 v[94:95], v[68:69], off
	global_store_dwordx4 v[80:81], v[64:67], off
	s_nop 1
	v_cvt_pk_bf16_f32 v64, v64, v65
	v_cvt_pk_bf16_f32 v65, v66, v67
	global_store_dwordx2 v[82:83], v[64:65], off
	global_load_dword v76, v[132:133], off offset:512
	v_add_u32_e32 v64, 0x80, v130
	v_mov_b32_e32 v65, v131
	v_lshlrev_b32_e32 v68, 2, v64
	v_lshlrev_b64 v[66:67], 12, v[64:65]
	v_and_b32_e32 v65, 0xfffffc00, v68
	v_or_b32_e32 v81, s9, v65
	v_and_or_b32 v64, v64, s5, v81
	v_ashrrev_i32_e32 v65, 31, v64
	v_lshlrev_b64 v[64:65], 9, v[64:65]
	v_lshl_add_u64 v[66:67], s[2:3], 0, v[66:67]
	v_lshl_add_u64 v[68:69], v[66:67], 0, v[146:147]
	v_lshl_add_u64 v[64:65], s[0:1], 0, v[64:65]
	v_lshl_add_u64 v[74:75], v[64:65], 0, v[138:139]
	v_lshl_add_u64 v[70:71], v[66:67], 0, v[144:145]
	v_lshl_add_u64 v[72:73], v[66:67], 0, v[142:143]
	v_lshl_add_u64 v[78:79], v[64:65], 0, v[136:137]
	v_lshl_add_u64 v[66:67], v[66:67], 0, v[140:141]
	s_waitcnt vmcnt(0)
	v_fmamk_f32 v76, v76, 0x3a800000, v148
	v_mul_f32_e32 v77, 0x4b800000, v76
	v_cmp_gt_f32_e32 vcc, s6, v76
	s_nop 1
	v_cndmask_b32_e32 v76, v76, v77, vcc
	v_rsq_f32_e32 v80, v76
	v_lshl_add_u64 v[76:77], v[64:65], 0, v[134:135]
	v_lshl_add_u64 v[64:65], v[64:65], 0, v[112:113]
	v_mul_f32_e32 v82, 0x45800000, v80
	v_cndmask_b32_e32 v80, v80, v82, vcc
	v_pk_mul_f32 v[62:63], v[62:63], v[80:81] op_sel_hi:[1,0]
	v_pk_mul_f32 v[60:61], v[60:61], v[80:81] op_sel_hi:[1,0]
	v_pk_mul_f32 v[56:57], v[56:57], v[80:81] op_sel_hi:[1,0]
	global_store_dwordx4 v[68:69], v[60:63], off
	v_pk_mul_f32 v[58:59], v[58:59], v[80:81] op_sel_hi:[1,0]
	v_pk_mul_f32 v[52:53], v[52:53], v[80:81] op_sel_hi:[1,0]
	v_cvt_pk_bf16_f32 v60, v60, v61
	v_cvt_pk_bf16_f32 v61, v62, v63
	global_store_dwordx2 v[74:75], v[60:61], off
	global_store_dwordx4 v[70:71], v[56:59], off
	v_pk_mul_f32 v[54:55], v[54:55], v[80:81] op_sel_hi:[1,0]
	v_pk_mul_f32 v[48:49], v[48:49], v[80:81] op_sel_hi:[1,0]
	v_cvt_pk_bf16_f32 v56, v56, v57
	v_cvt_pk_bf16_f32 v57, v58, v59
	global_store_dwordx2 v[76:77], v[56:57], off
	global_store_dwordx4 v[72:73], v[52:55], off
	v_pk_mul_f32 v[50:51], v[50:51], v[80:81] op_sel_hi:[1,0]
	s_nop 0
	v_cvt_pk_bf16_f32 v52, v52, v53
	v_cvt_pk_bf16_f32 v53, v54, v55
	global_store_dwordx2 v[78:79], v[52:53], off
	global_store_dwordx4 v[66:67], v[48:51], off
	s_nop 1
	v_cvt_pk_bf16_f32 v48, v48, v49
	v_cvt_pk_bf16_f32 v49, v50, v51
	global_store_dwordx2 v[64:65], v[48:49], off
	global_load_dword v60, v[132:133], off offset:576
	v_mov_b32_e32 v49, v131
	v_add_u32_e32 v48, 0x90, v130
	v_lshlrev_b64 v[50:51], 12, v[48:49]
	v_and_or_b32 v48, v48, s7, v81
	v_ashrrev_i32_e32 v49, 31, v48
	v_lshlrev_b64 v[48:49], 9, v[48:49]
	v_lshl_add_u64 v[50:51], s[2:3], 0, v[50:51]
	v_lshl_add_u64 v[52:53], v[50:51], 0, v[146:147]
	v_lshl_add_u64 v[48:49], s[0:1], 0, v[48:49]
	v_lshl_add_u64 v[58:59], v[48:49], 0, v[138:139]
	v_lshl_add_u64 v[54:55], v[50:51], 0, v[144:145]
	v_lshl_add_u64 v[56:57], v[50:51], 0, v[142:143]
	v_lshl_add_u64 v[62:63], v[48:49], 0, v[136:137]
	v_lshl_add_u64 v[50:51], v[50:51], 0, v[140:141]
	s_waitcnt vmcnt(0)
	v_fmamk_f32 v60, v60, 0x3a800000, v148
	v_mul_f32_e32 v61, 0x4b800000, v60
	v_cmp_gt_f32_e32 vcc, s6, v60
	s_nop 1
	v_cndmask_b32_e32 v60, v60, v61, vcc
	v_rsq_f32_e32 v64, v60
	v_lshl_add_u64 v[60:61], v[48:49], 0, v[134:135]
	v_lshl_add_u64 v[48:49], v[48:49], 0, v[112:113]
	v_mul_f32_e32 v65, 0x45800000, v64
	v_cndmask_b32_e32 v64, v64, v65, vcc
	v_pk_mul_f32 v[46:47], v[46:47], v[64:65] op_sel_hi:[1,0]
	v_pk_mul_f32 v[44:45], v[44:45], v[64:65] op_sel_hi:[1,0]
	v_pk_mul_f32 v[40:41], v[40:41], v[64:65] op_sel_hi:[1,0]
	global_store_dwordx4 v[52:53], v[44:47], off
	v_pk_mul_f32 v[42:43], v[42:43], v[64:65] op_sel_hi:[1,0]
	v_pk_mul_f32 v[36:37], v[36:37], v[64:65] op_sel_hi:[1,0]
	v_cvt_pk_bf16_f32 v44, v44, v45
	v_cvt_pk_bf16_f32 v45, v46, v47
	global_store_dwordx2 v[58:59], v[44:45], off
	global_store_dwordx4 v[54:55], v[40:43], off
	v_pk_mul_f32 v[38:39], v[38:39], v[64:65] op_sel_hi:[1,0]
	v_pk_mul_f32 v[32:33], v[32:33], v[64:65] op_sel_hi:[1,0]
	v_cvt_pk_bf16_f32 v40, v40, v41
	v_cvt_pk_bf16_f32 v41, v42, v43
	global_store_dwordx2 v[60:61], v[40:41], off
	global_store_dwordx4 v[56:57], v[36:39], off
	v_pk_mul_f32 v[34:35], v[34:35], v[64:65] op_sel_hi:[1,0]
	s_nop 0
	v_cvt_pk_bf16_f32 v36, v36, v37
	v_cvt_pk_bf16_f32 v37, v38, v39
	global_store_dwordx2 v[62:63], v[36:37], off
	global_store_dwordx4 v[50:51], v[32:35], off
	s_nop 1
	v_cvt_pk_bf16_f32 v32, v32, v33
	v_cvt_pk_bf16_f32 v33, v34, v35
	global_store_dwordx2 v[48:49], v[32:33], off
	global_load_dword v44, v[132:133], off offset:640
	v_mov_b32_e32 v33, v131
	v_add_u32_e32 v32, 0xa0, v130
	v_lshlrev_b64 v[34:35], 12, v[32:33]
	v_and_or_b32 v32, v32, s8, v81
	v_ashrrev_i32_e32 v33, 31, v32
	v_lshlrev_b64 v[32:33], 9, v[32:33]
	v_lshl_add_u64 v[34:35], s[2:3], 0, v[34:35]
	v_lshl_add_u64 v[36:37], v[34:35], 0, v[146:147]
	v_lshl_add_u64 v[32:33], s[0:1], 0, v[32:33]
	v_lshl_add_u64 v[42:43], v[32:33], 0, v[138:139]
	v_lshl_add_u64 v[38:39], v[34:35], 0, v[144:145]
	v_lshl_add_u64 v[40:41], v[34:35], 0, v[142:143]
	v_lshl_add_u64 v[46:47], v[32:33], 0, v[136:137]
	v_lshl_add_u64 v[34:35], v[34:35], 0, v[140:141]
	v_add_u32_e32 v130, 0xb0, v130
	s_waitcnt vmcnt(0)
	v_fmamk_f32 v44, v44, 0x3a800000, v148
	v_mul_f32_e32 v45, 0x4b800000, v44
	v_cmp_gt_f32_e32 vcc, s6, v44
	s_nop 1
	v_cndmask_b32_e32 v44, v44, v45, vcc
	v_rsq_f32_e32 v48, v44
	v_lshl_add_u64 v[44:45], v[32:33], 0, v[134:135]
	v_lshl_add_u64 v[32:33], v[32:33], 0, v[112:113]
	v_mul_f32_e32 v49, 0x45800000, v48
	v_cndmask_b32_e32 v48, v48, v49, vcc
	v_pk_mul_f32 v[30:31], v[30:31], v[48:49] op_sel_hi:[1,0]
	v_pk_mul_f32 v[28:29], v[28:29], v[48:49] op_sel_hi:[1,0]
	v_pk_mul_f32 v[24:25], v[24:25], v[48:49] op_sel_hi:[1,0]
	global_store_dwordx4 v[36:37], v[28:31], off
	v_pk_mul_f32 v[26:27], v[26:27], v[48:49] op_sel_hi:[1,0]
	v_pk_mul_f32 v[20:21], v[20:21], v[48:49] op_sel_hi:[1,0]
	v_cvt_pk_bf16_f32 v28, v28, v29
	v_cvt_pk_bf16_f32 v29, v30, v31
	global_store_dwordx2 v[42:43], v[28:29], off
	global_store_dwordx4 v[38:39], v[24:27], off
	v_pk_mul_f32 v[22:23], v[22:23], v[48:49] op_sel_hi:[1,0]
	v_pk_mul_f32 v[16:17], v[16:17], v[48:49] op_sel_hi:[1,0]
	v_cvt_pk_bf16_f32 v24, v24, v25
	v_cvt_pk_bf16_f32 v25, v26, v27
	global_store_dwordx2 v[44:45], v[24:25], off
	global_store_dwordx4 v[40:41], v[20:23], off
	v_pk_mul_f32 v[18:19], v[18:19], v[48:49] op_sel_hi:[1,0]
	s_nop 0
	v_cvt_pk_bf16_f32 v20, v20, v21
	v_cvt_pk_bf16_f32 v21, v22, v23
	global_store_dwordx2 v[46:47], v[20:21], off
	global_store_dwordx4 v[34:35], v[16:19], off
	s_nop 1
	v_cvt_pk_bf16_f32 v16, v16, v17
	v_cvt_pk_bf16_f32 v17, v18, v19
	global_store_dwordx2 v[32:33], v[16:17], off
	global_load_dword v28, v[132:133], off offset:704
	v_and_or_b32 v18, v130, s4, v81
	v_lshlrev_b64 v[16:17], 12, v[130:131]
	v_ashrrev_i32_e32 v19, 31, v18
	v_lshlrev_b64 v[18:19], 9, v[18:19]
	v_lshl_add_u64 v[16:17], s[2:3], 0, v[16:17]
	v_lshl_add_u64 v[20:21], v[16:17], 0, v[146:147]
	v_lshl_add_u64 v[18:19], s[0:1], 0, v[18:19]
	v_lshl_add_u64 v[26:27], v[18:19], 0, v[138:139]
	v_lshl_add_u64 v[22:23], v[16:17], 0, v[144:145]
	v_lshl_add_u64 v[24:25], v[16:17], 0, v[142:143]
	v_lshl_add_u64 v[30:31], v[18:19], 0, v[136:137]
	v_lshl_add_u64 v[16:17], v[16:17], 0, v[140:141]
	s_waitcnt vmcnt(0)
	v_fmac_f32_e32 v148, 0x3a800000, v28
	v_mul_f32_e32 v28, 0x4b800000, v148
	v_cmp_gt_f32_e32 vcc, s6, v148
	s_nop 1
	v_cndmask_b32_e32 v28, v148, v28, vcc
	v_rsq_f32_e32 v32, v28
	v_lshl_add_u64 v[28:29], v[18:19], 0, v[134:135]
	v_lshl_add_u64 v[18:19], v[18:19], 0, v[112:113]
	v_mul_f32_e32 v33, 0x45800000, v32
	v_cndmask_b32_e32 v32, v32, v33, vcc
	v_pk_mul_f32 v[14:15], v[14:15], v[32:33] op_sel_hi:[1,0]
	v_pk_mul_f32 v[12:13], v[12:13], v[32:33] op_sel_hi:[1,0]
	v_pk_mul_f32 v[8:9], v[8:9], v[32:33] op_sel_hi:[1,0]
	global_store_dwordx4 v[20:21], v[12:15], off
	v_pk_mul_f32 v[10:11], v[10:11], v[32:33] op_sel_hi:[1,0]
	v_pk_mul_f32 v[4:5], v[4:5], v[32:33] op_sel_hi:[1,0]
	v_cvt_pk_bf16_f32 v12, v12, v13
	v_cvt_pk_bf16_f32 v13, v14, v15
	global_store_dwordx2 v[26:27], v[12:13], off
	global_store_dwordx4 v[22:23], v[8:11], off
	v_pk_mul_f32 v[6:7], v[6:7], v[32:33] op_sel_hi:[1,0]
	v_pk_mul_f32 v[0:1], v[0:1], v[32:33] op_sel_hi:[1,0]
	v_cvt_pk_bf16_f32 v8, v8, v9
	v_cvt_pk_bf16_f32 v9, v10, v11
	global_store_dwordx2 v[28:29], v[8:9], off
	global_store_dwordx4 v[24:25], v[4:7], off
	v_pk_mul_f32 v[2:3], v[2:3], v[32:33] op_sel_hi:[1,0]
	s_nop 0
	v_cvt_pk_bf16_f32 v4, v4, v5
	v_cvt_pk_bf16_f32 v5, v6, v7
	global_store_dwordx2 v[30:31], v[4:5], off
	global_store_dwordx4 v[16:17], v[0:3], off
	s_nop 1
	v_cvt_pk_bf16_f32 v0, v0, v1
	v_cvt_pk_bf16_f32 v1, v2, v3
	global_store_dwordx2 v[18:19], v[0:1], off
	s_waitcnt vmcnt(0)
	s_cbranch_scc0 .LBB0_440
	s_barrier

.LBB0_980:
	s_add_u32 s10, s28, 0x7200000
	s_addc_u32 s11, s29, 0
	s_add_u32 s12, s28, 0x2f10400
	s_addc_u32 s13, s29, 0
	s_lshl_b32 s2, s2, 5
	s_mov_b64 s[14:15], 0x80
	s_and_b32 s18, s2, 0x60
	s_add_i32 m0, s51, 0x18000
	v_lshl_add_u64 v[6:7], v[6:7], 0, s[14:15]
	s_ashr_i32 s66, s34, 31
	s_ashr_i32 s67, s22, 31
	s_lshl_b32 s16, s5, 13
	s_lshl_b32 s17, s18, 7
	s_waitcnt vmcnt(2)
	s_barrier
	global_load_lds_dwordx4 v[6:7], off
	v_lshl_add_u64 v[4:5], v[4:5], 0, s[14:15]
	s_add_i32 m0, s51, 0x1a000
	s_add_i32 s68, s51, 0x8000
	s_add_i32 s69, s51, 0xa000
	global_load_lds_dwordx4 v[4:5], off
	v_lshl_add_u64 v[0:1], v[0:1], 0, s[14:15]
	s_mov_b32 m0, s68
	s_add_u32 s2, s56, 0x40080
	global_load_lds_dwordx4 v[0:1], off
	v_lshl_add_u64 v[0:1], v[2:3], 0, s[14:15]
	s_mov_b32 m0, s69
	s_addc_u32 s3, s57, 0
	global_load_lds_dwordx4 v[0:1], off
	s_add_i32 m0, s51, 0x1c000
	s_nop 0
	global_load_lds_dwordx4 v132, s[2:3]
	v_lshl_add_u64 v[0:1], s[2:3], 0, v[136:137]
	s_add_i32 m0, s51, 0x1e000
	v_lshlrev_b32_e32 v2, 6, v128
	global_load_lds_dwordx4 v[0:1], off
	v_and_b32_e32 v0, 3, v150
	v_lshlrev_b32_e32 v1, 4, v0
	s_movk_i32 s2, 0x3c0
	v_lshlrev_b32_e32 v3, 2, v128
	v_and_or_b32 v2, v2, s2, v1
	v_and_b32_e32 v3, 32, v3
	v_cmp_eq_u32_e64 s[2:3], 0, v0
	v_lshl_or_b32 v154, v0, 3, s18
	v_lshlrev_b32_e32 v0, 8, v128
	v_bitop3_b32 v153, s17, v2, v3 bitop3:0xf6
	v_and_b32_e32 v0, 0x38000, v0
	v_lshlrev_b32_e32 v2, 11, v10
	v_or3_b32 v0, v8, v0, v2
	v_add_u32_e32 v138, v0, v9
	v_lshlrev_b32_e32 v0, 4, v11
	v_lshlrev_b32_e32 v4, 2, v151
	v_and_b32_e32 v0, 0x78000, v0
	v_lshl_or_b32 v1, v151, 6, v1
	v_and_b32_e32 v4, 32, v4
	s_waitcnt vmcnt(6)
	s_cmpk_lt_u32 s4, 0x100
	v_or3_b32 v0, v8, v0, v2
	v_bitop3_b32 v1, v1, s16, v4 bitop3:0xde
	s_cselect_b64 s[16:17], -1, 0
	v_add_u32_e32 v140, v0, v9
	s_add_i32 s71, 0, 0x10000
	s_add_i32 s72, 0, 0x14000
	v_mbcnt_lo_u32_b32 v0, -1, 0
	s_mov_b32 s70, s34
	v_lshl_or_b32 v152, s5, 6, v151
	v_mov_b32_e32 v139, v133
	v_mov_b32_e32 v141, v133
	v_mov_b64_e32 v[142:143], 0x100
	v_mov_b64_e32 v[144:145], 0xff
	v_add_u32_e32 v155, s71, v153
	v_add_u32_e32 v156, s72, v153
	v_add_u32_e32 v157, 0, v1
	v_mbcnt_hi_u32_b32 v158, -1, v0
	s_barrier
	s_branch .LBB0_983

.LBB0_990:
	ds_read_b128 v[146:149], v155
	ds_read_b128 v[160:163], v155 offset:1024
	ds_read_b128 v[164:167], v155 offset:2048
	ds_read_b128 v[168:171], v155 offset:3072
	ds_read_b128 v[172:175], v156
	ds_read_b128 v[176:179], v156 offset:1024
	ds_read_b128 v[180:183], v156 offset:2048
	ds_read_b128 v[184:187], v156 offset:3072
	s_add_u32 s23, s54, 0xfffc0080
	s_addc_u32 s33, s55, -1
	s_cmp_eq_u32 s75, 12
	s_cselect_b32 s59, s20, s33
	s_cselect_b32 s58, s21, s23
	s_cselect_b32 s57, s19, s74
	s_cselect_b32 s56, s45, s73
	s_add_i32 m0, s51, 0xc000
	ds_read_b128 v[188:191], v157
	ds_read_b128 v[192:195], v157 offset:1024
	ds_read_b128 v[196:199], v157 offset:2048
	ds_read_b128 v[200:203], v157 offset:3072
	ds_read_b128 v[204:207], v157 offset:4096
	ds_read_b128 v[208:211], v157 offset:5120
	ds_read_b128 v[212:215], v157 offset:6144
	ds_read_b128 v[216:219], v157 offset:7168
	global_load_lds_dwordx4 v138, s[54:55]
	s_add_i32 m0, s51, 0xe000
	s_nop 0
	global_load_lds_dwordx4 v140, s[54:55]
	s_waitcnt vmcnt(8)
	s_waitcnt lgkmcnt(0)
	s_barrier
	s_setprio 1
	v_mfma_f32_16x16x32_bf16 v[124:127], v[146:149], v[188:191], v[124:127]
	v_mfma_f32_16x16x32_bf16 v[120:123], v[164:167], v[188:191], v[120:123]
	v_mfma_f32_16x16x32_bf16 v[108:111], v[146:149], v[196:199], v[108:111]
	v_mfma_f32_16x16x32_bf16 v[104:107], v[164:167], v[196:199], v[104:107]
	v_mfma_f32_16x16x32_bf16 v[92:95], v[146:149], v[204:207], v[92:95]
	v_mfma_f32_16x16x32_bf16 v[88:91], v[164:167], v[204:207], v[88:91]
	v_mfma_f32_16x16x32_bf16 v[76:79], v[146:149], v[212:215], v[76:79]
	v_mfma_f32_16x16x32_bf16 v[72:75], v[164:167], v[212:215], v[72:75]
	v_mfma_f32_16x16x32_bf16 v[124:127], v[160:163], v[192:195], v[124:127]
	v_mfma_f32_16x16x32_bf16 v[120:123], v[168:171], v[192:195], v[120:123]
	v_mfma_f32_16x16x32_bf16 v[108:111], v[160:163], v[200:203], v[108:111]
	v_mfma_f32_16x16x32_bf16 v[104:107], v[168:171], v[200:203], v[104:107]
	v_mfma_f32_16x16x32_bf16 v[92:95], v[160:163], v[208:211], v[92:95]
	v_mfma_f32_16x16x32_bf16 v[88:91], v[168:171], v[208:211], v[88:91]
	v_mfma_f32_16x16x32_bf16 v[76:79], v[160:163], v[216:219], v[76:79]
	v_mfma_f32_16x16x32_bf16 v[72:75], v[168:171], v[216:219], v[72:75]
	v_mfma_f32_16x16x32_bf16 v[116:119], v[172:175], v[188:191], v[116:119]
	v_mfma_f32_16x16x32_bf16 v[112:115], v[180:183], v[188:191], v[112:115]
	v_mfma_f32_16x16x32_bf16 v[100:103], v[172:175], v[196:199], v[100:103]
	v_mfma_f32_16x16x32_bf16 v[96:99], v[180:183], v[196:199], v[96:99]
	v_mfma_f32_16x16x32_bf16 v[84:87], v[172:175], v[204:207], v[84:87]
	v_mfma_f32_16x16x32_bf16 v[80:83], v[180:183], v[204:207], v[80:83]
	v_mfma_f32_16x16x32_bf16 v[68:71], v[172:175], v[212:215], v[68:71]
	v_mfma_f32_16x16x32_bf16 v[64:67], v[180:183], v[212:215], v[64:67]
	v_mfma_f32_16x16x32_bf16 v[116:119], v[176:179], v[192:195], v[116:119]
	v_mfma_f32_16x16x32_bf16 v[112:115], v[184:187], v[192:195], v[112:115]
	v_mfma_f32_16x16x32_bf16 v[100:103], v[176:179], v[200:203], v[100:103]
	v_mfma_f32_16x16x32_bf16 v[96:99], v[184:187], v[200:203], v[96:99]
	v_mfma_f32_16x16x32_bf16 v[84:87], v[176:179], v[208:211], v[84:87]
	v_mfma_f32_16x16x32_bf16 v[80:83], v[184:187], v[208:211], v[80:83]
	v_mfma_f32_16x16x32_bf16 v[68:71], v[176:179], v[216:219], v[68:71]
	v_mfma_f32_16x16x32_bf16 v[64:67], v[184:187], v[216:219], v[64:67]
	s_setprio 0
	s_barrier
	s_add_i32 s23, s71, s62
	v_lshl_add_u64 v[220:221], s[56:57], 0, v[132:133]
	s_mov_b32 m0, s23
	ds_read_b128 v[188:191], v157 offset:16384
	ds_read_b128 v[192:195], v157 offset:17408
	ds_read_b128 v[196:199], v157 offset:18432
	ds_read_b128 v[200:203], v157 offset:19456
	ds_read_b128 v[204:207], v157 offset:20480
	ds_read_b128 v[208:211], v157 offset:21504
	ds_read_b128 v[212:215], v157 offset:22528
	ds_read_b128 v[216:219], v157 offset:23552
	global_load_lds_dwordx4 v[220:221], off
	s_add_i32 m0, s23, 0x2000
	s_add_u32 s76, s56, 0x40000
	v_lshl_add_u64 v[222:223], s[56:57], 0, v[136:137]
	s_addc_u32 s77, s57, 0
	s_add_i32 s23, s72, s62
	global_load_lds_dwordx4 v[222:223], off
	s_mov_b32 m0, s23
	v_lshl_add_u64 v[226:227], s[58:59], 0, v[134:135]
	global_load_lds_dwordx4 v132, s[76:77]
	s_add_i32 m0, s23, 0x2000
	s_nop 0
	global_load_lds_dwordx4 v136, s[76:77]
	v_lshl_add_u64 v[224:225], s[58:59], 0, v[130:131]
	s_mov_b32 m0, s51
	s_nop 0
	global_load_lds_dwordx4 v[224:225], off
	s_mov_b32 m0, s53
	s_nop 0
	global_load_lds_dwordx4 v[226:227], off
	s_waitcnt vmcnt(8)
	s_waitcnt lgkmcnt(0)
	s_barrier
	s_setprio 1
	v_mfma_f32_16x16x32_bf16 v[60:63], v[146:149], v[188:191], v[60:63]
	v_mfma_f32_16x16x32_bf16 v[56:59], v[164:167], v[188:191], v[56:59]
	v_mfma_f32_16x16x32_bf16 v[44:47], v[146:149], v[196:199], v[44:47]
	v_mfma_f32_16x16x32_bf16 v[40:43], v[164:167], v[196:199], v[40:43]
	v_mfma_f32_16x16x32_bf16 v[28:31], v[146:149], v[204:207], v[28:31]
	v_mfma_f32_16x16x32_bf16 v[24:27], v[164:167], v[204:207], v[24:27]
	v_mfma_f32_16x16x32_bf16 v[12:15], v[146:149], v[212:215], v[12:15]
	v_mfma_f32_16x16x32_bf16 v[8:11], v[164:167], v[212:215], v[8:11]
	v_mfma_f32_16x16x32_bf16 v[60:63], v[160:163], v[192:195], v[60:63]
	v_mfma_f32_16x16x32_bf16 v[56:59], v[168:171], v[192:195], v[56:59]
	v_mfma_f32_16x16x32_bf16 v[44:47], v[160:163], v[200:203], v[44:47]
	v_mfma_f32_16x16x32_bf16 v[40:43], v[168:171], v[200:203], v[40:43]
	v_mfma_f32_16x16x32_bf16 v[28:31], v[160:163], v[208:211], v[28:31]
	v_mfma_f32_16x16x32_bf16 v[24:27], v[168:171], v[208:211], v[24:27]
	v_mfma_f32_16x16x32_bf16 v[12:15], v[160:163], v[216:219], v[12:15]
	v_mfma_f32_16x16x32_bf16 v[8:11], v[168:171], v[216:219], v[8:11]
	v_mfma_f32_16x16x32_bf16 v[52:55], v[172:175], v[188:191], v[52:55]
	v_mfma_f32_16x16x32_bf16 v[48:51], v[180:183], v[188:191], v[48:51]
	v_mfma_f32_16x16x32_bf16 v[36:39], v[172:175], v[196:199], v[36:39]
	v_mfma_f32_16x16x32_bf16 v[32:35], v[180:183], v[196:199], v[32:35]
	v_mfma_f32_16x16x32_bf16 v[20:23], v[172:175], v[204:207], v[20:23]
	v_mfma_f32_16x16x32_bf16 v[16:19], v[180:183], v[204:207], v[16:19]
	v_mfma_f32_16x16x32_bf16 v[4:7], v[172:175], v[212:215], v[4:7]
	v_mfma_f32_16x16x32_bf16 v[0:3], v[180:183], v[212:215], v[0:3]
	v_mfma_f32_16x16x32_bf16 v[52:55], v[176:179], v[192:195], v[52:55]
	v_mfma_f32_16x16x32_bf16 v[48:51], v[184:187], v[192:195], v[48:51]
	v_mfma_f32_16x16x32_bf16 v[36:39], v[176:179], v[200:203], v[36:39]
	v_mfma_f32_16x16x32_bf16 v[32:35], v[184:187], v[200:203], v[32:35]
	v_mfma_f32_16x16x32_bf16 v[20:23], v[176:179], v[208:211], v[20:23]
	v_mfma_f32_16x16x32_bf16 v[16:19], v[184:187], v[208:211], v[16:19]
	v_mfma_f32_16x16x32_bf16 v[4:7], v[176:179], v[216:219], v[4:7]
	v_mfma_f32_16x16x32_bf16 v[0:3], v[184:187], v[216:219], v[0:3]
	s_setprio 0
	s_barrier
	s_add_i32 s23, 0, 0x18000
	v_add_u32_e32 v159, s23, v153
	s_add_i32 s33, 0, 0x1c000
	ds_read_b128 v[146:149], v159
	ds_read_b128 v[160:163], v159 offset:1024
	ds_read_b128 v[164:167], v159 offset:2048
	ds_read_b128 v[168:171], v159 offset:3072
	v_add_u32_e32 v159, s33, v153
	ds_read_b128 v[172:175], v159
	ds_read_b128 v[176:179], v159 offset:1024
	ds_read_b128 v[180:183], v159 offset:2048
	ds_read_b128 v[184:187], v159 offset:3072
	s_add_u32 s58, s58, 0x40000
	s_addc_u32 s59, s59, 0
	s_mov_b32 m0, s63
	ds_read_b128 v[188:191], v157 offset:32768
	ds_read_b128 v[192:195], v157 offset:33792
	ds_read_b128 v[196:199], v157 offset:34816
	ds_read_b128 v[200:203], v157 offset:35840
	ds_read_b128 v[204:207], v157 offset:36864
	ds_read_b128 v[208:211], v157 offset:37888
	ds_read_b128 v[212:215], v157 offset:38912
	ds_read_b128 v[216:219], v157 offset:39936
	global_load_lds_dwordx4 v130, s[58:59]
	v_lshl_add_u64 v[228:229], s[58:59], 0, v[134:135]
	s_mov_b32 m0, s64
	s_nop 0
	global_load_lds_dwordx4 v[228:229], off
	s_waitcnt vmcnt(8)
	s_waitcnt lgkmcnt(0)
	s_barrier
	s_setprio 1
	v_mfma_f32_16x16x32_bf16 v[124:127], v[146:149], v[188:191], v[124:127]
	v_mfma_f32_16x16x32_bf16 v[120:123], v[164:167], v[188:191], v[120:123]
	v_mfma_f32_16x16x32_bf16 v[108:111], v[146:149], v[196:199], v[108:111]
	v_mfma_f32_16x16x32_bf16 v[104:107], v[164:167], v[196:199], v[104:107]
	v_mfma_f32_16x16x32_bf16 v[92:95], v[146:149], v[204:207], v[92:95]
	v_mfma_f32_16x16x32_bf16 v[88:91], v[164:167], v[204:207], v[88:91]
	v_mfma_f32_16x16x32_bf16 v[76:79], v[146:149], v[212:215], v[76:79]
	v_mfma_f32_16x16x32_bf16 v[72:75], v[164:167], v[212:215], v[72:75]
	v_mfma_f32_16x16x32_bf16 v[124:127], v[160:163], v[192:195], v[124:127]
	v_mfma_f32_16x16x32_bf16 v[120:123], v[168:171], v[192:195], v[120:123]
	v_mfma_f32_16x16x32_bf16 v[108:111], v[160:163], v[200:203], v[108:111]
	v_mfma_f32_16x16x32_bf16 v[104:107], v[168:171], v[200:203], v[104:107]
	v_mfma_f32_16x16x32_bf16 v[92:95], v[160:163], v[208:211], v[92:95]
	v_mfma_f32_16x16x32_bf16 v[88:91], v[168:171], v[208:211], v[88:91]
	v_mfma_f32_16x16x32_bf16 v[76:79], v[160:163], v[216:219], v[76:79]
	v_mfma_f32_16x16x32_bf16 v[72:75], v[168:171], v[216:219], v[72:75]
	v_mfma_f32_16x16x32_bf16 v[116:119], v[172:175], v[188:191], v[116:119]
	v_mfma_f32_16x16x32_bf16 v[112:115], v[180:183], v[188:191], v[112:115]
	v_mfma_f32_16x16x32_bf16 v[100:103], v[172:175], v[196:199], v[100:103]
	v_mfma_f32_16x16x32_bf16 v[96:99], v[180:183], v[196:199], v[96:99]
	v_mfma_f32_16x16x32_bf16 v[84:87], v[172:175], v[204:207], v[84:87]
	v_mfma_f32_16x16x32_bf16 v[80:83], v[180:183], v[204:207], v[80:83]
	v_mfma_f32_16x16x32_bf16 v[68:71], v[172:175], v[212:215], v[68:71]
	v_mfma_f32_16x16x32_bf16 v[64:67], v[180:183], v[212:215], v[64:67]
	v_mfma_f32_16x16x32_bf16 v[116:119], v[176:179], v[192:195], v[116:119]
	v_mfma_f32_16x16x32_bf16 v[112:115], v[184:187], v[192:195], v[112:115]
	v_mfma_f32_16x16x32_bf16 v[100:103], v[176:179], v[200:203], v[100:103]
	v_mfma_f32_16x16x32_bf16 v[96:99], v[184:187], v[200:203], v[96:99]
	v_mfma_f32_16x16x32_bf16 v[84:87], v[176:179], v[208:211], v[84:87]
	v_mfma_f32_16x16x32_bf16 v[80:83], v[184:187], v[208:211], v[80:83]
	v_mfma_f32_16x16x32_bf16 v[68:71], v[176:179], v[216:219], v[68:71]
	v_mfma_f32_16x16x32_bf16 v[64:67], v[184:187], v[216:219], v[64:67]
	s_setprio 0
	s_barrier
	s_add_i32 s23, s23, s62
	v_lshl_add_u64 v[220:221], v[220:221], 0, s[14:15]
	s_mov_b32 m0, s23
	ds_read_b128 v[188:191], v157 offset:49152
	ds_read_b128 v[192:195], v157 offset:50176
	ds_read_b128 v[196:199], v157 offset:51200
	ds_read_b128 v[200:203], v157 offset:52224
	ds_read_b128 v[204:207], v157 offset:53248
	ds_read_b128 v[208:211], v157 offset:54272
	ds_read_b128 v[212:215], v157 offset:55296
	ds_read_b128 v[216:219], v157 offset:56320
	global_load_lds_dwordx4 v[220:221], off
	s_add_i32 m0, s23, 0x2000
	s_add_u32 s56, s56, 0x40080
	v_lshl_add_u64 v[220:221], v[222:223], 0, s[14:15]
	s_addc_u32 s57, s57, 0
	s_add_i32 s23, s33, s62
	global_load_lds_dwordx4 v[220:221], off
	s_mov_b32 m0, s23
	s_nop 0
	global_load_lds_dwordx4 v132, s[56:57]
	s_add_i32 m0, s23, 0x2000
	s_nop 0
	global_load_lds_dwordx4 v136, s[56:57]
	v_lshl_add_u64 v[220:221], v[224:225], 0, s[14:15]
	s_mov_b32 m0, s68
	s_nop 0
	global_load_lds_dwordx4 v[220:221], off
	v_lshl_add_u64 v[220:221], v[226:227], 0, s[14:15]
	s_mov_b32 m0, s69
	s_nop 0
	global_load_lds_dwordx4 v[220:221], off
	s_waitcnt vmcnt(8)
	s_waitcnt lgkmcnt(0)
	s_barrier
	s_setprio 1
	v_mfma_f32_16x16x32_bf16 v[60:63], v[146:149], v[188:191], v[60:63]
	v_mfma_f32_16x16x32_bf16 v[56:59], v[164:167], v[188:191], v[56:59]
	v_mfma_f32_16x16x32_bf16 v[44:47], v[146:149], v[196:199], v[44:47]
	v_mfma_f32_16x16x32_bf16 v[40:43], v[164:167], v[196:199], v[40:43]
	v_mfma_f32_16x16x32_bf16 v[28:31], v[146:149], v[204:207], v[28:31]
	v_mfma_f32_16x16x32_bf16 v[24:27], v[164:167], v[204:207], v[24:27]
	v_mfma_f32_16x16x32_bf16 v[12:15], v[146:149], v[212:215], v[12:15]
	v_mfma_f32_16x16x32_bf16 v[8:11], v[164:167], v[212:215], v[8:11]
	v_mfma_f32_16x16x32_bf16 v[60:63], v[160:163], v[192:195], v[60:63]
	v_mfma_f32_16x16x32_bf16 v[56:59], v[168:171], v[192:195], v[56:59]
	v_mfma_f32_16x16x32_bf16 v[44:47], v[160:163], v[200:203], v[44:47]
	v_mfma_f32_16x16x32_bf16 v[40:43], v[168:171], v[200:203], v[40:43]
	v_mfma_f32_16x16x32_bf16 v[28:31], v[160:163], v[208:211], v[28:31]
	v_mfma_f32_16x16x32_bf16 v[24:27], v[168:171], v[208:211], v[24:27]
	v_mfma_f32_16x16x32_bf16 v[12:15], v[160:163], v[216:219], v[12:15]
	v_mfma_f32_16x16x32_bf16 v[8:11], v[168:171], v[216:219], v[8:11]
	v_mfma_f32_16x16x32_bf16 v[52:55], v[172:175], v[188:191], v[52:55]
	v_mfma_f32_16x16x32_bf16 v[48:51], v[180:183], v[188:191], v[48:51]
	v_mfma_f32_16x16x32_bf16 v[36:39], v[172:175], v[196:199], v[36:39]
	v_mfma_f32_16x16x32_bf16 v[32:35], v[180:183], v[196:199], v[32:35]
	v_mfma_f32_16x16x32_bf16 v[20:23], v[172:175], v[204:207], v[20:23]
	v_mfma_f32_16x16x32_bf16 v[16:19], v[180:183], v[204:207], v[16:19]
	v_mfma_f32_16x16x32_bf16 v[4:7], v[172:175], v[212:215], v[4:7]
	v_mfma_f32_16x16x32_bf16 v[0:3], v[180:183], v[212:215], v[0:3]
	v_mfma_f32_16x16x32_bf16 v[52:55], v[176:179], v[192:195], v[52:55]
	v_mfma_f32_16x16x32_bf16 v[48:51], v[184:187], v[192:195], v[48:51]
	v_mfma_f32_16x16x32_bf16 v[36:39], v[176:179], v[200:203], v[36:39]
	v_mfma_f32_16x16x32_bf16 v[32:35], v[184:187], v[200:203], v[32:35]
	v_mfma_f32_16x16x32_bf16 v[20:23], v[176:179], v[208:211], v[20:23]
	v_mfma_f32_16x16x32_bf16 v[16:19], v[184:187], v[208:211], v[16:19]
	v_mfma_f32_16x16x32_bf16 v[4:7], v[176:179], v[216:219], v[4:7]
	v_mfma_f32_16x16x32_bf16 v[0:3], v[184:187], v[216:219], v[0:3]
	s_setprio 0
	s_barrier
	s_add_i32 s75, s75, 2
	s_add_u32 s54, s54, 0x100
	s_addc_u32 s55, s55, 0
	s_add_u32 s73, s73, 0x100
	s_addc_u32 s74, s74, 0
	s_cmp_gt_u32 s75, 13
	s_cbranch_scc0 .LBB0_990
	s_and_b64 vcc, exec, s[16:17]
	s_cbranch_vccz .LBB0_993
	s_barrier

.LBB0_1076:
	s_add_u32 s12, s28, 0x3000000
	s_addc_u32 s13, s29, 0
	s_add_u32 s14, s28, 0x2f10400
	s_addc_u32 s15, s29, 0
	s_lshl_b32 s1, s16, 5
	s_mov_b64 s[16:17], 0x80
	s_and_b32 s23, s1, 0x60
	s_add_i32 m0, s64, 0x18000
	v_lshl_add_u64 v[6:7], v[6:7], 0, s[16:17]
	s_ashr_i32 s69, s34, 31
	s_lshl_b32 s19, s18, 13
	s_lshl_b32 s33, s23, 7
	s_waitcnt vmcnt(2)
	s_barrier
	global_load_lds_dwordx4 v[6:7], off
	v_lshl_add_u64 v[4:5], v[4:5], 0, s[16:17]
	s_add_i32 m0, s64, 0x1a000
	s_add_i32 s70, s64, 0x8000
	s_add_i32 s71, s64, 0xa000
	global_load_lds_dwordx4 v[4:5], off
	v_lshl_add_u64 v[0:1], v[0:1], 0, s[16:17]
	s_mov_b32 m0, s70
	s_add_u32 s20, s56, 0x40080
	global_load_lds_dwordx4 v[0:1], off
	v_lshl_add_u64 v[0:1], v[2:3], 0, s[16:17]
	s_mov_b32 m0, s71
	s_addc_u32 s21, s57, 0
	global_load_lds_dwordx4 v[0:1], off
	s_add_i32 m0, s64, 0x1c000
	s_nop 0
	global_load_lds_dwordx4 v132, s[20:21]
	v_lshl_add_u64 v[0:1], s[20:21], 0, v[136:137]
	s_add_i32 m0, s64, 0x1e000
	s_sext_i32_i8 s1, s2
	global_load_lds_dwordx4 v[0:1], off
	v_and_b32_e32 v0, 15, v128
	v_lshlrev_b32_e32 v1, 1, v11
	v_lshlrev_b32_e32 v2, 6, v128
	s_movk_i32 s2, 0x3c0
	v_lshlrev_b32_e32 v3, 2, v128
	v_and_or_b32 v2, v2, s2, v1
	v_and_b32_e32 v3, 32, v3
	v_lshl_or_b32 v152, s18, 6, v0
	v_lshl_or_b32 v0, v0, 6, v1
	v_lshlrev_b32_e32 v1, 8, v128
	v_bitop3_b32 v153, s33, v2, v3 bitop3:0xf6
	v_and_b32_e32 v1, 0x38000, v1
	v_lshlrev_b32_e32 v2, 11, v10
	v_or3_b32 v1, v8, v1, v2
	v_add_u32_e32 v138, v1, v9
	v_lshlrev_b32_e32 v1, 4, v12
	s_waitcnt vmcnt(6)
	s_cmpk_lt_u32 s3, 0x100
	v_and_b32_e32 v1, 0x78000, v1
	v_bitop3_b32 v0, v0, s19, v3 bitop3:0xde
	s_cselect_b64 s[18:19], -1, 0
	v_or3_b32 v1, v8, v1, v2
	s_add_i32 s73, 0, 0x10000
	s_add_i32 s74, 0, 0x14000
	s_mov_b32 s72, s34
	v_or_b32_e32 v154, s23, v11
	v_mov_b32_e32 v139, v133
	v_add_u32_e32 v140, v1, v9
	v_mov_b32_e32 v141, v133
	v_mov_b64_e32 v[142:143], 0x100
	v_mov_b64_e32 v[144:145], 0xff
	v_add_u32_e32 v155, s73, v153
	v_add_u32_e32 v156, s74, v153
	v_add_u32_e32 v157, 0, v0
	v_mov_b32_e32 v158, 0x358637bd
	s_mov_b32 s75, 0x800000
	s_mov_b32 s76, 0x40000
	s_mov_b64 s[36:37], 0x48000
	s_mov_b32 s77, 0x48000
	s_mov_b64 s[38:39], 0x50000
	s_mov_b32 s78, 0x50000
	s_mov_b64 s[44:45], 0x58000
	s_mov_b32 s79, 0x58000
	s_barrier
	s_branch .LBB0_1079

.LBB0_1086:
	ds_read_b128 v[146:149], v155
	ds_read_b128 v[160:163], v155 offset:1024
	ds_read_b128 v[164:167], v155 offset:2048
	ds_read_b128 v[168:171], v155 offset:3072
	ds_read_b128 v[172:175], v156
	ds_read_b128 v[176:179], v156 offset:1024
	ds_read_b128 v[180:183], v156 offset:2048
	ds_read_b128 v[184:187], v156 offset:3072
	s_add_u32 s23, s54, 0xfffc0080
	s_addc_u32 s33, s55, -1
	s_cmp_eq_u32 s82, 12
	s_cselect_b32 s59, s20, s33
	s_cselect_b32 s58, s21, s23
	s_cselect_b32 s57, s47, s81
	s_cselect_b32 s56, s49, s80
	s_add_i32 m0, s64, 0xc000
	ds_read_b128 v[188:191], v157
	ds_read_b128 v[192:195], v157 offset:1024
	ds_read_b128 v[196:199], v157 offset:2048
	ds_read_b128 v[200:203], v157 offset:3072
	ds_read_b128 v[204:207], v157 offset:4096
	ds_read_b128 v[208:211], v157 offset:5120
	ds_read_b128 v[212:215], v157 offset:6144
	ds_read_b128 v[216:219], v157 offset:7168
	global_load_lds_dwordx4 v138, s[54:55]
	s_add_i32 m0, s64, 0xe000
	s_nop 0
	global_load_lds_dwordx4 v140, s[54:55]
	s_waitcnt vmcnt(8)
	s_waitcnt lgkmcnt(0)
	s_barrier
	s_setprio 1
	v_mfma_f32_16x16x32_bf16 v[124:127], v[146:149], v[188:191], v[124:127]
	v_mfma_f32_16x16x32_bf16 v[120:123], v[164:167], v[188:191], v[120:123]
	v_mfma_f32_16x16x32_bf16 v[108:111], v[146:149], v[196:199], v[108:111]
	v_mfma_f32_16x16x32_bf16 v[104:107], v[164:167], v[196:199], v[104:107]
	v_mfma_f32_16x16x32_bf16 v[92:95], v[146:149], v[204:207], v[92:95]
	v_mfma_f32_16x16x32_bf16 v[88:91], v[164:167], v[204:207], v[88:91]
	v_mfma_f32_16x16x32_bf16 v[76:79], v[146:149], v[212:215], v[76:79]
	v_mfma_f32_16x16x32_bf16 v[72:75], v[164:167], v[212:215], v[72:75]
	v_mfma_f32_16x16x32_bf16 v[124:127], v[160:163], v[192:195], v[124:127]
	v_mfma_f32_16x16x32_bf16 v[120:123], v[168:171], v[192:195], v[120:123]
	v_mfma_f32_16x16x32_bf16 v[108:111], v[160:163], v[200:203], v[108:111]
	v_mfma_f32_16x16x32_bf16 v[104:107], v[168:171], v[200:203], v[104:107]
	v_mfma_f32_16x16x32_bf16 v[92:95], v[160:163], v[208:211], v[92:95]
	v_mfma_f32_16x16x32_bf16 v[88:91], v[168:171], v[208:211], v[88:91]
	v_mfma_f32_16x16x32_bf16 v[76:79], v[160:163], v[216:219], v[76:79]
	v_mfma_f32_16x16x32_bf16 v[72:75], v[168:171], v[216:219], v[72:75]
	v_mfma_f32_16x16x32_bf16 v[116:119], v[172:175], v[188:191], v[116:119]
	v_mfma_f32_16x16x32_bf16 v[112:115], v[180:183], v[188:191], v[112:115]
	v_mfma_f32_16x16x32_bf16 v[100:103], v[172:175], v[196:199], v[100:103]
	v_mfma_f32_16x16x32_bf16 v[96:99], v[180:183], v[196:199], v[96:99]
	v_mfma_f32_16x16x32_bf16 v[84:87], v[172:175], v[204:207], v[84:87]
	v_mfma_f32_16x16x32_bf16 v[80:83], v[180:183], v[204:207], v[80:83]
	v_mfma_f32_16x16x32_bf16 v[68:71], v[172:175], v[212:215], v[68:71]
	v_mfma_f32_16x16x32_bf16 v[64:67], v[180:183], v[212:215], v[64:67]
	v_mfma_f32_16x16x32_bf16 v[116:119], v[176:179], v[192:195], v[116:119]
	v_mfma_f32_16x16x32_bf16 v[112:115], v[184:187], v[192:195], v[112:115]
	v_mfma_f32_16x16x32_bf16 v[100:103], v[176:179], v[200:203], v[100:103]
	v_mfma_f32_16x16x32_bf16 v[96:99], v[184:187], v[200:203], v[96:99]
	v_mfma_f32_16x16x32_bf16 v[84:87], v[176:179], v[208:211], v[84:87]
	v_mfma_f32_16x16x32_bf16 v[80:83], v[184:187], v[208:211], v[80:83]
	v_mfma_f32_16x16x32_bf16 v[68:71], v[176:179], v[216:219], v[68:71]
	v_mfma_f32_16x16x32_bf16 v[64:67], v[184:187], v[216:219], v[64:67]
	s_setprio 0
	s_barrier
	s_add_i32 s23, s73, s62
	v_lshl_add_u64 v[150:151], s[56:57], 0, v[132:133]
	s_mov_b32 m0, s23
	ds_read_b128 v[188:191], v157 offset:16384
	ds_read_b128 v[192:195], v157 offset:17408
	ds_read_b128 v[196:199], v157 offset:18432
	ds_read_b128 v[200:203], v157 offset:19456
	ds_read_b128 v[204:207], v157 offset:20480
	ds_read_b128 v[208:211], v157 offset:21504
	ds_read_b128 v[212:215], v157 offset:22528
	ds_read_b128 v[216:219], v157 offset:23552
	global_load_lds_dwordx4 v[150:151], off
	s_add_i32 m0, s23, 0x2000
	s_add_u32 s84, s56, 0x40000
	v_lshl_add_u64 v[220:221], s[56:57], 0, v[136:137]
	s_addc_u32 s85, s57, 0
	s_add_i32 s23, s74, s62
	global_load_lds_dwordx4 v[220:221], off
	s_mov_b32 m0, s23
	v_lshl_add_u64 v[224:225], s[58:59], 0, v[134:135]
	global_load_lds_dwordx4 v132, s[84:85]
	s_add_i32 m0, s23, 0x2000
	s_nop 0
	global_load_lds_dwordx4 v136, s[84:85]
	v_lshl_add_u64 v[222:223], s[58:59], 0, v[130:131]
	s_mov_b32 m0, s64
	s_nop 0
	global_load_lds_dwordx4 v[222:223], off
	s_mov_b32 m0, s65
	s_nop 0
	global_load_lds_dwordx4 v[224:225], off
	s_waitcnt vmcnt(8)
	s_waitcnt lgkmcnt(0)
	s_barrier
	s_setprio 1
	v_mfma_f32_16x16x32_bf16 v[60:63], v[146:149], v[188:191], v[60:63]
	v_mfma_f32_16x16x32_bf16 v[56:59], v[164:167], v[188:191], v[56:59]
	v_mfma_f32_16x16x32_bf16 v[44:47], v[146:149], v[196:199], v[44:47]
	v_mfma_f32_16x16x32_bf16 v[40:43], v[164:167], v[196:199], v[40:43]
	v_mfma_f32_16x16x32_bf16 v[28:31], v[146:149], v[204:207], v[28:31]
	v_mfma_f32_16x16x32_bf16 v[24:27], v[164:167], v[204:207], v[24:27]
	v_mfma_f32_16x16x32_bf16 v[12:15], v[146:149], v[212:215], v[12:15]
	v_mfma_f32_16x16x32_bf16 v[8:11], v[164:167], v[212:215], v[8:11]
	v_mfma_f32_16x16x32_bf16 v[60:63], v[160:163], v[192:195], v[60:63]
	v_mfma_f32_16x16x32_bf16 v[56:59], v[168:171], v[192:195], v[56:59]
	v_mfma_f32_16x16x32_bf16 v[44:47], v[160:163], v[200:203], v[44:47]
	v_mfma_f32_16x16x32_bf16 v[40:43], v[168:171], v[200:203], v[40:43]
	v_mfma_f32_16x16x32_bf16 v[28:31], v[160:163], v[208:211], v[28:31]
	v_mfma_f32_16x16x32_bf16 v[24:27], v[168:171], v[208:211], v[24:27]
	v_mfma_f32_16x16x32_bf16 v[12:15], v[160:163], v[216:219], v[12:15]
	v_mfma_f32_16x16x32_bf16 v[8:11], v[168:171], v[216:219], v[8:11]
	v_mfma_f32_16x16x32_bf16 v[52:55], v[172:175], v[188:191], v[52:55]
	v_mfma_f32_16x16x32_bf16 v[48:51], v[180:183], v[188:191], v[48:51]
	v_mfma_f32_16x16x32_bf16 v[36:39], v[172:175], v[196:199], v[36:39]
	v_mfma_f32_16x16x32_bf16 v[32:35], v[180:183], v[196:199], v[32:35]
	v_mfma_f32_16x16x32_bf16 v[20:23], v[172:175], v[204:207], v[20:23]
	v_mfma_f32_16x16x32_bf16 v[16:19], v[180:183], v[204:207], v[16:19]
	v_mfma_f32_16x16x32_bf16 v[4:7], v[172:175], v[212:215], v[4:7]
	v_mfma_f32_16x16x32_bf16 v[0:3], v[180:183], v[212:215], v[0:3]
	v_mfma_f32_16x16x32_bf16 v[52:55], v[176:179], v[192:195], v[52:55]
	v_mfma_f32_16x16x32_bf16 v[48:51], v[184:187], v[192:195], v[48:51]
	v_mfma_f32_16x16x32_bf16 v[36:39], v[176:179], v[200:203], v[36:39]
	v_mfma_f32_16x16x32_bf16 v[32:35], v[184:187], v[200:203], v[32:35]
	v_mfma_f32_16x16x32_bf16 v[20:23], v[176:179], v[208:211], v[20:23]
	v_mfma_f32_16x16x32_bf16 v[16:19], v[184:187], v[208:211], v[16:19]
	v_mfma_f32_16x16x32_bf16 v[4:7], v[176:179], v[216:219], v[4:7]
	v_mfma_f32_16x16x32_bf16 v[0:3], v[184:187], v[216:219], v[0:3]
	s_setprio 0
	s_barrier
	s_add_i32 s23, 0, 0x18000
	v_add_u32_e32 v159, s23, v153
	s_add_i32 s33, 0, 0x1c000
	ds_read_b128 v[146:149], v159
	ds_read_b128 v[160:163], v159 offset:1024
	ds_read_b128 v[164:167], v159 offset:2048
	ds_read_b128 v[168:171], v159 offset:3072
	v_add_u32_e32 v159, s33, v153
	ds_read_b128 v[172:175], v159
	ds_read_b128 v[176:179], v159 offset:1024
	ds_read_b128 v[180:183], v159 offset:2048
	ds_read_b128 v[184:187], v159 offset:3072
	s_add_u32 s58, s58, 0x40000
	s_addc_u32 s59, s59, 0
	s_mov_b32 m0, s66
	ds_read_b128 v[188:191], v157 offset:32768
	ds_read_b128 v[192:195], v157 offset:33792
	ds_read_b128 v[196:199], v157 offset:34816
	ds_read_b128 v[200:203], v157 offset:35840
	ds_read_b128 v[204:207], v157 offset:36864
	ds_read_b128 v[208:211], v157 offset:37888
	ds_read_b128 v[212:215], v157 offset:38912
	ds_read_b128 v[216:219], v157 offset:39936
	global_load_lds_dwordx4 v130, s[58:59]
	v_lshl_add_u64 v[226:227], s[58:59], 0, v[134:135]
	s_mov_b32 m0, s67
	s_nop 0
	global_load_lds_dwordx4 v[226:227], off
	s_waitcnt vmcnt(8)
	s_waitcnt lgkmcnt(0)
	s_barrier
	s_setprio 1
	v_mfma_f32_16x16x32_bf16 v[124:127], v[146:149], v[188:191], v[124:127]
	v_mfma_f32_16x16x32_bf16 v[120:123], v[164:167], v[188:191], v[120:123]
	v_mfma_f32_16x16x32_bf16 v[108:111], v[146:149], v[196:199], v[108:111]
	v_mfma_f32_16x16x32_bf16 v[104:107], v[164:167], v[196:199], v[104:107]
	v_mfma_f32_16x16x32_bf16 v[92:95], v[146:149], v[204:207], v[92:95]
	v_mfma_f32_16x16x32_bf16 v[88:91], v[164:167], v[204:207], v[88:91]
	v_mfma_f32_16x16x32_bf16 v[76:79], v[146:149], v[212:215], v[76:79]
	v_mfma_f32_16x16x32_bf16 v[72:75], v[164:167], v[212:215], v[72:75]
	v_mfma_f32_16x16x32_bf16 v[124:127], v[160:163], v[192:195], v[124:127]
	v_mfma_f32_16x16x32_bf16 v[120:123], v[168:171], v[192:195], v[120:123]
	v_mfma_f32_16x16x32_bf16 v[108:111], v[160:163], v[200:203], v[108:111]
	v_mfma_f32_16x16x32_bf16 v[104:107], v[168:171], v[200:203], v[104:107]
	v_mfma_f32_16x16x32_bf16 v[92:95], v[160:163], v[208:211], v[92:95]
	v_mfma_f32_16x16x32_bf16 v[88:91], v[168:171], v[208:211], v[88:91]
	v_mfma_f32_16x16x32_bf16 v[76:79], v[160:163], v[216:219], v[76:79]
	v_mfma_f32_16x16x32_bf16 v[72:75], v[168:171], v[216:219], v[72:75]
	v_mfma_f32_16x16x32_bf16 v[116:119], v[172:175], v[188:191], v[116:119]
	v_mfma_f32_16x16x32_bf16 v[112:115], v[180:183], v[188:191], v[112:115]
	v_mfma_f32_16x16x32_bf16 v[100:103], v[172:175], v[196:199], v[100:103]
	v_mfma_f32_16x16x32_bf16 v[96:99], v[180:183], v[196:199], v[96:99]
	v_mfma_f32_16x16x32_bf16 v[84:87], v[172:175], v[204:207], v[84:87]
	v_mfma_f32_16x16x32_bf16 v[80:83], v[180:183], v[204:207], v[80:83]
	v_mfma_f32_16x16x32_bf16 v[68:71], v[172:175], v[212:215], v[68:71]
	v_mfma_f32_16x16x32_bf16 v[64:67], v[180:183], v[212:215], v[64:67]
	v_mfma_f32_16x16x32_bf16 v[116:119], v[176:179], v[192:195], v[116:119]
	v_mfma_f32_16x16x32_bf16 v[112:115], v[184:187], v[192:195], v[112:115]
	v_mfma_f32_16x16x32_bf16 v[100:103], v[176:179], v[200:203], v[100:103]
	v_mfma_f32_16x16x32_bf16 v[96:99], v[184:187], v[200:203], v[96:99]
	v_mfma_f32_16x16x32_bf16 v[84:87], v[176:179], v[208:211], v[84:87]
	v_mfma_f32_16x16x32_bf16 v[80:83], v[184:187], v[208:211], v[80:83]
	v_mfma_f32_16x16x32_bf16 v[68:71], v[176:179], v[216:219], v[68:71]
	v_mfma_f32_16x16x32_bf16 v[64:67], v[184:187], v[216:219], v[64:67]
	s_setprio 0
	s_barrier
	s_add_i32 s23, s23, s62
	v_lshl_add_u64 v[150:151], v[150:151], 0, s[16:17]
	s_mov_b32 m0, s23
	ds_read_b128 v[188:191], v157 offset:49152
	ds_read_b128 v[192:195], v157 offset:50176
	ds_read_b128 v[196:199], v157 offset:51200
	ds_read_b128 v[200:203], v157 offset:52224
	ds_read_b128 v[204:207], v157 offset:53248
	ds_read_b128 v[208:211], v157 offset:54272
	ds_read_b128 v[212:215], v157 offset:55296
	ds_read_b128 v[216:219], v157 offset:56320
	global_load_lds_dwordx4 v[150:151], off
	s_add_i32 m0, s23, 0x2000
	s_add_u32 s56, s56, 0x40080
	v_lshl_add_u64 v[150:151], v[220:221], 0, s[16:17]
	s_addc_u32 s57, s57, 0
	s_add_i32 s23, s33, s62
	global_load_lds_dwordx4 v[150:151], off
	s_mov_b32 m0, s23
	s_nop 0
	global_load_lds_dwordx4 v132, s[56:57]
	s_add_i32 m0, s23, 0x2000
	s_nop 0
	global_load_lds_dwordx4 v136, s[56:57]
	v_lshl_add_u64 v[150:151], v[222:223], 0, s[16:17]
	s_mov_b32 m0, s70
	s_nop 0
	global_load_lds_dwordx4 v[150:151], off
	v_lshl_add_u64 v[150:151], v[224:225], 0, s[16:17]
	s_mov_b32 m0, s71
	s_nop 0
	global_load_lds_dwordx4 v[150:151], off
	s_waitcnt vmcnt(8)
	s_waitcnt lgkmcnt(0)
	s_barrier
	s_setprio 1
	v_mfma_f32_16x16x32_bf16 v[60:63], v[146:149], v[188:191], v[60:63]
	v_mfma_f32_16x16x32_bf16 v[56:59], v[164:167], v[188:191], v[56:59]
	v_mfma_f32_16x16x32_bf16 v[44:47], v[146:149], v[196:199], v[44:47]
	v_mfma_f32_16x16x32_bf16 v[40:43], v[164:167], v[196:199], v[40:43]
	v_mfma_f32_16x16x32_bf16 v[28:31], v[146:149], v[204:207], v[28:31]
	v_mfma_f32_16x16x32_bf16 v[24:27], v[164:167], v[204:207], v[24:27]
	v_mfma_f32_16x16x32_bf16 v[12:15], v[146:149], v[212:215], v[12:15]
	v_mfma_f32_16x16x32_bf16 v[8:11], v[164:167], v[212:215], v[8:11]
	v_mfma_f32_16x16x32_bf16 v[60:63], v[160:163], v[192:195], v[60:63]
	v_mfma_f32_16x16x32_bf16 v[56:59], v[168:171], v[192:195], v[56:59]
	v_mfma_f32_16x16x32_bf16 v[44:47], v[160:163], v[200:203], v[44:47]
	v_mfma_f32_16x16x32_bf16 v[40:43], v[168:171], v[200:203], v[40:43]
	v_mfma_f32_16x16x32_bf16 v[28:31], v[160:163], v[208:211], v[28:31]
	v_mfma_f32_16x16x32_bf16 v[24:27], v[168:171], v[208:211], v[24:27]
	v_mfma_f32_16x16x32_bf16 v[12:15], v[160:163], v[216:219], v[12:15]
	v_mfma_f32_16x16x32_bf16 v[8:11], v[168:171], v[216:219], v[8:11]
	v_mfma_f32_16x16x32_bf16 v[52:55], v[172:175], v[188:191], v[52:55]
	v_mfma_f32_16x16x32_bf16 v[48:51], v[180:183], v[188:191], v[48:51]
	v_mfma_f32_16x16x32_bf16 v[36:39], v[172:175], v[196:199], v[36:39]
	v_mfma_f32_16x16x32_bf16 v[32:35], v[180:183], v[196:199], v[32:35]
	v_mfma_f32_16x16x32_bf16 v[20:23], v[172:175], v[204:207], v[20:23]
	v_mfma_f32_16x16x32_bf16 v[16:19], v[180:183], v[204:207], v[16:19]
	v_mfma_f32_16x16x32_bf16 v[4:7], v[172:175], v[212:215], v[4:7]
	v_mfma_f32_16x16x32_bf16 v[0:3], v[180:183], v[212:215], v[0:3]
	v_mfma_f32_16x16x32_bf16 v[52:55], v[176:179], v[192:195], v[52:55]
	v_mfma_f32_16x16x32_bf16 v[48:51], v[184:187], v[192:195], v[48:51]
	v_mfma_f32_16x16x32_bf16 v[36:39], v[176:179], v[200:203], v[36:39]
	v_mfma_f32_16x16x32_bf16 v[32:35], v[184:187], v[200:203], v[32:35]
	v_mfma_f32_16x16x32_bf16 v[20:23], v[176:179], v[208:211], v[20:23]
	v_mfma_f32_16x16x32_bf16 v[16:19], v[184:187], v[208:211], v[16:19]
	v_mfma_f32_16x16x32_bf16 v[4:7], v[176:179], v[216:219], v[4:7]
	v_mfma_f32_16x16x32_bf16 v[0:3], v[184:187], v[216:219], v[0:3]
	s_setprio 0
	s_barrier
	s_add_i32 s82, s82, 2
	s_add_u32 s54, s54, 0x100
	s_addc_u32 s55, s55, 0
	s_add_u32 s80, s80, 0x100
	s_addc_u32 s81, s81, 0
	s_cmp_gt_u32 s82, 13
	s_cbranch_scc0 .LBB0_1086
	s_and_b64 vcc, exec, s[18:19]
	s_cbranch_vccz .LBB0_1089
	s_barrier

.LBB0_1236:
	s_add_u32 s10, s28, 0x7200000
	s_addc_u32 s11, s29, 0
	s_add_u32 s12, s28, 0x2f20800
	s_addc_u32 s13, s29, 0
	s_lshl_b32 s2, s2, 5
	s_mov_b64 s[14:15], 0x80
	s_and_b32 s18, s2, 0x60
	s_add_i32 m0, s43, 0x18000
	v_lshl_add_u64 v[6:7], v[6:7], 0, s[14:15]
	s_ashr_i32 s58, s34, 31
	s_ashr_i32 s59, s22, 31
	s_lshl_b32 s16, s5, 13
	s_lshl_b32 s17, s18, 7
	s_waitcnt vmcnt(2)
	s_barrier
	global_load_lds_dwordx4 v[6:7], off
	v_lshl_add_u64 v[4:5], v[4:5], 0, s[14:15]
	s_add_i32 m0, s43, 0x1a000
	s_add_i32 s60, s43, 0x8000
	s_add_i32 s61, s43, 0xa000
	global_load_lds_dwordx4 v[4:5], off
	v_lshl_add_u64 v[0:1], v[0:1], 0, s[14:15]
	s_mov_b32 m0, s60
	s_add_u32 s2, s48, 0x40080
	global_load_lds_dwordx4 v[0:1], off
	v_lshl_add_u64 v[0:1], v[2:3], 0, s[14:15]
	s_mov_b32 m0, s61
	s_addc_u32 s3, s49, 0
	global_load_lds_dwordx4 v[0:1], off
	s_add_i32 m0, s43, 0x1c000
	s_nop 0
	global_load_lds_dwordx4 v132, s[2:3]
	v_lshl_add_u64 v[0:1], s[2:3], 0, v[136:137]
	s_add_i32 m0, s43, 0x1e000
	v_lshlrev_b32_e32 v2, 6, v128
	global_load_lds_dwordx4 v[0:1], off
	v_and_b32_e32 v0, 3, v150
	v_lshlrev_b32_e32 v1, 4, v0
	s_movk_i32 s2, 0x3c0
	v_lshlrev_b32_e32 v3, 2, v128
	v_and_or_b32 v2, v2, s2, v1
	v_and_b32_e32 v3, 32, v3
	v_cmp_eq_u32_e64 s[2:3], 0, v0
	v_lshl_or_b32 v154, v0, 3, s18
	v_lshlrev_b32_e32 v0, 8, v128
	v_bitop3_b32 v153, s17, v2, v3 bitop3:0xf6
	v_and_b32_e32 v0, 0x38000, v0
	v_lshlrev_b32_e32 v2, 11, v10
	v_or3_b32 v0, v8, v0, v2
	v_add_u32_e32 v138, v0, v9
	v_lshlrev_b32_e32 v0, 4, v11
	v_lshlrev_b32_e32 v4, 2, v151
	v_and_b32_e32 v0, 0x78000, v0
	v_lshl_or_b32 v1, v151, 6, v1
	v_and_b32_e32 v4, 32, v4
	s_waitcnt vmcnt(6)
	s_cmpk_lt_u32 s4, 0x100
	v_or3_b32 v0, v8, v0, v2
	v_bitop3_b32 v1, v1, s16, v4 bitop3:0xde
	s_cselect_b64 s[16:17], -1, 0
	v_add_u32_e32 v140, v0, v9
	s_add_i32 s63, 0, 0x10000
	s_add_i32 s64, 0, 0x14000
	v_mbcnt_lo_u32_b32 v0, -1, 0
	s_mov_b32 s62, s34
	v_lshl_or_b32 v152, s5, 6, v151
	v_mov_b32_e32 v139, v133
	v_mov_b32_e32 v141, v133
	v_mov_b64_e32 v[142:143], 0x100
	v_mov_b64_e32 v[144:145], 0xff
	v_add_u32_e32 v155, s63, v153
	v_add_u32_e32 v156, s64, v153
	v_add_u32_e32 v157, 0, v1
	v_mbcnt_hi_u32_b32 v158, -1, v0
	s_barrier
	s_branch .LBB0_1239

.LBB0_1246:
	ds_read_b128 v[146:149], v155
	ds_read_b128 v[160:163], v155 offset:1024
	ds_read_b128 v[164:167], v155 offset:2048
	ds_read_b128 v[168:171], v155 offset:3072
	ds_read_b128 v[172:175], v156
	ds_read_b128 v[176:179], v156 offset:1024
	ds_read_b128 v[180:183], v156 offset:2048
	ds_read_b128 v[184:187], v156 offset:3072
	s_add_u32 s23, s46, 0xfffc0080
	s_addc_u32 s33, s47, -1
	s_cmp_eq_u32 s67, 12
	s_cselect_b32 s51, s20, s33
	s_cselect_b32 s50, s21, s23
	s_cselect_b32 s49, s19, s66
	s_cselect_b32 s48, s37, s65
	s_add_i32 m0, s43, 0xc000
	ds_read_b128 v[188:191], v157
	ds_read_b128 v[192:195], v157 offset:1024
	ds_read_b128 v[196:199], v157 offset:2048
	ds_read_b128 v[200:203], v157 offset:3072
	ds_read_b128 v[204:207], v157 offset:4096
	ds_read_b128 v[208:211], v157 offset:5120
	ds_read_b128 v[212:215], v157 offset:6144
	ds_read_b128 v[216:219], v157 offset:7168
	global_load_lds_dwordx4 v138, s[46:47]
	s_add_i32 m0, s43, 0xe000
	s_nop 0
	global_load_lds_dwordx4 v140, s[46:47]
	s_waitcnt vmcnt(8)
	s_waitcnt lgkmcnt(0)
	s_barrier
	s_setprio 1
	v_mfma_f32_16x16x32_bf16 v[124:127], v[146:149], v[188:191], v[124:127]
	v_mfma_f32_16x16x32_bf16 v[120:123], v[164:167], v[188:191], v[120:123]
	v_mfma_f32_16x16x32_bf16 v[108:111], v[146:149], v[196:199], v[108:111]
	v_mfma_f32_16x16x32_bf16 v[104:107], v[164:167], v[196:199], v[104:107]
	v_mfma_f32_16x16x32_bf16 v[92:95], v[146:149], v[204:207], v[92:95]
	v_mfma_f32_16x16x32_bf16 v[88:91], v[164:167], v[204:207], v[88:91]
	v_mfma_f32_16x16x32_bf16 v[76:79], v[146:149], v[212:215], v[76:79]
	v_mfma_f32_16x16x32_bf16 v[72:75], v[164:167], v[212:215], v[72:75]
	v_mfma_f32_16x16x32_bf16 v[124:127], v[160:163], v[192:195], v[124:127]
	v_mfma_f32_16x16x32_bf16 v[120:123], v[168:171], v[192:195], v[120:123]
	v_mfma_f32_16x16x32_bf16 v[108:111], v[160:163], v[200:203], v[108:111]
	v_mfma_f32_16x16x32_bf16 v[104:107], v[168:171], v[200:203], v[104:107]
	v_mfma_f32_16x16x32_bf16 v[92:95], v[160:163], v[208:211], v[92:95]
	v_mfma_f32_16x16x32_bf16 v[88:91], v[168:171], v[208:211], v[88:91]
	v_mfma_f32_16x16x32_bf16 v[76:79], v[160:163], v[216:219], v[76:79]
	v_mfma_f32_16x16x32_bf16 v[72:75], v[168:171], v[216:219], v[72:75]
	v_mfma_f32_16x16x32_bf16 v[116:119], v[172:175], v[188:191], v[116:119]
	v_mfma_f32_16x16x32_bf16 v[112:115], v[180:183], v[188:191], v[112:115]
	v_mfma_f32_16x16x32_bf16 v[100:103], v[172:175], v[196:199], v[100:103]
	v_mfma_f32_16x16x32_bf16 v[96:99], v[180:183], v[196:199], v[96:99]
	v_mfma_f32_16x16x32_bf16 v[84:87], v[172:175], v[204:207], v[84:87]
	v_mfma_f32_16x16x32_bf16 v[80:83], v[180:183], v[204:207], v[80:83]
	v_mfma_f32_16x16x32_bf16 v[68:71], v[172:175], v[212:215], v[68:71]
	v_mfma_f32_16x16x32_bf16 v[64:67], v[180:183], v[212:215], v[64:67]
	v_mfma_f32_16x16x32_bf16 v[116:119], v[176:179], v[192:195], v[116:119]
	v_mfma_f32_16x16x32_bf16 v[112:115], v[184:187], v[192:195], v[112:115]
	v_mfma_f32_16x16x32_bf16 v[100:103], v[176:179], v[200:203], v[100:103]
	v_mfma_f32_16x16x32_bf16 v[96:99], v[184:187], v[200:203], v[96:99]
	v_mfma_f32_16x16x32_bf16 v[84:87], v[176:179], v[208:211], v[84:87]
	v_mfma_f32_16x16x32_bf16 v[80:83], v[184:187], v[208:211], v[80:83]
	v_mfma_f32_16x16x32_bf16 v[68:71], v[176:179], v[216:219], v[68:71]
	v_mfma_f32_16x16x32_bf16 v[64:67], v[184:187], v[216:219], v[64:67]
	s_setprio 0
	s_barrier
	s_add_i32 s23, s63, s54
	v_lshl_add_u64 v[220:221], s[48:49], 0, v[132:133]
	s_mov_b32 m0, s23
	ds_read_b128 v[188:191], v157 offset:16384
	ds_read_b128 v[192:195], v157 offset:17408
	ds_read_b128 v[196:199], v157 offset:18432
	ds_read_b128 v[200:203], v157 offset:19456
	ds_read_b128 v[204:207], v157 offset:20480
	ds_read_b128 v[208:211], v157 offset:21504
	ds_read_b128 v[212:215], v157 offset:22528
	ds_read_b128 v[216:219], v157 offset:23552
	global_load_lds_dwordx4 v[220:221], off
	s_add_i32 m0, s23, 0x2000
	s_add_u32 s68, s48, 0x40000
	v_lshl_add_u64 v[222:223], s[48:49], 0, v[136:137]
	s_addc_u32 s69, s49, 0
	s_add_i32 s23, s64, s54
	global_load_lds_dwordx4 v[222:223], off
	s_mov_b32 m0, s23
	v_lshl_add_u64 v[226:227], s[50:51], 0, v[134:135]
	global_load_lds_dwordx4 v132, s[68:69]
	s_add_i32 m0, s23, 0x2000
	s_nop 0
	global_load_lds_dwordx4 v136, s[68:69]
	v_lshl_add_u64 v[224:225], s[50:51], 0, v[130:131]
	s_mov_b32 m0, s43
	s_nop 0
	global_load_lds_dwordx4 v[224:225], off
	s_mov_b32 m0, s45
	s_nop 0
	global_load_lds_dwordx4 v[226:227], off
	s_waitcnt vmcnt(8)
	s_waitcnt lgkmcnt(0)
	s_barrier
	s_setprio 1
	v_mfma_f32_16x16x32_bf16 v[60:63], v[146:149], v[188:191], v[60:63]
	v_mfma_f32_16x16x32_bf16 v[56:59], v[164:167], v[188:191], v[56:59]
	v_mfma_f32_16x16x32_bf16 v[44:47], v[146:149], v[196:199], v[44:47]
	v_mfma_f32_16x16x32_bf16 v[40:43], v[164:167], v[196:199], v[40:43]
	v_mfma_f32_16x16x32_bf16 v[28:31], v[146:149], v[204:207], v[28:31]
	v_mfma_f32_16x16x32_bf16 v[24:27], v[164:167], v[204:207], v[24:27]
	v_mfma_f32_16x16x32_bf16 v[12:15], v[146:149], v[212:215], v[12:15]
	v_mfma_f32_16x16x32_bf16 v[8:11], v[164:167], v[212:215], v[8:11]
	v_mfma_f32_16x16x32_bf16 v[60:63], v[160:163], v[192:195], v[60:63]
	v_mfma_f32_16x16x32_bf16 v[56:59], v[168:171], v[192:195], v[56:59]
	v_mfma_f32_16x16x32_bf16 v[44:47], v[160:163], v[200:203], v[44:47]
	v_mfma_f32_16x16x32_bf16 v[40:43], v[168:171], v[200:203], v[40:43]
	v_mfma_f32_16x16x32_bf16 v[28:31], v[160:163], v[208:211], v[28:31]
	v_mfma_f32_16x16x32_bf16 v[24:27], v[168:171], v[208:211], v[24:27]
	v_mfma_f32_16x16x32_bf16 v[12:15], v[160:163], v[216:219], v[12:15]
	v_mfma_f32_16x16x32_bf16 v[8:11], v[168:171], v[216:219], v[8:11]
	v_mfma_f32_16x16x32_bf16 v[52:55], v[172:175], v[188:191], v[52:55]
	v_mfma_f32_16x16x32_bf16 v[48:51], v[180:183], v[188:191], v[48:51]
	v_mfma_f32_16x16x32_bf16 v[36:39], v[172:175], v[196:199], v[36:39]
	v_mfma_f32_16x16x32_bf16 v[32:35], v[180:183], v[196:199], v[32:35]
	v_mfma_f32_16x16x32_bf16 v[20:23], v[172:175], v[204:207], v[20:23]
	v_mfma_f32_16x16x32_bf16 v[16:19], v[180:183], v[204:207], v[16:19]
	v_mfma_f32_16x16x32_bf16 v[4:7], v[172:175], v[212:215], v[4:7]
	v_mfma_f32_16x16x32_bf16 v[0:3], v[180:183], v[212:215], v[0:3]
	v_mfma_f32_16x16x32_bf16 v[52:55], v[176:179], v[192:195], v[52:55]
	v_mfma_f32_16x16x32_bf16 v[48:51], v[184:187], v[192:195], v[48:51]
	v_mfma_f32_16x16x32_bf16 v[36:39], v[176:179], v[200:203], v[36:39]
	v_mfma_f32_16x16x32_bf16 v[32:35], v[184:187], v[200:203], v[32:35]
	v_mfma_f32_16x16x32_bf16 v[20:23], v[176:179], v[208:211], v[20:23]
	v_mfma_f32_16x16x32_bf16 v[16:19], v[184:187], v[208:211], v[16:19]
	v_mfma_f32_16x16x32_bf16 v[4:7], v[176:179], v[216:219], v[4:7]
	v_mfma_f32_16x16x32_bf16 v[0:3], v[184:187], v[216:219], v[0:3]
	s_setprio 0
	s_barrier
	s_add_i32 s23, 0, 0x18000
	v_add_u32_e32 v159, s23, v153
	s_add_i32 s33, 0, 0x1c000
	ds_read_b128 v[146:149], v159
	ds_read_b128 v[160:163], v159 offset:1024
	ds_read_b128 v[164:167], v159 offset:2048
	ds_read_b128 v[168:171], v159 offset:3072
	v_add_u32_e32 v159, s33, v153
	ds_read_b128 v[172:175], v159
	ds_read_b128 v[176:179], v159 offset:1024
	ds_read_b128 v[180:183], v159 offset:2048
	ds_read_b128 v[184:187], v159 offset:3072
	s_add_u32 s50, s50, 0x40000
	s_addc_u32 s51, s51, 0
	s_mov_b32 m0, s55
	ds_read_b128 v[188:191], v157 offset:32768
	ds_read_b128 v[192:195], v157 offset:33792
	ds_read_b128 v[196:199], v157 offset:34816
	ds_read_b128 v[200:203], v157 offset:35840
	ds_read_b128 v[204:207], v157 offset:36864
	ds_read_b128 v[208:211], v157 offset:37888
	ds_read_b128 v[212:215], v157 offset:38912
	ds_read_b128 v[216:219], v157 offset:39936
	global_load_lds_dwordx4 v130, s[50:51]
	v_lshl_add_u64 v[228:229], s[50:51], 0, v[134:135]
	s_mov_b32 m0, s56
	s_nop 0
	global_load_lds_dwordx4 v[228:229], off
	s_waitcnt vmcnt(8)
	s_waitcnt lgkmcnt(0)
	s_barrier
	s_setprio 1
	v_mfma_f32_16x16x32_bf16 v[124:127], v[146:149], v[188:191], v[124:127]
	v_mfma_f32_16x16x32_bf16 v[120:123], v[164:167], v[188:191], v[120:123]
	v_mfma_f32_16x16x32_bf16 v[108:111], v[146:149], v[196:199], v[108:111]
	v_mfma_f32_16x16x32_bf16 v[104:107], v[164:167], v[196:199], v[104:107]
	v_mfma_f32_16x16x32_bf16 v[92:95], v[146:149], v[204:207], v[92:95]
	v_mfma_f32_16x16x32_bf16 v[88:91], v[164:167], v[204:207], v[88:91]
	v_mfma_f32_16x16x32_bf16 v[76:79], v[146:149], v[212:215], v[76:79]
	v_mfma_f32_16x16x32_bf16 v[72:75], v[164:167], v[212:215], v[72:75]
	v_mfma_f32_16x16x32_bf16 v[124:127], v[160:163], v[192:195], v[124:127]
	v_mfma_f32_16x16x32_bf16 v[120:123], v[168:171], v[192:195], v[120:123]
	v_mfma_f32_16x16x32_bf16 v[108:111], v[160:163], v[200:203], v[108:111]
	v_mfma_f32_16x16x32_bf16 v[104:107], v[168:171], v[200:203], v[104:107]
	v_mfma_f32_16x16x32_bf16 v[92:95], v[160:163], v[208:211], v[92:95]
	v_mfma_f32_16x16x32_bf16 v[88:91], v[168:171], v[208:211], v[88:91]
	v_mfma_f32_16x16x32_bf16 v[76:79], v[160:163], v[216:219], v[76:79]
	v_mfma_f32_16x16x32_bf16 v[72:75], v[168:171], v[216:219], v[72:75]
	v_mfma_f32_16x16x32_bf16 v[116:119], v[172:175], v[188:191], v[116:119]
	v_mfma_f32_16x16x32_bf16 v[112:115], v[180:183], v[188:191], v[112:115]
	v_mfma_f32_16x16x32_bf16 v[100:103], v[172:175], v[196:199], v[100:103]
	v_mfma_f32_16x16x32_bf16 v[96:99], v[180:183], v[196:199], v[96:99]
	v_mfma_f32_16x16x32_bf16 v[84:87], v[172:175], v[204:207], v[84:87]
	v_mfma_f32_16x16x32_bf16 v[80:83], v[180:183], v[204:207], v[80:83]
	v_mfma_f32_16x16x32_bf16 v[68:71], v[172:175], v[212:215], v[68:71]
	v_mfma_f32_16x16x32_bf16 v[64:67], v[180:183], v[212:215], v[64:67]
	v_mfma_f32_16x16x32_bf16 v[116:119], v[176:179], v[192:195], v[116:119]
	v_mfma_f32_16x16x32_bf16 v[112:115], v[184:187], v[192:195], v[112:115]
	v_mfma_f32_16x16x32_bf16 v[100:103], v[176:179], v[200:203], v[100:103]
	v_mfma_f32_16x16x32_bf16 v[96:99], v[184:187], v[200:203], v[96:99]
	v_mfma_f32_16x16x32_bf16 v[84:87], v[176:179], v[208:211], v[84:87]
	v_mfma_f32_16x16x32_bf16 v[80:83], v[184:187], v[208:211], v[80:83]
	v_mfma_f32_16x16x32_bf16 v[68:71], v[176:179], v[216:219], v[68:71]
	v_mfma_f32_16x16x32_bf16 v[64:67], v[184:187], v[216:219], v[64:67]
	s_setprio 0
	s_barrier
	s_add_i32 s23, s23, s54
	v_lshl_add_u64 v[220:221], v[220:221], 0, s[14:15]
	s_mov_b32 m0, s23
	ds_read_b128 v[188:191], v157 offset:49152
	ds_read_b128 v[192:195], v157 offset:50176
	ds_read_b128 v[196:199], v157 offset:51200
	ds_read_b128 v[200:203], v157 offset:52224
	ds_read_b128 v[204:207], v157 offset:53248
	ds_read_b128 v[208:211], v157 offset:54272
	ds_read_b128 v[212:215], v157 offset:55296
	ds_read_b128 v[216:219], v157 offset:56320
	global_load_lds_dwordx4 v[220:221], off
	s_add_i32 m0, s23, 0x2000
	s_add_u32 s48, s48, 0x40080
	v_lshl_add_u64 v[220:221], v[222:223], 0, s[14:15]
	s_addc_u32 s49, s49, 0
	s_add_i32 s23, s33, s54
	global_load_lds_dwordx4 v[220:221], off
	s_mov_b32 m0, s23
	s_nop 0
	global_load_lds_dwordx4 v132, s[48:49]
	s_add_i32 m0, s23, 0x2000
	s_nop 0
	global_load_lds_dwordx4 v136, s[48:49]
	v_lshl_add_u64 v[220:221], v[224:225], 0, s[14:15]
	s_mov_b32 m0, s60
	s_nop 0
	global_load_lds_dwordx4 v[220:221], off
	v_lshl_add_u64 v[220:221], v[226:227], 0, s[14:15]
	s_mov_b32 m0, s61
	s_nop 0
	global_load_lds_dwordx4 v[220:221], off
	s_waitcnt vmcnt(8)
	s_waitcnt lgkmcnt(0)
	s_barrier
	s_setprio 1
	v_mfma_f32_16x16x32_bf16 v[60:63], v[146:149], v[188:191], v[60:63]
	v_mfma_f32_16x16x32_bf16 v[56:59], v[164:167], v[188:191], v[56:59]
	v_mfma_f32_16x16x32_bf16 v[44:47], v[146:149], v[196:199], v[44:47]
	v_mfma_f32_16x16x32_bf16 v[40:43], v[164:167], v[196:199], v[40:43]
	v_mfma_f32_16x16x32_bf16 v[28:31], v[146:149], v[204:207], v[28:31]
	v_mfma_f32_16x16x32_bf16 v[24:27], v[164:167], v[204:207], v[24:27]
	v_mfma_f32_16x16x32_bf16 v[12:15], v[146:149], v[212:215], v[12:15]
	v_mfma_f32_16x16x32_bf16 v[8:11], v[164:167], v[212:215], v[8:11]
	v_mfma_f32_16x16x32_bf16 v[60:63], v[160:163], v[192:195], v[60:63]
	v_mfma_f32_16x16x32_bf16 v[56:59], v[168:171], v[192:195], v[56:59]
	v_mfma_f32_16x16x32_bf16 v[44:47], v[160:163], v[200:203], v[44:47]
	v_mfma_f32_16x16x32_bf16 v[40:43], v[168:171], v[200:203], v[40:43]
	v_mfma_f32_16x16x32_bf16 v[28:31], v[160:163], v[208:211], v[28:31]
	v_mfma_f32_16x16x32_bf16 v[24:27], v[168:171], v[208:211], v[24:27]
	v_mfma_f32_16x16x32_bf16 v[12:15], v[160:163], v[216:219], v[12:15]
	v_mfma_f32_16x16x32_bf16 v[8:11], v[168:171], v[216:219], v[8:11]
	v_mfma_f32_16x16x32_bf16 v[52:55], v[172:175], v[188:191], v[52:55]
	v_mfma_f32_16x16x32_bf16 v[48:51], v[180:183], v[188:191], v[48:51]
	v_mfma_f32_16x16x32_bf16 v[36:39], v[172:175], v[196:199], v[36:39]
	v_mfma_f32_16x16x32_bf16 v[32:35], v[180:183], v[196:199], v[32:35]
	v_mfma_f32_16x16x32_bf16 v[20:23], v[172:175], v[204:207], v[20:23]
	v_mfma_f32_16x16x32_bf16 v[16:19], v[180:183], v[204:207], v[16:19]
	v_mfma_f32_16x16x32_bf16 v[4:7], v[172:175], v[212:215], v[4:7]
	v_mfma_f32_16x16x32_bf16 v[0:3], v[180:183], v[212:215], v[0:3]
	v_mfma_f32_16x16x32_bf16 v[52:55], v[176:179], v[192:195], v[52:55]
	v_mfma_f32_16x16x32_bf16 v[48:51], v[184:187], v[192:195], v[48:51]
	v_mfma_f32_16x16x32_bf16 v[36:39], v[176:179], v[200:203], v[36:39]
	v_mfma_f32_16x16x32_bf16 v[32:35], v[184:187], v[200:203], v[32:35]
	v_mfma_f32_16x16x32_bf16 v[20:23], v[176:179], v[208:211], v[20:23]
	v_mfma_f32_16x16x32_bf16 v[16:19], v[184:187], v[208:211], v[16:19]
	v_mfma_f32_16x16x32_bf16 v[4:7], v[176:179], v[216:219], v[4:7]
	v_mfma_f32_16x16x32_bf16 v[0:3], v[184:187], v[216:219], v[0:3]
	s_setprio 0
	s_barrier
	s_add_i32 s67, s67, 2
	s_add_u32 s46, s46, 0x100
	s_addc_u32 s47, s47, 0
	s_add_u32 s65, s65, 0x100
	s_addc_u32 s66, s66, 0
	s_cmp_gt_u32 s67, 13
	s_cbranch_scc0 .LBB0_1246
	s_and_b64 vcc, exec, s[16:17]
	s_cbranch_vccz .LBB0_1249
	s_barrier

.LBB0_1332:
	s_add_u32 s8, s28, 0x11500000
	s_addc_u32 s9, s29, 0
	s_add_u32 s10, s28, 0x2f20800
	s_addc_u32 s11, s29, 0
	s_lshl_b32 s1, s12, 5
	s_mov_b64 s[12:13], 0x80
	s_and_b32 s18, s1, 0x60
	s_add_i32 m0, s52, 0x18000
	v_lshl_add_u64 v[6:7], v[6:7], 0, s[12:13]
	s_ashr_i32 s57, s34, 31
	s_lshl_b32 s15, s14, 13
	s_lshl_b32 s19, s18, 7
	s_waitcnt vmcnt(2)
	s_barrier
	global_load_lds_dwordx4 v[6:7], off
	v_lshl_add_u64 v[4:5], v[4:5], 0, s[12:13]
	s_add_i32 m0, s52, 0x1a000
	s_add_i32 s58, s52, 0x8000
	s_add_i32 s59, s52, 0xa000
	global_load_lds_dwordx4 v[4:5], off
	v_lshl_add_u64 v[0:1], v[0:1], 0, s[12:13]
	s_mov_b32 m0, s58
	s_add_u32 s16, s42, 0x40080
	global_load_lds_dwordx4 v[0:1], off
	v_lshl_add_u64 v[0:1], v[2:3], 0, s[12:13]
	s_mov_b32 m0, s59
	s_addc_u32 s17, s43, 0
	global_load_lds_dwordx4 v[0:1], off
	s_add_i32 m0, s52, 0x1c000
	s_nop 0
	global_load_lds_dwordx4 v132, s[16:17]
	v_lshl_add_u64 v[0:1], s[16:17], 0, v[136:137]
	s_add_i32 m0, s52, 0x1e000
	s_sext_i32_i16 s1, s2
	global_load_lds_dwordx4 v[0:1], off
	v_lshlrev_b32_e32 v0, 1, v11
	v_lshlrev_b32_e32 v1, 6, v128
	s_movk_i32 s2, 0x3c0
	v_lshlrev_b32_e32 v2, 2, v128
	v_and_or_b32 v1, v1, s2, v0
	v_and_b32_e32 v2, 32, v2
	v_lshl_or_b32 v0, v151, 6, v0
	v_bitop3_b32 v152, s19, v1, v2 bitop3:0xf6
	v_lshlrev_b32_e32 v1, 8, v128
	v_bitop3_b32 v0, v0, s15, v2 bitop3:0xde
	v_and_b32_e32 v1, 0x38000, v1
	v_lshlrev_b32_e32 v2, 11, v10
	v_or3_b32 v1, v8, v1, v2
	v_add_u32_e32 v138, v1, v9
	v_lshlrev_b32_e32 v1, 4, v12
	s_waitcnt vmcnt(6)
	s_cmpk_lt_u32 s3, 0x100
	v_and_b32_e32 v1, 0x78000, v1
	v_lshl_or_b32 v150, s14, 6, v151
	s_cselect_b64 s[14:15], -1, 0
	v_or3_b32 v1, v8, v1, v2
	s_add_i32 s61, 0, 0x10000
	s_add_i32 s62, 0, 0x14000
	s_mov_b32 s60, s34
	v_or_b32_e32 v153, s18, v11
	v_mov_b32_e32 v139, v133
	v_add_u32_e32 v140, v1, v9
	v_mov_b32_e32 v141, v133
	v_mov_b64_e32 v[142:143], 0x596
	v_mov_b64_e32 v[144:145], 0x595
	v_add_u32_e32 v154, s61, v152
	v_add_u32_e32 v155, s62, v152
	v_add_u32_e32 v156, 0, v0
	v_mov_b32_e32 v157, 0x358637bd
	s_mov_b32 s63, 0x800000
	s_movk_i32 s64, 0x1600
	s_barrier
	s_branch .LBB0_1335

.LBB0_1342:
	ds_read_b128 v[146:149], v154
	ds_read_b128 v[158:161], v154 offset:1024
	ds_read_b128 v[162:165], v154 offset:2048
	ds_read_b128 v[166:169], v154 offset:3072
	ds_read_b128 v[170:173], v155
	ds_read_b128 v[174:177], v155 offset:1024
	ds_read_b128 v[178:181], v155 offset:2048
	ds_read_b128 v[182:185], v155 offset:3072
	s_add_u32 s23, s40, 0xfffc0080
	s_addc_u32 s33, s41, -1
	s_cmp_eq_u32 s67, 12
	s_cselect_b32 s45, s19, s33
	s_cselect_b32 s44, s20, s23
	s_cselect_b32 s43, s17, s66
	s_cselect_b32 s42, s21, s65
	s_add_i32 m0, s52, 0xc000
	ds_read_b128 v[186:189], v156
	ds_read_b128 v[190:193], v156 offset:1024
	ds_read_b128 v[194:197], v156 offset:2048
	ds_read_b128 v[198:201], v156 offset:3072
	ds_read_b128 v[202:205], v156 offset:4096
	ds_read_b128 v[206:209], v156 offset:5120
	ds_read_b128 v[210:213], v156 offset:6144
	ds_read_b128 v[214:217], v156 offset:7168
	global_load_lds_dwordx4 v138, s[40:41]
	s_add_i32 m0, s52, 0xe000
	s_nop 0
	global_load_lds_dwordx4 v140, s[40:41]
	s_waitcnt vmcnt(8)
	s_waitcnt lgkmcnt(0)
	s_barrier
	s_setprio 1
	v_mfma_f32_16x16x32_bf16 v[116:119], v[146:149], v[186:189], v[116:119]
	v_mfma_f32_16x16x32_bf16 v[112:115], v[162:165], v[186:189], v[112:115]
	v_mfma_f32_16x16x32_bf16 v[100:103], v[146:149], v[194:197], v[100:103]
	v_mfma_f32_16x16x32_bf16 v[96:99], v[162:165], v[194:197], v[96:99]
	v_mfma_f32_16x16x32_bf16 v[84:87], v[146:149], v[202:205], v[84:87]
	v_mfma_f32_16x16x32_bf16 v[80:83], v[162:165], v[202:205], v[80:83]
	v_mfma_f32_16x16x32_bf16 v[72:75], v[146:149], v[210:213], v[72:75]
	v_mfma_f32_16x16x32_bf16 v[64:67], v[162:165], v[210:213], v[64:67]
	v_mfma_f32_16x16x32_bf16 v[116:119], v[158:161], v[190:193], v[116:119]
	v_mfma_f32_16x16x32_bf16 v[112:115], v[166:169], v[190:193], v[112:115]
	v_mfma_f32_16x16x32_bf16 v[100:103], v[158:161], v[198:201], v[100:103]
	v_mfma_f32_16x16x32_bf16 v[96:99], v[166:169], v[198:201], v[96:99]
	v_mfma_f32_16x16x32_bf16 v[84:87], v[158:161], v[206:209], v[84:87]
	v_mfma_f32_16x16x32_bf16 v[80:83], v[166:169], v[206:209], v[80:83]
	v_mfma_f32_16x16x32_bf16 v[72:75], v[158:161], v[214:217], v[72:75]
	v_mfma_f32_16x16x32_bf16 v[64:67], v[166:169], v[214:217], v[64:67]
	v_mfma_f32_16x16x32_bf16 v[124:127], v[170:173], v[186:189], v[124:127]
	v_mfma_f32_16x16x32_bf16 v[120:123], v[178:181], v[186:189], v[120:123]
	v_mfma_f32_16x16x32_bf16 v[108:111], v[170:173], v[194:197], v[108:111]
	v_mfma_f32_16x16x32_bf16 v[104:107], v[178:181], v[194:197], v[104:107]
	v_mfma_f32_16x16x32_bf16 v[92:95], v[170:173], v[202:205], v[92:95]
	v_mfma_f32_16x16x32_bf16 v[88:91], v[178:181], v[202:205], v[88:91]
	v_mfma_f32_16x16x32_bf16 v[76:79], v[170:173], v[210:213], v[76:79]
	v_mfma_f32_16x16x32_bf16 v[68:71], v[178:181], v[210:213], v[68:71]
	v_mfma_f32_16x16x32_bf16 v[124:127], v[174:177], v[190:193], v[124:127]
	v_mfma_f32_16x16x32_bf16 v[120:123], v[182:185], v[190:193], v[120:123]
	v_mfma_f32_16x16x32_bf16 v[108:111], v[174:177], v[198:201], v[108:111]
	v_mfma_f32_16x16x32_bf16 v[104:107], v[182:185], v[198:201], v[104:107]
	v_mfma_f32_16x16x32_bf16 v[92:95], v[174:177], v[206:209], v[92:95]
	v_mfma_f32_16x16x32_bf16 v[88:91], v[182:185], v[206:209], v[88:91]
	v_mfma_f32_16x16x32_bf16 v[76:79], v[174:177], v[214:217], v[76:79]
	v_mfma_f32_16x16x32_bf16 v[68:71], v[182:185], v[214:217], v[68:71]
	s_setprio 0
	s_barrier
	s_add_i32 s23, s61, s50
	v_lshl_add_u64 v[218:219], s[42:43], 0, v[132:133]
	s_mov_b32 m0, s23
	ds_read_b128 v[186:189], v156 offset:16384
	ds_read_b128 v[190:193], v156 offset:17408
	ds_read_b128 v[194:197], v156 offset:18432
	ds_read_b128 v[198:201], v156 offset:19456
	ds_read_b128 v[202:205], v156 offset:20480
	ds_read_b128 v[206:209], v156 offset:21504
	ds_read_b128 v[210:213], v156 offset:22528
	ds_read_b128 v[214:217], v156 offset:23552
	global_load_lds_dwordx4 v[218:219], off
	s_add_i32 m0, s23, 0x2000
	s_add_u32 s68, s42, 0x40000
	v_lshl_add_u64 v[220:221], s[42:43], 0, v[136:137]
	s_addc_u32 s69, s43, 0
	s_add_i32 s23, s62, s50
	global_load_lds_dwordx4 v[220:221], off
	s_mov_b32 m0, s23
	v_lshl_add_u64 v[224:225], s[44:45], 0, v[134:135]
	global_load_lds_dwordx4 v132, s[68:69]
	s_add_i32 m0, s23, 0x2000
	s_nop 0
	global_load_lds_dwordx4 v136, s[68:69]
	v_lshl_add_u64 v[222:223], s[44:45], 0, v[130:131]
	s_mov_b32 m0, s52
	s_nop 0
	global_load_lds_dwordx4 v[222:223], off
	s_mov_b32 m0, s53
	s_nop 0
	global_load_lds_dwordx4 v[224:225], off
	s_waitcnt vmcnt(8)
	s_waitcnt lgkmcnt(0)
	s_barrier
	s_setprio 1
	v_mfma_f32_16x16x32_bf16 v[56:59], v[146:149], v[186:189], v[56:59]
	v_mfma_f32_16x16x32_bf16 v[48:51], v[162:165], v[186:189], v[48:51]
	v_mfma_f32_16x16x32_bf16 v[40:43], v[146:149], v[194:197], v[40:43]
	v_mfma_f32_16x16x32_bf16 v[32:35], v[162:165], v[194:197], v[32:35]
	v_mfma_f32_16x16x32_bf16 v[24:27], v[146:149], v[202:205], v[24:27]
	v_mfma_f32_16x16x32_bf16 v[16:19], v[162:165], v[202:205], v[16:19]
	v_mfma_f32_16x16x32_bf16 v[8:11], v[146:149], v[210:213], v[8:11]
	v_mfma_f32_16x16x32_bf16 v[0:3], v[162:165], v[210:213], v[0:3]
	v_mfma_f32_16x16x32_bf16 v[56:59], v[158:161], v[190:193], v[56:59]
	v_mfma_f32_16x16x32_bf16 v[48:51], v[166:169], v[190:193], v[48:51]
	v_mfma_f32_16x16x32_bf16 v[40:43], v[158:161], v[198:201], v[40:43]
	v_mfma_f32_16x16x32_bf16 v[32:35], v[166:169], v[198:201], v[32:35]
	v_mfma_f32_16x16x32_bf16 v[24:27], v[158:161], v[206:209], v[24:27]
	v_mfma_f32_16x16x32_bf16 v[16:19], v[166:169], v[206:209], v[16:19]
	v_mfma_f32_16x16x32_bf16 v[8:11], v[158:161], v[214:217], v[8:11]
	v_mfma_f32_16x16x32_bf16 v[0:3], v[166:169], v[214:217], v[0:3]
	v_mfma_f32_16x16x32_bf16 v[60:63], v[170:173], v[186:189], v[60:63]
	v_mfma_f32_16x16x32_bf16 v[52:55], v[178:181], v[186:189], v[52:55]
	v_mfma_f32_16x16x32_bf16 v[44:47], v[170:173], v[194:197], v[44:47]
	v_mfma_f32_16x16x32_bf16 v[36:39], v[178:181], v[194:197], v[36:39]
	v_mfma_f32_16x16x32_bf16 v[28:31], v[170:173], v[202:205], v[28:31]
	v_mfma_f32_16x16x32_bf16 v[20:23], v[178:181], v[202:205], v[20:23]
	v_mfma_f32_16x16x32_bf16 v[12:15], v[170:173], v[210:213], v[12:15]
	v_mfma_f32_16x16x32_bf16 v[4:7], v[178:181], v[210:213], v[4:7]
	v_mfma_f32_16x16x32_bf16 v[60:63], v[174:177], v[190:193], v[60:63]
	v_mfma_f32_16x16x32_bf16 v[52:55], v[182:185], v[190:193], v[52:55]
	v_mfma_f32_16x16x32_bf16 v[44:47], v[174:177], v[198:201], v[44:47]
	v_mfma_f32_16x16x32_bf16 v[36:39], v[182:185], v[198:201], v[36:39]
	v_mfma_f32_16x16x32_bf16 v[28:31], v[174:177], v[206:209], v[28:31]
	v_mfma_f32_16x16x32_bf16 v[20:23], v[182:185], v[206:209], v[20:23]
	v_mfma_f32_16x16x32_bf16 v[12:15], v[174:177], v[214:217], v[12:15]
	v_mfma_f32_16x16x32_bf16 v[4:7], v[182:185], v[214:217], v[4:7]
	s_setprio 0
	s_barrier
	s_add_i32 s23, 0, 0x18000
	s_add_i32 s33, 0, 0x1c000
	v_add_u32_e32 v166, s23, v152
	v_add_u32_e32 v182, s33, v152
	ds_read_b128 v[146:149], v166
	ds_read_b128 v[158:161], v166 offset:1024
	ds_read_b128 v[162:165], v166 offset:2048
	ds_read_b128 v[166:169], v166 offset:3072
	ds_read_b128 v[170:173], v182
	ds_read_b128 v[174:177], v182 offset:1024
	ds_read_b128 v[178:181], v182 offset:2048
	ds_read_b128 v[182:185], v182 offset:3072
	s_add_u32 s44, s44, 0x40000
	s_addc_u32 s45, s45, 0
	s_mov_b32 m0, s54
	ds_read_b128 v[186:189], v156 offset:32768
	ds_read_b128 v[190:193], v156 offset:33792
	ds_read_b128 v[194:197], v156 offset:34816
	ds_read_b128 v[198:201], v156 offset:35840
	ds_read_b128 v[202:205], v156 offset:36864
	ds_read_b128 v[206:209], v156 offset:37888
	ds_read_b128 v[210:213], v156 offset:38912
	ds_read_b128 v[214:217], v156 offset:39936
	global_load_lds_dwordx4 v130, s[44:45]
	v_lshl_add_u64 v[226:227], s[44:45], 0, v[134:135]
	s_mov_b32 m0, s55
	s_nop 0
	global_load_lds_dwordx4 v[226:227], off
	s_waitcnt vmcnt(8)
	s_waitcnt lgkmcnt(0)
	s_barrier
	s_setprio 1
	v_mfma_f32_16x16x32_bf16 v[116:119], v[146:149], v[186:189], v[116:119]
	v_mfma_f32_16x16x32_bf16 v[112:115], v[162:165], v[186:189], v[112:115]
	v_mfma_f32_16x16x32_bf16 v[100:103], v[146:149], v[194:197], v[100:103]
	v_mfma_f32_16x16x32_bf16 v[96:99], v[162:165], v[194:197], v[96:99]
	v_mfma_f32_16x16x32_bf16 v[84:87], v[146:149], v[202:205], v[84:87]
	v_mfma_f32_16x16x32_bf16 v[80:83], v[162:165], v[202:205], v[80:83]
	v_mfma_f32_16x16x32_bf16 v[72:75], v[146:149], v[210:213], v[72:75]
	v_mfma_f32_16x16x32_bf16 v[64:67], v[162:165], v[210:213], v[64:67]
	v_mfma_f32_16x16x32_bf16 v[116:119], v[158:161], v[190:193], v[116:119]
	v_mfma_f32_16x16x32_bf16 v[112:115], v[166:169], v[190:193], v[112:115]
	v_mfma_f32_16x16x32_bf16 v[100:103], v[158:161], v[198:201], v[100:103]
	v_mfma_f32_16x16x32_bf16 v[96:99], v[166:169], v[198:201], v[96:99]
	v_mfma_f32_16x16x32_bf16 v[84:87], v[158:161], v[206:209], v[84:87]
	v_mfma_f32_16x16x32_bf16 v[80:83], v[166:169], v[206:209], v[80:83]
	v_mfma_f32_16x16x32_bf16 v[72:75], v[158:161], v[214:217], v[72:75]
	v_mfma_f32_16x16x32_bf16 v[64:67], v[166:169], v[214:217], v[64:67]
	v_mfma_f32_16x16x32_bf16 v[124:127], v[170:173], v[186:189], v[124:127]
	v_mfma_f32_16x16x32_bf16 v[120:123], v[178:181], v[186:189], v[120:123]
	v_mfma_f32_16x16x32_bf16 v[108:111], v[170:173], v[194:197], v[108:111]
	v_mfma_f32_16x16x32_bf16 v[104:107], v[178:181], v[194:197], v[104:107]
	v_mfma_f32_16x16x32_bf16 v[92:95], v[170:173], v[202:205], v[92:95]
	v_mfma_f32_16x16x32_bf16 v[88:91], v[178:181], v[202:205], v[88:91]
	v_mfma_f32_16x16x32_bf16 v[76:79], v[170:173], v[210:213], v[76:79]
	v_mfma_f32_16x16x32_bf16 v[68:71], v[178:181], v[210:213], v[68:71]
	v_mfma_f32_16x16x32_bf16 v[124:127], v[174:177], v[190:193], v[124:127]
	v_mfma_f32_16x16x32_bf16 v[120:123], v[182:185], v[190:193], v[120:123]
	v_mfma_f32_16x16x32_bf16 v[108:111], v[174:177], v[198:201], v[108:111]
	v_mfma_f32_16x16x32_bf16 v[104:107], v[182:185], v[198:201], v[104:107]
	v_mfma_f32_16x16x32_bf16 v[92:95], v[174:177], v[206:209], v[92:95]
	v_mfma_f32_16x16x32_bf16 v[88:91], v[182:185], v[206:209], v[88:91]
	v_mfma_f32_16x16x32_bf16 v[76:79], v[174:177], v[214:217], v[76:79]
	v_mfma_f32_16x16x32_bf16 v[68:71], v[182:185], v[214:217], v[68:71]
	s_setprio 0
	s_barrier
	s_add_i32 s23, s23, s50
	v_lshl_add_u64 v[218:219], v[218:219], 0, s[12:13]
	s_mov_b32 m0, s23
	ds_read_b128 v[186:189], v156 offset:49152
	ds_read_b128 v[190:193], v156 offset:50176
	ds_read_b128 v[194:197], v156 offset:51200
	ds_read_b128 v[198:201], v156 offset:52224
	ds_read_b128 v[202:205], v156 offset:53248
	ds_read_b128 v[206:209], v156 offset:54272
	ds_read_b128 v[210:213], v156 offset:55296
	ds_read_b128 v[214:217], v156 offset:56320
	global_load_lds_dwordx4 v[218:219], off
	s_add_i32 m0, s23, 0x2000
	s_add_u32 s42, s42, 0x40080
	v_lshl_add_u64 v[218:219], v[220:221], 0, s[12:13]
	s_addc_u32 s43, s43, 0
	s_add_i32 s23, s33, s50
	global_load_lds_dwordx4 v[218:219], off
	s_mov_b32 m0, s23
	s_nop 0
	global_load_lds_dwordx4 v132, s[42:43]
	s_add_i32 m0, s23, 0x2000
	s_nop 0
	global_load_lds_dwordx4 v136, s[42:43]
	v_lshl_add_u64 v[218:219], v[222:223], 0, s[12:13]
	s_mov_b32 m0, s58
	s_nop 0
	global_load_lds_dwordx4 v[218:219], off
	v_lshl_add_u64 v[218:219], v[224:225], 0, s[12:13]
	s_mov_b32 m0, s59
	s_nop 0
	global_load_lds_dwordx4 v[218:219], off
	s_waitcnt vmcnt(8)
	s_waitcnt lgkmcnt(0)
	s_barrier
	s_setprio 1
	v_mfma_f32_16x16x32_bf16 v[56:59], v[146:149], v[186:189], v[56:59]
	v_mfma_f32_16x16x32_bf16 v[48:51], v[162:165], v[186:189], v[48:51]
	v_mfma_f32_16x16x32_bf16 v[40:43], v[146:149], v[194:197], v[40:43]
	v_mfma_f32_16x16x32_bf16 v[32:35], v[162:165], v[194:197], v[32:35]
	v_mfma_f32_16x16x32_bf16 v[24:27], v[146:149], v[202:205], v[24:27]
	v_mfma_f32_16x16x32_bf16 v[16:19], v[162:165], v[202:205], v[16:19]
	v_mfma_f32_16x16x32_bf16 v[8:11], v[146:149], v[210:213], v[8:11]
	v_mfma_f32_16x16x32_bf16 v[0:3], v[162:165], v[210:213], v[0:3]
	v_mfma_f32_16x16x32_bf16 v[56:59], v[158:161], v[190:193], v[56:59]
	v_mfma_f32_16x16x32_bf16 v[48:51], v[166:169], v[190:193], v[48:51]
	v_mfma_f32_16x16x32_bf16 v[40:43], v[158:161], v[198:201], v[40:43]
	v_mfma_f32_16x16x32_bf16 v[32:35], v[166:169], v[198:201], v[32:35]
	v_mfma_f32_16x16x32_bf16 v[24:27], v[158:161], v[206:209], v[24:27]
	v_mfma_f32_16x16x32_bf16 v[16:19], v[166:169], v[206:209], v[16:19]
	v_mfma_f32_16x16x32_bf16 v[8:11], v[158:161], v[214:217], v[8:11]
	v_mfma_f32_16x16x32_bf16 v[0:3], v[166:169], v[214:217], v[0:3]
	v_mfma_f32_16x16x32_bf16 v[60:63], v[170:173], v[186:189], v[60:63]
	v_mfma_f32_16x16x32_bf16 v[52:55], v[178:181], v[186:189], v[52:55]
	v_mfma_f32_16x16x32_bf16 v[44:47], v[170:173], v[194:197], v[44:47]
	v_mfma_f32_16x16x32_bf16 v[36:39], v[178:181], v[194:197], v[36:39]
	v_mfma_f32_16x16x32_bf16 v[28:31], v[170:173], v[202:205], v[28:31]
	v_mfma_f32_16x16x32_bf16 v[20:23], v[178:181], v[202:205], v[20:23]
	v_mfma_f32_16x16x32_bf16 v[12:15], v[170:173], v[210:213], v[12:15]
	v_mfma_f32_16x16x32_bf16 v[4:7], v[178:181], v[210:213], v[4:7]
	v_mfma_f32_16x16x32_bf16 v[60:63], v[174:177], v[190:193], v[60:63]
	v_mfma_f32_16x16x32_bf16 v[52:55], v[182:185], v[190:193], v[52:55]
	v_mfma_f32_16x16x32_bf16 v[44:47], v[174:177], v[198:201], v[44:47]
	v_mfma_f32_16x16x32_bf16 v[36:39], v[182:185], v[198:201], v[36:39]
	v_mfma_f32_16x16x32_bf16 v[28:31], v[174:177], v[206:209], v[28:31]
	v_mfma_f32_16x16x32_bf16 v[20:23], v[182:185], v[206:209], v[20:23]
	v_mfma_f32_16x16x32_bf16 v[12:15], v[174:177], v[214:217], v[12:15]
	v_mfma_f32_16x16x32_bf16 v[4:7], v[182:185], v[214:217], v[4:7]
	s_setprio 0
	s_barrier
	s_add_i32 s67, s67, 2
	s_add_u32 s40, s40, 0x100
	s_addc_u32 s41, s41, 0
	s_add_u32 s65, s65, 0x100
	s_addc_u32 s66, s66, 0
	s_cmp_gt_u32 s67, 13
	s_cbranch_scc0 .LBB0_1342
	s_and_b64 vcc, exec, s[14:15]
	s_cbranch_vccz .LBB0_1345
	s_barrier

.LBB0_1410:
	s_add_u32 s10, s28, 0x7200000
	s_addc_u32 s11, s29, 0
	s_add_u32 s12, s28, 0x3000000
	s_addc_u32 s13, s29, 0
	s_add_u32 s14, s28, 0x2f30c00
	s_addc_u32 s15, s29, 0
	s_lshl_b32 s1, s1, 5
	s_mov_b64 s[16:17], 0x80
	s_and_b32 s1, s1, 0x60
	s_add_i32 m0, s49, 0x18000
	v_lshl_add_u64 v[6:7], v[6:7], 0, s[16:17]
	s_ashr_i32 s54, s34, 31
	s_ashr_i32 s55, s22, 31
	s_lshl_b32 s5, s0, 13
	s_lshl_b32 s18, s1, 7
	s_waitcnt vmcnt(2)
	s_barrier
	global_load_lds_dwordx4 v[6:7], off
	v_lshl_add_u64 v[4:5], v[4:5], 0, s[16:17]
	s_add_i32 m0, s49, 0x1a000
	s_add_i32 s56, s49, 0x8000
	s_add_i32 s57, s49, 0xa000
	global_load_lds_dwordx4 v[4:5], off
	v_lshl_add_u64 v[0:1], v[0:1], 0, s[16:17]
	s_mov_b32 m0, s56
	s_add_u32 s2, s40, 0xb0080
	global_load_lds_dwordx4 v[0:1], off
	v_lshl_add_u64 v[0:1], v[2:3], 0, s[16:17]
	s_mov_b32 m0, s57
	s_addc_u32 s3, s41, 0
	global_load_lds_dwordx4 v[0:1], off
	s_add_i32 m0, s49, 0x1c000
	s_nop 0
	global_load_lds_dwordx4 v132, s[2:3]
	v_lshl_add_u64 v[0:1], s[2:3], 0, v[136:137]
	s_add_i32 m0, s49, 0x1e000
	v_lshlrev_b32_e32 v2, 6, v128
	global_load_lds_dwordx4 v[0:1], off
	v_and_b32_e32 v0, 3, v150
	v_lshlrev_b32_e32 v1, 4, v0
	s_movk_i32 s2, 0x3c0
	v_and_or_b32 v2, v2, s2, v1
	v_lshlrev_b32_e32 v3, 2, v128
	v_cmp_eq_u32_e64 s[2:3], 0, v0
	v_lshlrev_b32_e32 v4, 2, v151
	v_lshl_or_b32 v155, v0, 3, s1
	v_add_u16_e32 v0, v8, v9
	v_and_b32_e32 v3, 32, v3
	v_lshl_or_b32 v1, v151, 6, v1
	v_and_b32_e32 v4, 32, v4
	s_waitcnt vmcnt(6)
	s_cmpk_lt_u32 s4, 0x100
	v_lshrrev_b16_e32 v0, 1, v0
	v_bitop3_b32 v1, v1, s5, v4 bitop3:0xde
	v_bitop3_b32 v154, s18, v2, v3 bitop3:0xf6
	s_cselect_b64 s[18:19], -1, 0
	v_add_lshl_u32 v138, v10, v0, 1
	v_add_lshl_u32 v140, v11, v0, 1
	s_add_i32 s59, 0, 0x10000
	s_add_i32 s60, 0, 0x14000
	v_mbcnt_lo_u32_b32 v0, -1, 0
	s_mov_b32 s58, s34
	v_lshl_or_b32 v153, s0, 6, v151
	v_mov_b32_e32 v139, v133
	v_mov_b32_e32 v141, v133
	v_mov_b64_e32 v[142:143], 0x100
	v_mov_b64_e32 v[144:145], 0xff
	v_add_u32_e32 v156, s59, v154
	v_add_u32_e32 v157, s60, v154
	v_add_u32_e32 v158, 0, v1
	v_mbcnt_hi_u32_b32 v159, -1, v0
	s_barrier
	s_branch .LBB0_1413

.LBB0_1424:
	ds_read_b128 v[146:149], v156
	ds_read_b128 v[160:163], v156 offset:1024
	ds_read_b128 v[164:167], v156 offset:2048
	ds_read_b128 v[168:171], v156 offset:3072
	ds_read_b128 v[172:175], v157
	ds_read_b128 v[176:179], v157 offset:1024
	ds_read_b128 v[180:183], v157 offset:2048
	ds_read_b128 v[184:187], v157 offset:3072
	s_add_u32 s23, s38, 0xfff50080
	s_addc_u32 s33, s39, -1
	s_cmp_eq_u32 s65, 40
	s_cselect_b32 s43, s1, s33
	s_cselect_b32 s42, s0, s23
	s_cselect_b32 s41, s37, s64
	s_cselect_b32 s40, s36, s63
	s_add_i32 m0, s49, 0xc000
	ds_read_b128 v[188:191], v158
	ds_read_b128 v[192:195], v158 offset:1024
	ds_read_b128 v[196:199], v158 offset:2048
	ds_read_b128 v[200:203], v158 offset:3072
	ds_read_b128 v[204:207], v158 offset:4096
	ds_read_b128 v[208:211], v158 offset:5120
	ds_read_b128 v[212:215], v158 offset:6144
	ds_read_b128 v[216:219], v158 offset:7168
	global_load_lds_dwordx4 v138, s[38:39]
	s_add_i32 m0, s49, 0xe000
	s_nop 0
	global_load_lds_dwordx4 v140, s[38:39]
	s_waitcnt vmcnt(8)
	s_waitcnt lgkmcnt(0)
	s_barrier
	s_setprio 1
	v_mfma_f32_16x16x32_bf16 v[124:127], v[146:149], v[188:191], v[124:127]
	v_mfma_f32_16x16x32_bf16 v[120:123], v[164:167], v[188:191], v[120:123]
	v_mfma_f32_16x16x32_bf16 v[108:111], v[146:149], v[196:199], v[108:111]
	v_mfma_f32_16x16x32_bf16 v[104:107], v[164:167], v[196:199], v[104:107]
	v_mfma_f32_16x16x32_bf16 v[92:95], v[146:149], v[204:207], v[92:95]
	v_mfma_f32_16x16x32_bf16 v[88:91], v[164:167], v[204:207], v[88:91]
	v_mfma_f32_16x16x32_bf16 v[76:79], v[146:149], v[212:215], v[76:79]
	v_mfma_f32_16x16x32_bf16 v[72:75], v[164:167], v[212:215], v[72:75]
	v_mfma_f32_16x16x32_bf16 v[124:127], v[160:163], v[192:195], v[124:127]
	v_mfma_f32_16x16x32_bf16 v[120:123], v[168:171], v[192:195], v[120:123]
	v_mfma_f32_16x16x32_bf16 v[108:111], v[160:163], v[200:203], v[108:111]
	v_mfma_f32_16x16x32_bf16 v[104:107], v[168:171], v[200:203], v[104:107]
	v_mfma_f32_16x16x32_bf16 v[92:95], v[160:163], v[208:211], v[92:95]
	v_mfma_f32_16x16x32_bf16 v[88:91], v[168:171], v[208:211], v[88:91]
	v_mfma_f32_16x16x32_bf16 v[76:79], v[160:163], v[216:219], v[76:79]
	v_mfma_f32_16x16x32_bf16 v[72:75], v[168:171], v[216:219], v[72:75]
	v_mfma_f32_16x16x32_bf16 v[116:119], v[172:175], v[188:191], v[116:119]
	v_mfma_f32_16x16x32_bf16 v[112:115], v[180:183], v[188:191], v[112:115]
	v_mfma_f32_16x16x32_bf16 v[100:103], v[172:175], v[196:199], v[100:103]
	v_mfma_f32_16x16x32_bf16 v[96:99], v[180:183], v[196:199], v[96:99]
	v_mfma_f32_16x16x32_bf16 v[84:87], v[172:175], v[204:207], v[84:87]
	v_mfma_f32_16x16x32_bf16 v[80:83], v[180:183], v[204:207], v[80:83]
	v_mfma_f32_16x16x32_bf16 v[68:71], v[172:175], v[212:215], v[68:71]
	v_mfma_f32_16x16x32_bf16 v[64:67], v[180:183], v[212:215], v[64:67]
	v_mfma_f32_16x16x32_bf16 v[116:119], v[176:179], v[192:195], v[116:119]
	v_mfma_f32_16x16x32_bf16 v[112:115], v[184:187], v[192:195], v[112:115]
	v_mfma_f32_16x16x32_bf16 v[100:103], v[176:179], v[200:203], v[100:103]
	v_mfma_f32_16x16x32_bf16 v[96:99], v[184:187], v[200:203], v[96:99]
	v_mfma_f32_16x16x32_bf16 v[84:87], v[176:179], v[208:211], v[84:87]
	v_mfma_f32_16x16x32_bf16 v[80:83], v[184:187], v[208:211], v[80:83]
	v_mfma_f32_16x16x32_bf16 v[68:71], v[176:179], v[216:219], v[68:71]
	v_mfma_f32_16x16x32_bf16 v[64:67], v[184:187], v[216:219], v[64:67]
	s_setprio 0
	s_barrier
	s_add_i32 s23, s59, s48
	v_lshl_add_u64 v[220:221], s[40:41], 0, v[132:133]
	s_mov_b32 m0, s23
	ds_read_b128 v[188:191], v158 offset:16384
	ds_read_b128 v[192:195], v158 offset:17408
	ds_read_b128 v[196:199], v158 offset:18432
	ds_read_b128 v[200:203], v158 offset:19456
	ds_read_b128 v[204:207], v158 offset:20480
	ds_read_b128 v[208:211], v158 offset:21504
	ds_read_b128 v[212:215], v158 offset:22528
	ds_read_b128 v[216:219], v158 offset:23552
	global_load_lds_dwordx4 v[220:221], off
	s_add_i32 m0, s23, 0x2000
	s_add_u32 s66, s40, 0xb0000
	v_lshl_add_u64 v[222:223], s[40:41], 0, v[136:137]
	s_addc_u32 s67, s41, 0
	s_add_i32 s23, s60, s48
	global_load_lds_dwordx4 v[222:223], off
	s_mov_b32 m0, s23
	v_lshl_add_u64 v[226:227], s[42:43], 0, v[134:135]
	global_load_lds_dwordx4 v132, s[66:67]
	s_add_i32 m0, s23, 0x2000
	s_nop 0
	global_load_lds_dwordx4 v136, s[66:67]
	v_lshl_add_u64 v[224:225], s[42:43], 0, v[130:131]
	s_mov_b32 m0, s49
	s_nop 0
	global_load_lds_dwordx4 v[224:225], off
	s_mov_b32 m0, s50
	s_nop 0
	global_load_lds_dwordx4 v[226:227], off
	s_waitcnt vmcnt(8)
	s_waitcnt lgkmcnt(0)
	s_barrier
	s_setprio 1
	v_mfma_f32_16x16x32_bf16 v[60:63], v[146:149], v[188:191], v[60:63]
	v_mfma_f32_16x16x32_bf16 v[56:59], v[164:167], v[188:191], v[56:59]
	v_mfma_f32_16x16x32_bf16 v[44:47], v[146:149], v[196:199], v[44:47]
	v_mfma_f32_16x16x32_bf16 v[40:43], v[164:167], v[196:199], v[40:43]
	v_mfma_f32_16x16x32_bf16 v[28:31], v[146:149], v[204:207], v[28:31]
	v_mfma_f32_16x16x32_bf16 v[24:27], v[164:167], v[204:207], v[24:27]
	v_mfma_f32_16x16x32_bf16 v[12:15], v[146:149], v[212:215], v[12:15]
	v_mfma_f32_16x16x32_bf16 v[8:11], v[164:167], v[212:215], v[8:11]
	v_mfma_f32_16x16x32_bf16 v[60:63], v[160:163], v[192:195], v[60:63]
	v_mfma_f32_16x16x32_bf16 v[56:59], v[168:171], v[192:195], v[56:59]
	v_mfma_f32_16x16x32_bf16 v[44:47], v[160:163], v[200:203], v[44:47]
	v_mfma_f32_16x16x32_bf16 v[40:43], v[168:171], v[200:203], v[40:43]
	v_mfma_f32_16x16x32_bf16 v[28:31], v[160:163], v[208:211], v[28:31]
	v_mfma_f32_16x16x32_bf16 v[24:27], v[168:171], v[208:211], v[24:27]
	v_mfma_f32_16x16x32_bf16 v[12:15], v[160:163], v[216:219], v[12:15]
	v_mfma_f32_16x16x32_bf16 v[8:11], v[168:171], v[216:219], v[8:11]
	v_mfma_f32_16x16x32_bf16 v[52:55], v[172:175], v[188:191], v[52:55]
	v_mfma_f32_16x16x32_bf16 v[48:51], v[180:183], v[188:191], v[48:51]
	v_mfma_f32_16x16x32_bf16 v[36:39], v[172:175], v[196:199], v[36:39]
	v_mfma_f32_16x16x32_bf16 v[32:35], v[180:183], v[196:199], v[32:35]
	v_mfma_f32_16x16x32_bf16 v[20:23], v[172:175], v[204:207], v[20:23]
	v_mfma_f32_16x16x32_bf16 v[16:19], v[180:183], v[204:207], v[16:19]
	v_mfma_f32_16x16x32_bf16 v[4:7], v[172:175], v[212:215], v[4:7]
	v_mfma_f32_16x16x32_bf16 v[0:3], v[180:183], v[212:215], v[0:3]
	v_mfma_f32_16x16x32_bf16 v[52:55], v[176:179], v[192:195], v[52:55]
	v_mfma_f32_16x16x32_bf16 v[48:51], v[184:187], v[192:195], v[48:51]
	v_mfma_f32_16x16x32_bf16 v[36:39], v[176:179], v[200:203], v[36:39]
	v_mfma_f32_16x16x32_bf16 v[32:35], v[184:187], v[200:203], v[32:35]
	v_mfma_f32_16x16x32_bf16 v[20:23], v[176:179], v[208:211], v[20:23]
	v_mfma_f32_16x16x32_bf16 v[16:19], v[184:187], v[208:211], v[16:19]
	v_mfma_f32_16x16x32_bf16 v[4:7], v[176:179], v[216:219], v[4:7]
	v_mfma_f32_16x16x32_bf16 v[0:3], v[184:187], v[216:219], v[0:3]
	s_setprio 0
	s_barrier
	s_add_i32 s23, 0, 0x18000
	s_add_i32 s33, 0, 0x1c000
	v_add_u32_e32 v168, s23, v154
	v_add_u32_e32 v184, s33, v154
	ds_read_b128 v[146:149], v168
	ds_read_b128 v[160:163], v168 offset:1024
	ds_read_b128 v[164:167], v168 offset:2048
	ds_read_b128 v[168:171], v168 offset:3072
	ds_read_b128 v[172:175], v184
	ds_read_b128 v[176:179], v184 offset:1024
	ds_read_b128 v[180:183], v184 offset:2048
	ds_read_b128 v[184:187], v184 offset:3072
	s_add_u32 s42, s42, 0xb0000
	s_addc_u32 s43, s43, 0
	s_mov_b32 m0, s51
	ds_read_b128 v[188:191], v158 offset:32768
	ds_read_b128 v[192:195], v158 offset:33792
	ds_read_b128 v[196:199], v158 offset:34816
	ds_read_b128 v[200:203], v158 offset:35840
	ds_read_b128 v[204:207], v158 offset:36864
	ds_read_b128 v[208:211], v158 offset:37888
	ds_read_b128 v[212:215], v158 offset:38912
	ds_read_b128 v[216:219], v158 offset:39936
	global_load_lds_dwordx4 v130, s[42:43]
	v_lshl_add_u64 v[228:229], s[42:43], 0, v[134:135]
	s_mov_b32 m0, s52
	s_nop 0
	global_load_lds_dwordx4 v[228:229], off
	s_waitcnt vmcnt(8)
	s_waitcnt lgkmcnt(0)
	s_barrier
	s_setprio 1
	v_mfma_f32_16x16x32_bf16 v[124:127], v[146:149], v[188:191], v[124:127]
	v_mfma_f32_16x16x32_bf16 v[120:123], v[164:167], v[188:191], v[120:123]
	v_mfma_f32_16x16x32_bf16 v[108:111], v[146:149], v[196:199], v[108:111]
	v_mfma_f32_16x16x32_bf16 v[104:107], v[164:167], v[196:199], v[104:107]
	v_mfma_f32_16x16x32_bf16 v[92:95], v[146:149], v[204:207], v[92:95]
	v_mfma_f32_16x16x32_bf16 v[88:91], v[164:167], v[204:207], v[88:91]
	v_mfma_f32_16x16x32_bf16 v[76:79], v[146:149], v[212:215], v[76:79]
	v_mfma_f32_16x16x32_bf16 v[72:75], v[164:167], v[212:215], v[72:75]
	v_mfma_f32_16x16x32_bf16 v[124:127], v[160:163], v[192:195], v[124:127]
	v_mfma_f32_16x16x32_bf16 v[120:123], v[168:171], v[192:195], v[120:123]
	v_mfma_f32_16x16x32_bf16 v[108:111], v[160:163], v[200:203], v[108:111]
	v_mfma_f32_16x16x32_bf16 v[104:107], v[168:171], v[200:203], v[104:107]
	v_mfma_f32_16x16x32_bf16 v[92:95], v[160:163], v[208:211], v[92:95]
	v_mfma_f32_16x16x32_bf16 v[88:91], v[168:171], v[208:211], v[88:91]
	v_mfma_f32_16x16x32_bf16 v[76:79], v[160:163], v[216:219], v[76:79]
	v_mfma_f32_16x16x32_bf16 v[72:75], v[168:171], v[216:219], v[72:75]
	v_mfma_f32_16x16x32_bf16 v[116:119], v[172:175], v[188:191], v[116:119]
	v_mfma_f32_16x16x32_bf16 v[112:115], v[180:183], v[188:191], v[112:115]
	v_mfma_f32_16x16x32_bf16 v[100:103], v[172:175], v[196:199], v[100:103]
	v_mfma_f32_16x16x32_bf16 v[96:99], v[180:183], v[196:199], v[96:99]
	v_mfma_f32_16x16x32_bf16 v[84:87], v[172:175], v[204:207], v[84:87]
	v_mfma_f32_16x16x32_bf16 v[80:83], v[180:183], v[204:207], v[80:83]
	v_mfma_f32_16x16x32_bf16 v[68:71], v[172:175], v[212:215], v[68:71]
	v_mfma_f32_16x16x32_bf16 v[64:67], v[180:183], v[212:215], v[64:67]
	v_mfma_f32_16x16x32_bf16 v[116:119], v[176:179], v[192:195], v[116:119]
	v_mfma_f32_16x16x32_bf16 v[112:115], v[184:187], v[192:195], v[112:115]
	v_mfma_f32_16x16x32_bf16 v[100:103], v[176:179], v[200:203], v[100:103]
	v_mfma_f32_16x16x32_bf16 v[96:99], v[184:187], v[200:203], v[96:99]
	v_mfma_f32_16x16x32_bf16 v[84:87], v[176:179], v[208:211], v[84:87]
	v_mfma_f32_16x16x32_bf16 v[80:83], v[184:187], v[208:211], v[80:83]
	v_mfma_f32_16x16x32_bf16 v[68:71], v[176:179], v[216:219], v[68:71]
	v_mfma_f32_16x16x32_bf16 v[64:67], v[184:187], v[216:219], v[64:67]
	s_setprio 0
	s_barrier
	s_add_i32 s23, s23, s48
	v_lshl_add_u64 v[220:221], v[220:221], 0, s[16:17]
	s_mov_b32 m0, s23
	ds_read_b128 v[188:191], v158 offset:49152
	ds_read_b128 v[192:195], v158 offset:50176
	ds_read_b128 v[196:199], v158 offset:51200
	ds_read_b128 v[200:203], v158 offset:52224
	ds_read_b128 v[204:207], v158 offset:53248
	ds_read_b128 v[208:211], v158 offset:54272
	ds_read_b128 v[212:215], v158 offset:55296
	ds_read_b128 v[216:219], v158 offset:56320
	global_load_lds_dwordx4 v[220:221], off
	s_add_i32 m0, s23, 0x2000
	s_add_u32 s40, s40, 0xb0080
	v_lshl_add_u64 v[220:221], v[222:223], 0, s[16:17]
	s_addc_u32 s41, s41, 0
	s_add_i32 s23, s33, s48
	global_load_lds_dwordx4 v[220:221], off
	s_mov_b32 m0, s23
	s_nop 0
	global_load_lds_dwordx4 v132, s[40:41]
	s_add_i32 m0, s23, 0x2000
	s_nop 0
	global_load_lds_dwordx4 v136, s[40:41]
	v_lshl_add_u64 v[220:221], v[224:225], 0, s[16:17]
	s_mov_b32 m0, s56
	s_nop 0
	global_load_lds_dwordx4 v[220:221], off
	v_lshl_add_u64 v[220:221], v[226:227], 0, s[16:17]
	s_mov_b32 m0, s57
	s_nop 0
	global_load_lds_dwordx4 v[220:221], off
	s_waitcnt vmcnt(8)
	s_waitcnt lgkmcnt(0)
	s_barrier
	s_setprio 1
	v_mfma_f32_16x16x32_bf16 v[60:63], v[146:149], v[188:191], v[60:63]
	v_mfma_f32_16x16x32_bf16 v[56:59], v[164:167], v[188:191], v[56:59]
	v_mfma_f32_16x16x32_bf16 v[44:47], v[146:149], v[196:199], v[44:47]
	v_mfma_f32_16x16x32_bf16 v[40:43], v[164:167], v[196:199], v[40:43]
	v_mfma_f32_16x16x32_bf16 v[28:31], v[146:149], v[204:207], v[28:31]
	v_mfma_f32_16x16x32_bf16 v[24:27], v[164:167], v[204:207], v[24:27]
	v_mfma_f32_16x16x32_bf16 v[12:15], v[146:149], v[212:215], v[12:15]
	v_mfma_f32_16x16x32_bf16 v[8:11], v[164:167], v[212:215], v[8:11]
	v_mfma_f32_16x16x32_bf16 v[60:63], v[160:163], v[192:195], v[60:63]
	v_mfma_f32_16x16x32_bf16 v[56:59], v[168:171], v[192:195], v[56:59]
	v_mfma_f32_16x16x32_bf16 v[44:47], v[160:163], v[200:203], v[44:47]
	v_mfma_f32_16x16x32_bf16 v[40:43], v[168:171], v[200:203], v[40:43]
	v_mfma_f32_16x16x32_bf16 v[28:31], v[160:163], v[208:211], v[28:31]
	v_mfma_f32_16x16x32_bf16 v[24:27], v[168:171], v[208:211], v[24:27]
	v_mfma_f32_16x16x32_bf16 v[12:15], v[160:163], v[216:219], v[12:15]
	v_mfma_f32_16x16x32_bf16 v[8:11], v[168:171], v[216:219], v[8:11]
	v_mfma_f32_16x16x32_bf16 v[52:55], v[172:175], v[188:191], v[52:55]
	v_mfma_f32_16x16x32_bf16 v[48:51], v[180:183], v[188:191], v[48:51]
	v_mfma_f32_16x16x32_bf16 v[36:39], v[172:175], v[196:199], v[36:39]
	v_mfma_f32_16x16x32_bf16 v[32:35], v[180:183], v[196:199], v[32:35]
	v_mfma_f32_16x16x32_bf16 v[20:23], v[172:175], v[204:207], v[20:23]
	v_mfma_f32_16x16x32_bf16 v[16:19], v[180:183], v[204:207], v[16:19]
	v_mfma_f32_16x16x32_bf16 v[4:7], v[172:175], v[212:215], v[4:7]
	v_mfma_f32_16x16x32_bf16 v[0:3], v[180:183], v[212:215], v[0:3]
	v_mfma_f32_16x16x32_bf16 v[52:55], v[176:179], v[192:195], v[52:55]
	v_mfma_f32_16x16x32_bf16 v[48:51], v[184:187], v[192:195], v[48:51]
	v_mfma_f32_16x16x32_bf16 v[36:39], v[176:179], v[200:203], v[36:39]
	v_mfma_f32_16x16x32_bf16 v[32:35], v[184:187], v[200:203], v[32:35]
	v_mfma_f32_16x16x32_bf16 v[20:23], v[176:179], v[208:211], v[20:23]
	v_mfma_f32_16x16x32_bf16 v[16:19], v[184:187], v[208:211], v[16:19]
	v_mfma_f32_16x16x32_bf16 v[4:7], v[176:179], v[216:219], v[4:7]
	v_mfma_f32_16x16x32_bf16 v[0:3], v[184:187], v[216:219], v[0:3]
	s_setprio 0
	s_barrier
	s_add_i32 s65, s65, 2
	s_add_u32 s38, s38, 0x100
	s_addc_u32 s39, s39, 0
	s_add_u32 s63, s63, 0x100
	s_addc_u32 s64, s64, 0
	s_cmp_gt_u32 s65, 41
	s_cbranch_scc0 .LBB0_1424
	s_and_b64 vcc, exec, s[18:19]
	s_cbranch_vccz .LBB0_1427
	s_barrier
